# v10: v9 + norm ctx-row slab fold de-serialised (20 loads in flight, counted vmcnt, ws from s[72:73])
# baseline (speedup 1.0000x reference)
; #define GAS __attribute__((address_space(1)))
; #define LAS __attribute__((address_space(3)))
; #define NR_LOAD(dst, k_) do { const GAS v2u* xr_ = (const GAS v2u*)(X + (size_t)(nw + 2048 * (k_)) * D) + F.lane; \
;         _Pragma("unroll") for (int j = 0; j < 8; ++j) dst[j] = __builtin_nontemporal_load(xr_ + 64 * j); } while (0)
; __device__ __forceinline__ void norm_mod_phase2(const Args& a, Frame& F, const float* gain, const float* modl, int sh_off, int sc_off, int nrows, const float* slab_gate) {
;     ...
;     NR_LOAD(r0, 0); NR_LOAD(r1, 1); NR_LOAD(r2, 2); NR_LOAD(r3, 3); NR_LOAD(r4, 4); NR_LOAD(r5, 5); NR_LOAD(r6, 6); NR_LOAD(r7, 7);
;     { const GAS f32x4* g4 = (const GAS f32x4*)gain;
;       for (int q = F.tid; q < 5 * D / 4; q += NWAVES * 64) { const int bq = q >> 9, cq = q & 511; const GAS f32x4* mb4 = (const GAS f32x4*)(modl + (size_t)bq * MOD_LD);
;           ((LAS f32x4*)CA)[q] = g4[cq] * (mb4[sc_off / 4 + cq] + 1.0f); ((LAS f32x4*)CB)[q] = mb4[sh_off / 4 + cq]; } }
;     asm volatile("s_waitcnt lgkmcnt(0)" ::: "memory"); __builtin_amdgcn_s_barrier(); asm volatile("" ::: "memory");
.LBB0_219:
	s_or_b64 exec, exec, s[6:7]
	s_waitcnt vmcnt(62)
	v_cvt_f32_f16_sdwa v153, v140 dst_sel:DWORD dst_unused:UNUSED_PAD src0_sel:WORD_1
	v_cvt_f32_f16_sdwa v149, v138 dst_sel:DWORD dst_unused:UNUSED_PAD src0_sel:WORD_1
	v_cvt_f32_f16_e32 v152, v140
	v_cvt_f32_f16_sdwa v155, v141 dst_sel:DWORD dst_unused:UNUSED_PAD src0_sel:WORD_1
	v_cvt_f32_f16_e32 v148, v138
	v_cvt_f32_f16_sdwa v151, v139 dst_sel:DWORD dst_unused:UNUSED_PAD src0_sel:WORD_1
	v_cvt_f32_f16_e32 v154, v141
	v_cvt_f32_f16_e32 v150, v139
	s_waitcnt vmcnt(61)
	v_cvt_f32_f16_sdwa v139, v136 dst_sel:DWORD dst_unused:UNUSED_PAD src0_sel:WORD_1
	v_cvt_f32_f16_sdwa v141, v137 dst_sel:DWORD dst_unused:UNUSED_PAD src0_sel:WORD_1
	s_mov_b64 s[6:7], 0x8c00000
	v_mov_b32_e32 v74, v153
	v_mov_b32_e32 v75, v149
	v_cvt_f32_f16_e32 v138, v136
	v_cvt_f32_f16_e32 v140, v137
	v_lshl_add_u64 v[2:3], v[128:129], 0, s[6:7]
	v_mov_b32_e32 v4, v152
	v_mov_b32_e32 v5, v148
	v_pk_mul_f32 v[74:75], v[74:75], v[74:75]
	v_mov_b32_e32 v128, v155
	v_mov_b32_e32 v129, v151
	v_pk_fma_f32 v[4:5], v[4:5], v[4:5], v[74:75]
	v_mov_b32_e32 v74, v154
	v_mov_b32_e32 v75, v150
	v_pk_mul_f32 v[128:129], v[128:129], v[128:129]
	s_waitcnt vmcnt(60)
	v_cvt_f32_f16_sdwa v145, v132 dst_sel:DWORD dst_unused:UNUSED_PAD src0_sel:WORD_1
	v_pk_fma_f32 v[74:75], v[74:75], v[74:75], v[128:129]
	v_mov_b32_e32 v128, v139
	v_mov_b32_e32 v129, v141
	v_pk_add_f32 v[4:5], v[4:5], v[74:75]
	v_mov_b32_e32 v74, v138
	v_mov_b32_e32 v75, v140
	v_pk_mul_f32 v[128:129], v[128:129], v[128:129]
	v_cvt_f32_f16_e32 v144, v132
	v_cvt_f32_f16_sdwa v147, v133 dst_sel:DWORD dst_unused:UNUSED_PAD src0_sel:WORD_1
	v_pk_fma_f32 v[74:75], v[74:75], v[74:75], v[128:129]
	v_cvt_f32_f16_e32 v146, v133
	s_waitcnt vmcnt(59)
	v_cvt_f32_f16_sdwa v129, v134 dst_sel:DWORD dst_unused:UNUSED_PAD src0_sel:WORD_1
	v_cvt_f32_f16_e32 v128, v134
	v_cvt_f32_f16_sdwa v133, v135 dst_sel:DWORD dst_unused:UNUSED_PAD src0_sel:WORD_1
	v_cvt_f32_f16_e32 v132, v135
	v_mul_f32_e32 v0, v145, v145
	v_pk_fma_f32 v[136:137], v[144:145], v[144:145], v[0:1] op_sel_hi:[1,1,0]
	v_mul_f32_e32 v0, v147, v147
	v_pk_add_f32 v[4:5], v[4:5], v[4:5] op_sel:[0,1] op_sel_hi:[1,0]
	v_pk_add_f32 v[74:75], v[74:75], v[74:75] op_sel:[0,1] op_sel_hi:[1,0]
	v_pk_fma_f32 v[156:157], v[146:147], v[146:147], v[0:1] op_sel_hi:[1,1,0]
	v_pk_mul_f32 v[134:135], v[128:129], v[128:129]
	v_pk_mul_f32 v[158:159], v[132:133], v[132:133]
	v_mov_b32_e32 v5, v134
	v_mov_b32_e32 v75, v135
	v_mov_b32_e32 v137, v158
	v_mov_b32_e32 v157, v159
	v_pk_add_f32 v[4:5], v[4:5], v[74:75]
	v_pk_add_f32 v[74:75], v[136:137], v[156:157]
	s_waitcnt vmcnt(58)
	v_cvt_f32_f16_sdwa v135, v124 dst_sel:DWORD dst_unused:UNUSED_PAD src0_sel:WORD_1
	v_cvt_f32_f16_sdwa v137, v125 dst_sel:DWORD dst_unused:UNUSED_PAD src0_sel:WORD_1
	v_cvt_f32_f16_e32 v134, v124
	v_cvt_f32_f16_e32 v136, v125
	v_pk_add_f32 v[4:5], v[4:5], v[74:75]
	v_mov_b32_e32 v74, v135
	v_mov_b32_e32 v75, v137
	v_pk_add_f32 v[156:157], v[4:5], v[4:5] op_sel:[0,1] op_sel_hi:[1,0]
	v_mov_b32_e32 v4, v134
	v_mov_b32_e32 v5, v136
	v_pk_mul_f32 v[74:75], v[74:75], v[74:75]
	s_waitcnt vmcnt(57)
	v_cvt_f32_f16_sdwa v125, v127 dst_sel:DWORD dst_unused:UNUSED_PAD src0_sel:WORD_1
	v_pk_fma_f32 v[4:5], v[4:5], v[4:5], v[74:75]
	v_cvt_f32_f16_e32 v124, v127
	v_pk_add_f32 v[158:159], v[4:5], v[4:5] op_sel:[0,1] op_sel_hi:[1,0]
	v_cvt_f32_f16_sdwa v5, v126 dst_sel:DWORD dst_unused:UNUSED_PAD src0_sel:WORD_1
	v_cvt_f32_f16_e32 v4, v126
	s_waitcnt vmcnt(56)
	v_cvt_f32_f16_sdwa v75, v130 dst_sel:DWORD dst_unused:UNUSED_PAD src0_sel:WORD_1
	v_cvt_f32_f16_e32 v74, v130
	v_cvt_f32_f16_sdwa v127, v131 dst_sel:DWORD dst_unused:UNUSED_PAD src0_sel:WORD_1
	v_cvt_f32_f16_e32 v126, v131
	v_mul_f32_e32 v0, v5, v5
	v_pk_fma_f32 v[160:161], v[4:5], v[4:5], v[0:1] op_sel_hi:[1,1,0]
	v_mul_f32_e32 v0, v125, v125
	v_pk_fma_f32 v[162:163], v[124:125], v[124:125], v[0:1] op_sel_hi:[1,1,0]
	v_pk_mul_f32 v[130:131], v[74:75], v[74:75]
	v_pk_mul_f32 v[164:165], v[126:127], v[126:127]
	v_mov_b32_e32 v157, v130
	v_mov_b32_e32 v159, v131
	v_mov_b32_e32 v161, v164
	v_mov_b32_e32 v163, v165
	v_pk_add_f32 v[130:131], v[156:157], v[158:159]
	v_pk_add_f32 v[156:157], v[160:161], v[162:163]
	s_lshl_b64 s[8:9], s[4:5], 11
	v_pk_add_f32 v[130:131], v[130:131], v[156:157]
	s_lshl_b64 s[12:13], s[10:11], 11
	v_add_f32_e32 v0, v130, v131
	s_waitcnt lgkmcnt(0)
	s_barrier
	s_lshl_b64 s[40:41], s[36:37], 11
	v_add_f32_dpp v0, v0, v0 quad_perm:[1,0,3,2] row_mask:0xf bank_mask:0xf bound_ctrl:1
	s_lshl_b64 s[34:35], s[30:31], 11
	s_lshl_b64 s[28:29], s[26:27], 11
	v_add_f32_dpp v0, v0, v0 quad_perm:[2,3,0,1] row_mask:0xf bank_mask:0xf bound_ctrl:1
	s_lshl_b64 s[24:25], s[22:23], 11
	s_lshl_b64 s[20:21], s[18:19], 11
	v_add_f32_dpp v0, v0, v0 row_half_mirror row_mask:0xf bank_mask:0xf bound_ctrl:1
	s_lshl_b64 s[16:17], s[14:15], 11
	s_nop 0
	v_add_f32_dpp v0, v0, v0 row_mirror row_mask:0xf bank_mask:0xf bound_ctrl:1
	s_nop 0
	v_readlane_b32 s5, v0, 16
	v_readlane_b32 s11, v0, 48
	v_readlane_b32 s6, v0, 0
	v_readlane_b32 s7, v0, 32
	v_mov_b32_e32 v130, s5
	v_mov_b32_e32 v131, s11
	v_pk_add_f32 v[130:131], s[6:7], v[130:131]
	s_lshl_b32 s5, s4, 1
	v_add_f32_e32 v0, v130, v131
	v_fmamk_f32 v0, v0, 0x3a000000, v252
	v_cmp_gt_f32_e32 vcc, s55, v0
	v_mul_f32_e32 v7, 0x4f800000, v0
	s_and_b32 s5, s5, 0xffffe000
	v_cndmask_b32_e32 v0, v0, v7, vcc
	v_sqrt_f32_e32 v7, v0
	s_add_i32 s5, s5, 0
	v_add_u32_e32 v130, -1, v7
	v_fma_f32 v131, -v130, v7, v0
	v_cmp_ge_f32_e64 s[6:7], 0, v131
	v_add_u32_e32 v131, 1, v7
	s_nop 0
	v_cndmask_b32_e64 v130, v7, v130, s[6:7]
	v_fma_f32 v7, -v131, v7, v0
	v_cmp_lt_f32_e64 s[6:7], 0, v7
	s_nop 1
	v_cndmask_b32_e64 v7, v130, v131, s[6:7]
	v_mul_f32_e32 v130, 0x37800000, v7
	v_cndmask_b32_e32 v7, v7, v130, vcc
	v_cmp_class_f32_e32 vcc, v0, v253
	s_nop 1
	v_cndmask_b32_e32 v0, v7, v0, vcc
	v_div_scale_f32 v7, s[6:7], v0, v0, 1.0
	v_rcp_f32_e32 v130, v7
	s_nop 0
	v_fma_f32 v131, -v7, v130, 1.0
	v_fmac_f32_e32 v130, v131, v130
	v_div_scale_f32 v131, vcc, 1.0, v0, 1.0
	v_mul_f32_e32 v142, v131, v130
	v_fma_f32 v156, -v7, v142, v131
	v_fmac_f32_e32 v142, v156, v130
	v_fma_f32 v7, -v7, v142, v131
	v_div_fmas_f32 v7, v7, v130, v142
	v_div_fixup_f32 v142, v7, v0, 1.0
	v_lshlrev_b32_e32 v0, 4, v143
	v_add_u32_e32 v164, s5, v0
	v_pk_mul_f32 v[160:161], v[152:153], v[142:143] op_sel_hi:[1,0]
	v_pk_mul_f32 v[162:163], v[154:155], v[142:143] op_sel_hi:[1,0]
	ds_read_b128 v[152:155], v164
	ds_read_b128 v[156:159], v164 offset:40960
	v_lshl_add_u64 v[130:131], s[8:9], 1, v[2:3]
	v_mov_b32_e32 v7, v1
	v_lshl_add_u64 v[130:131], v[130:131], 0, v[6:7]
	v_pk_mul_f32 v[128:129], v[128:129], v[142:143] op_sel_hi:[1,0]
	s_waitcnt lgkmcnt(0)
	v_pk_fma_f32 v[154:155], v[154:155], v[162:163], v[158:159]
	v_pk_fma_f32 v[152:153], v[152:153], v[160:161], v[156:157]
	v_pk_mul_f32 v[156:157], v[148:149], v[142:143] op_sel_hi:[1,0]
	v_cvt_pk_bf16_f32 v152, v152, v153
	v_cvt_pk_bf16_f32 v153, v154, v155
	global_store_dwordx2 v[130:131], v[152:153], off
	v_pk_mul_f32 v[158:159], v[150:151], v[142:143] op_sel_hi:[1,0]
	ds_read_b128 v[148:151], v164 offset:1024
	ds_read_b128 v[152:155], v164 offset:41984
	v_pk_mul_f32 v[132:133], v[132:133], v[142:143] op_sel_hi:[1,0]
	v_pk_mul_f32 v[4:5], v[4:5], v[142:143] op_sel_hi:[1,0]
	v_pk_mul_f32 v[124:125], v[124:125], v[142:143] op_sel_hi:[1,0]
	s_waitcnt lgkmcnt(0)
	v_pk_fma_f32 v[150:151], v[150:151], v[158:159], v[154:155]
	v_pk_fma_f32 v[148:149], v[148:149], v[156:157], v[152:153]
	v_pk_mul_f32 v[152:153], v[138:139], v[142:143] op_sel_hi:[1,0]
	v_cvt_pk_bf16_f32 v148, v148, v149
	v_cvt_pk_bf16_f32 v149, v150, v151
	global_store_dwordx2 v[130:131], v[148:149], off offset:512
	v_pk_mul_f32 v[154:155], v[140:141], v[142:143] op_sel_hi:[1,0]
	ds_read_b128 v[138:141], v164 offset:2048
	ds_read_b128 v[148:151], v164 offset:43008
	s_waitcnt lgkmcnt(0)
	v_pk_fma_f32 v[140:141], v[140:141], v[154:155], v[150:151]
	v_pk_fma_f32 v[138:139], v[138:139], v[152:153], v[148:149]
	v_pk_mul_f32 v[148:149], v[144:145], v[142:143] op_sel_hi:[1,0]
	v_cvt_pk_bf16_f32 v138, v138, v139
	v_cvt_pk_bf16_f32 v139, v140, v141
	global_store_dwordx2 v[130:131], v[138:139], off offset:1024
	v_pk_mul_f32 v[150:151], v[146:147], v[142:143] op_sel_hi:[1,0]
	ds_read_b128 v[138:141], v164 offset:3072
	ds_read_b128 v[144:147], v164 offset:44032
	s_waitcnt lgkmcnt(0)
	v_pk_fma_f32 v[140:141], v[150:151], v[140:141], v[146:147]
	v_pk_fma_f32 v[138:139], v[148:149], v[138:139], v[144:145]
	s_nop 0
	v_cvt_pk_bf16_f32 v138, v138, v139
	v_cvt_pk_bf16_f32 v139, v140, v141
	global_store_dwordx2 v[130:131], v[138:139], off offset:1536
	ds_read_b128 v[138:141], v164 offset:4096
	ds_read_b128 v[144:147], v164 offset:45056
	s_waitcnt lgkmcnt(0)
	v_pk_fma_f32 v[132:133], v[132:133], v[140:141], v[146:147]
	v_pk_fma_f32 v[128:129], v[128:129], v[138:139], v[144:145]
	v_pk_mul_f32 v[140:141], v[136:137], v[142:143] op_sel_hi:[1,0]
	v_cvt_pk_bf16_f32 v128, v128, v129
	v_cvt_pk_bf16_f32 v129, v132, v133
	global_store_dwordx2 v[130:131], v[128:129], off offset:2048
	v_pk_mul_f32 v[128:129], v[134:135], v[142:143] op_sel_hi:[1,0]
	ds_read_b128 v[132:135], v164 offset:5120
	ds_read_b128 v[136:139], v164 offset:46080
	s_waitcnt lgkmcnt(0)
	v_pk_fma_f32 v[134:135], v[140:141], v[134:135], v[138:139]
	v_pk_fma_f32 v[128:129], v[128:129], v[132:133], v[136:137]
	s_nop 0
	v_cvt_pk_bf16_f32 v128, v128, v129
	v_cvt_pk_bf16_f32 v129, v134, v135
	global_store_dwordx2 v[130:131], v[128:129], off offset:2560
	ds_read_b128 v[132:135], v164 offset:6144
	ds_read_b128 v[136:139], v164 offset:47104
	s_waitcnt vmcnt(58)
	v_cvt_f32_f16_sdwa v129, v117 dst_sel:DWORD dst_unused:UNUSED_PAD src0_sel:WORD_1
	v_cvt_f32_f16_e32 v128, v117
	s_waitcnt lgkmcnt(0)
	v_pk_fma_f32 v[124:125], v[124:125], v[134:135], v[138:139]
	v_pk_fma_f32 v[4:5], v[4:5], v[132:133], v[136:137]
	v_cvt_f32_f16_sdwa v137, v122 dst_sel:DWORD dst_unused:UNUSED_PAD src0_sel:WORD_1
	v_cvt_pk_bf16_f32 v4, v4, v5
	v_cvt_pk_bf16_f32 v5, v124, v125
	global_store_dwordx2 v[130:131], v[4:5], off offset:3072
	v_pk_mul_f32 v[4:5], v[74:75], v[142:143] op_sel_hi:[1,0]
	v_pk_mul_f32 v[74:75], v[126:127], v[142:143] op_sel_hi:[1,0]
	ds_read_b128 v[124:127], v164 offset:7168
	ds_read_b128 v[132:135], v164 offset:48128
	v_cvt_f32_f16_e32 v136, v122
	v_cvt_f32_f16_sdwa v139, v123 dst_sel:DWORD dst_unused:UNUSED_PAD src0_sel:WORD_1
	v_cvt_f32_f16_e32 v138, v123
	v_cvt_f32_f16_sdwa v123, v118 dst_sel:DWORD dst_unused:UNUSED_PAD src0_sel:WORD_1
	s_waitcnt lgkmcnt(0)
	v_pk_fma_f32 v[4:5], v[4:5], v[124:125], v[132:133]
	v_cvt_f32_f16_sdwa v133, v120 dst_sel:DWORD dst_unused:UNUSED_PAD src0_sel:WORD_1
	v_pk_fma_f32 v[74:75], v[74:75], v[126:127], v[134:135]
	v_cvt_f32_f16_e32 v132, v120
	v_cvt_f32_f16_sdwa v135, v121 dst_sel:DWORD dst_unused:UNUSED_PAD src0_sel:WORD_1
	v_cvt_f32_f16_e32 v134, v121
	v_cvt_f32_f16_sdwa v125, v119 dst_sel:DWORD dst_unused:UNUSED_PAD src0_sel:WORD_1
	v_cvt_f32_f16_sdwa v127, v116 dst_sel:DWORD dst_unused:UNUSED_PAD src0_sel:WORD_1
	v_cvt_pk_bf16_f32 v4, v4, v5
	v_cvt_pk_bf16_f32 v5, v74, v75
	v_mov_b32_e32 v74, v137
	v_mov_b32_e32 v75, v133
	v_cvt_f32_f16_e32 v122, v118
	v_cvt_f32_f16_e32 v124, v119
	v_cvt_f32_f16_e32 v126, v116
	global_store_dwordx2 v[130:131], v[4:5], off offset:3584
	v_mov_b32_e32 v4, v136
	v_mov_b32_e32 v5, v132
	v_pk_mul_f32 v[74:75], v[74:75], v[74:75]
	v_mov_b32_e32 v120, v139
	v_mov_b32_e32 v121, v135
	v_pk_fma_f32 v[4:5], v[4:5], v[4:5], v[74:75]
	v_mov_b32_e32 v74, v138
	v_mov_b32_e32 v75, v134
	v_pk_mul_f32 v[120:121], v[120:121], v[120:121]
	v_mov_b32_e32 v118, v123
	v_pk_fma_f32 v[74:75], v[74:75], v[74:75], v[120:121]
	v_mov_b32_e32 v119, v125
	v_mul_f32_e32 v116, v127, v127
	v_pk_add_f32 v[4:5], v[4:5], v[74:75]
	v_mov_b32_e32 v74, v122
	v_mov_b32_e32 v75, v124
	v_pk_mul_f32 v[118:119], v[118:119], v[118:119]
	v_pk_fma_f32 v[120:121], v[126:127], v[126:127], v[116:117] op_sel_hi:[1,1,0]
	v_mul_f32_e32 v116, v129, v129
	v_pk_fma_f32 v[74:75], v[74:75], v[74:75], v[118:119]
	v_pk_fma_f32 v[130:131], v[128:129], v[128:129], v[116:117] op_sel_hi:[1,1,0]
	s_waitcnt vmcnt(59)
	v_cvt_f32_f16_sdwa v117, v114 dst_sel:DWORD dst_unused:UNUSED_PAD src0_sel:WORD_1
	v_cvt_f32_f16_e32 v116, v114
	v_cvt_f32_f16_sdwa v119, v115 dst_sel:DWORD dst_unused:UNUSED_PAD src0_sel:WORD_1
	v_cvt_f32_f16_e32 v118, v115
	v_pk_add_f32 v[4:5], v[4:5], v[4:5] op_sel:[0,1] op_sel_hi:[1,0]
	v_pk_add_f32 v[74:75], v[74:75], v[74:75] op_sel:[0,1] op_sel_hi:[1,0]
	v_pk_mul_f32 v[114:115], v[116:117], v[116:117]
	v_pk_mul_f32 v[140:141], v[118:119], v[118:119]
	v_mov_b32_e32 v5, v114
	v_mov_b32_e32 v75, v115
	v_mov_b32_e32 v121, v140
	v_mov_b32_e32 v131, v141
	v_pk_add_f32 v[4:5], v[4:5], v[74:75]
	v_pk_add_f32 v[74:75], v[120:121], v[130:131]
	s_waitcnt vmcnt(58)
	v_cvt_f32_f16_sdwa v115, v112 dst_sel:DWORD dst_unused:UNUSED_PAD src0_sel:WORD_1
	v_cvt_f32_f16_sdwa v121, v113 dst_sel:DWORD dst_unused:UNUSED_PAD src0_sel:WORD_1
	v_cvt_f32_f16_e32 v114, v112
	v_cvt_f32_f16_e32 v120, v113
	v_pk_add_f32 v[4:5], v[4:5], v[74:75]
	v_mov_b32_e32 v74, v115
	v_mov_b32_e32 v75, v121
	v_pk_add_f32 v[130:131], v[4:5], v[4:5] op_sel:[0,1] op_sel_hi:[1,0]
	v_mov_b32_e32 v4, v114
	v_mov_b32_e32 v5, v120
	v_pk_mul_f32 v[74:75], v[74:75], v[74:75]
	s_waitcnt vmcnt(57)
	v_cvt_f32_f16_sdwa v113, v111 dst_sel:DWORD dst_unused:UNUSED_PAD src0_sel:WORD_1
	v_pk_fma_f32 v[4:5], v[4:5], v[4:5], v[74:75]
	v_cvt_f32_f16_e32 v112, v111
	v_pk_add_f32 v[140:141], v[4:5], v[4:5] op_sel:[0,1] op_sel_hi:[1,0]
	v_cvt_f32_f16_sdwa v5, v110 dst_sel:DWORD dst_unused:UNUSED_PAD src0_sel:WORD_1
	v_cvt_f32_f16_e32 v4, v110
	s_waitcnt vmcnt(56)
	v_cvt_f32_f16_sdwa v111, v109 dst_sel:DWORD dst_unused:UNUSED_PAD src0_sel:WORD_1
	v_cvt_f32_f16_e32 v110, v109
	v_mul_f32_e32 v74, v5, v5
	v_pk_fma_f32 v[144:145], v[4:5], v[4:5], v[74:75] op_sel_hi:[1,1,0]
	v_mul_f32_e32 v74, v113, v113
	v_pk_fma_f32 v[146:147], v[112:113], v[112:113], v[74:75] op_sel_hi:[1,1,0]
	v_cvt_f32_f16_sdwa v75, v108 dst_sel:DWORD dst_unused:UNUSED_PAD src0_sel:WORD_1
	v_cvt_f32_f16_e32 v74, v108
	v_pk_mul_f32 v[148:149], v[110:111], v[110:111]
	v_pk_mul_f32 v[108:109], v[74:75], v[74:75]
	s_nop 0
	v_mov_b32_e32 v131, v108
	v_mov_b32_e32 v141, v109
	v_mov_b32_e32 v145, v148
	v_mov_b32_e32 v147, v149
	v_pk_add_f32 v[108:109], v[130:131], v[140:141]
	v_pk_add_f32 v[130:131], v[144:145], v[146:147]
	s_nop 0
	v_pk_add_f32 v[108:109], v[108:109], v[130:131]
	s_nop 0
	v_add_f32_e32 v108, v108, v109
	s_nop 1
	v_add_f32_dpp v108, v108, v108 quad_perm:[1,0,3,2] row_mask:0xf bank_mask:0xf bound_ctrl:1
	s_nop 1
	v_add_f32_dpp v108, v108, v108 quad_perm:[2,3,0,1] row_mask:0xf bank_mask:0xf bound_ctrl:1
	s_nop 1
	v_add_f32_dpp v108, v108, v108 row_half_mirror row_mask:0xf bank_mask:0xf bound_ctrl:1
	s_nop 1
	v_add_f32_dpp v108, v108, v108 row_mirror row_mask:0xf bank_mask:0xf bound_ctrl:1
	s_nop 0
	v_readlane_b32 s5, v108, 16
	v_readlane_b32 s11, v108, 48
	v_readlane_b32 s6, v108, 0
	v_readlane_b32 s7, v108, 32
	v_mov_b32_e32 v108, s5
	v_mov_b32_e32 v109, s11
	v_pk_add_f32 v[108:109], s[6:7], v[108:109]
	s_lshl_b32 s5, s36, 1
	v_add_f32_e32 v108, v108, v109
	v_fmamk_f32 v108, v108, 0x3a000000, v252
	v_cmp_gt_f32_e32 vcc, s55, v108
	v_mul_f32_e32 v109, 0x4f800000, v108
	s_and_b32 s5, s5, 0xffffe000
	v_cndmask_b32_e32 v108, v108, v109, vcc
	v_sqrt_f32_e32 v109, v108
	s_add_i32 s5, s5, 0
	v_add_u32_e32 v130, -1, v109
	v_fma_f32 v131, -v130, v109, v108
	v_cmp_ge_f32_e64 s[6:7], 0, v131
	v_add_u32_e32 v131, 1, v109
	s_nop 0
	v_cndmask_b32_e64 v130, v109, v130, s[6:7]
	v_fma_f32 v109, -v131, v109, v108
	v_cmp_lt_f32_e64 s[6:7], 0, v109
	s_nop 1
	v_cndmask_b32_e64 v109, v130, v131, s[6:7]
	v_mul_f32_e32 v130, 0x37800000, v109
	v_cndmask_b32_e32 v109, v109, v130, vcc
	v_cmp_class_f32_e32 vcc, v108, v253
	s_nop 1
	v_cndmask_b32_e32 v108, v109, v108, vcc
	v_div_scale_f32 v109, s[6:7], v108, v108, 1.0
	v_rcp_f32_e32 v130, v109
	s_nop 0
	v_fma_f32 v131, -v109, v130, 1.0
	v_fmac_f32_e32 v130, v131, v130
	v_div_scale_f32 v131, vcc, 1.0, v108, 1.0
	v_mul_f32_e32 v140, v131, v130
	v_fma_f32 v141, -v109, v140, v131
	v_fmac_f32_e32 v140, v141, v130
	v_fma_f32 v109, -v109, v140, v131
	v_div_fmas_f32 v109, v109, v130, v140
	v_div_fixup_f32 v130, v109, v108, 1.0
	v_pk_mul_f32 v[140:141], v[136:137], v[130:131] op_sel_hi:[1,0]
	v_pk_mul_f32 v[148:149], v[138:139], v[130:131] op_sel_hi:[1,0]
	v_add_u32_e32 v131, s5, v0
	ds_read_b128 v[136:139], v131
	ds_read_b128 v[144:147], v131 offset:40960
	v_lshl_add_u64 v[108:109], s[40:41], 1, v[2:3]
	v_lshl_add_u64 v[108:109], v[108:109], 0, v[6:7]
	v_pk_mul_f32 v[4:5], v[4:5], v[130:131] op_sel_hi:[1,0]
	s_waitcnt lgkmcnt(0)
	v_pk_fma_f32 v[138:139], v[138:139], v[148:149], v[146:147]
	v_pk_fma_f32 v[136:137], v[136:137], v[140:141], v[144:145]
	v_pk_mul_f32 v[140:141], v[132:133], v[130:131] op_sel_hi:[1,0]
	v_cvt_pk_bf16_f32 v136, v136, v137
	v_cvt_pk_bf16_f32 v137, v138, v139
	global_store_dwordx2 v[108:109], v[136:137], off
	v_pk_mul_f32 v[144:145], v[134:135], v[130:131] op_sel_hi:[1,0]
	ds_read_b128 v[132:135], v131 offset:1024
	ds_read_b128 v[136:139], v131 offset:41984
	s_waitcnt lgkmcnt(0)
	v_pk_fma_f32 v[134:135], v[134:135], v[144:145], v[138:139]
	v_pk_fma_f32 v[132:133], v[132:133], v[140:141], v[136:137]
	v_pk_mul_f32 v[136:137], v[122:123], v[130:131] op_sel_hi:[1,0]
	v_cvt_pk_bf16_f32 v132, v132, v133
	v_cvt_pk_bf16_f32 v133, v134, v135
	global_store_dwordx2 v[108:109], v[132:133], off offset:512
	v_pk_mul_f32 v[138:139], v[124:125], v[130:131] op_sel_hi:[1,0]
	ds_read_b128 v[122:125], v131 offset:2048
	ds_read_b128 v[132:135], v131 offset:43008
	s_waitcnt lgkmcnt(0)
	v_pk_fma_f32 v[124:125], v[124:125], v[138:139], v[134:135]
	v_pk_fma_f32 v[122:123], v[122:123], v[136:137], v[132:133]
	v_pk_mul_f32 v[132:133], v[126:127], v[130:131] op_sel_hi:[1,0]
	v_cvt_pk_bf16_f32 v122, v122, v123
	v_cvt_pk_bf16_f32 v123, v124, v125
	global_store_dwordx2 v[108:109], v[122:123], off offset:1024
	v_pk_mul_f32 v[134:135], v[128:129], v[130:131] op_sel_hi:[1,0]
	ds_read_b128 v[122:125], v131 offset:3072
	ds_read_b128 v[126:129], v131 offset:44032
	s_waitcnt lgkmcnt(0)
	v_pk_fma_f32 v[124:125], v[134:135], v[124:125], v[128:129]
	v_pk_fma_f32 v[122:123], v[132:133], v[122:123], v[126:127]
	v_pk_mul_f32 v[126:127], v[116:117], v[130:131] op_sel_hi:[1,0]
	v_cvt_pk_bf16_f32 v122, v122, v123
	v_cvt_pk_bf16_f32 v123, v124, v125
	global_store_dwordx2 v[108:109], v[122:123], off offset:1536
	v_pk_mul_f32 v[128:129], v[118:119], v[130:131] op_sel_hi:[1,0]
	ds_read_b128 v[116:119], v131 offset:4096
	ds_read_b128 v[122:125], v131 offset:45056
	s_waitcnt lgkmcnt(0)
	v_pk_fma_f32 v[118:119], v[128:129], v[118:119], v[124:125]
	v_pk_fma_f32 v[116:117], v[126:127], v[116:117], v[122:123]
	v_pk_mul_f32 v[122:123], v[114:115], v[130:131] op_sel_hi:[1,0]
	v_cvt_pk_bf16_f32 v116, v116, v117
	v_cvt_pk_bf16_f32 v117, v118, v119
	global_store_dwordx2 v[108:109], v[116:117], off offset:2048
	v_pk_mul_f32 v[124:125], v[120:121], v[130:131] op_sel_hi:[1,0]
	ds_read_b128 v[114:117], v131 offset:5120
	ds_read_b128 v[118:121], v131 offset:46080
	s_waitcnt lgkmcnt(0)
	v_pk_fma_f32 v[116:117], v[124:125], v[116:117], v[120:121]
	v_pk_fma_f32 v[114:115], v[122:123], v[114:115], v[118:119]
	v_pk_mul_f32 v[120:121], v[112:113], v[130:131] op_sel_hi:[1,0]
	v_cvt_pk_bf16_f32 v114, v114, v115
	v_cvt_pk_bf16_f32 v115, v116, v117
	global_store_dwordx2 v[108:109], v[114:115], off offset:2560
	ds_read_b128 v[112:115], v131 offset:6144
	ds_read_b128 v[116:119], v131 offset:47104
	s_waitcnt vmcnt(61)
	v_cvt_f32_f16_sdwa v123, v107 dst_sel:DWORD dst_unused:UNUSED_PAD src0_sel:WORD_1
	v_cvt_f32_f16_e32 v122, v107
	s_waitcnt vmcnt(59)
	v_cvt_f32_f16_sdwa v107, v102 dst_sel:DWORD dst_unused:UNUSED_PAD src0_sel:WORD_1
	s_waitcnt lgkmcnt(0)
	v_pk_fma_f32 v[114:115], v[120:121], v[114:115], v[118:119]
	v_pk_fma_f32 v[4:5], v[4:5], v[112:113], v[116:117]
	v_cvt_f32_f16_sdwa v121, v106 dst_sel:DWORD dst_unused:UNUSED_PAD src0_sel:WORD_1
	v_cvt_pk_bf16_f32 v4, v4, v5
	v_cvt_pk_bf16_f32 v5, v114, v115
	global_store_dwordx2 v[108:109], v[4:5], off offset:3072
	v_pk_mul_f32 v[4:5], v[74:75], v[130:131] op_sel_hi:[1,0]
	v_pk_mul_f32 v[74:75], v[110:111], v[130:131] op_sel_hi:[1,0]
	ds_read_b128 v[110:113], v131 offset:7168
	ds_read_b128 v[114:117], v131 offset:48128
	v_cvt_f32_f16_e32 v120, v106
	v_cvt_f32_f16_sdwa v119, v105 dst_sel:DWORD dst_unused:UNUSED_PAD src0_sel:WORD_1
	v_cvt_f32_f16_e32 v118, v105
	v_cvt_f32_f16_e32 v106, v102
	s_waitcnt lgkmcnt(0)
	v_pk_fma_f32 v[74:75], v[74:75], v[112:113], v[116:117]
	v_cvt_f32_f16_sdwa v117, v104 dst_sel:DWORD dst_unused:UNUSED_PAD src0_sel:WORD_1
	v_pk_fma_f32 v[4:5], v[4:5], v[110:111], v[114:115]
	v_cvt_f32_f16_e32 v116, v104
	v_cvt_pk_bf16_f32 v4, v4, v5
	v_cvt_pk_bf16_f32 v5, v74, v75
	global_store_dwordx2 v[108:109], v[4:5], off offset:3584
	v_cvt_f32_f16_sdwa v109, v103 dst_sel:DWORD dst_unused:UNUSED_PAD src0_sel:WORD_1
	s_waitcnt vmcnt(60)
	v_cvt_f32_f16_sdwa v111, v100 dst_sel:DWORD dst_unused:UNUSED_PAD src0_sel:WORD_1
	v_mov_b32_e32 v74, v121
	v_mov_b32_e32 v75, v117
	v_cvt_f32_f16_e32 v108, v103
	v_cvt_f32_f16_e32 v110, v100
	v_cvt_f32_f16_sdwa v113, v101 dst_sel:DWORD dst_unused:UNUSED_PAD src0_sel:WORD_1
	v_mov_b32_e32 v4, v120
	v_mov_b32_e32 v5, v116
	v_pk_mul_f32 v[74:75], v[74:75], v[74:75]
	v_mov_b32_e32 v104, v123
	v_mov_b32_e32 v105, v119
	v_cvt_f32_f16_e32 v112, v101
	v_pk_fma_f32 v[4:5], v[4:5], v[4:5], v[74:75]
	v_mov_b32_e32 v74, v122
	v_mov_b32_e32 v75, v118
	v_pk_mul_f32 v[104:105], v[104:105], v[104:105]
	v_mov_b32_e32 v102, v107
	v_pk_fma_f32 v[74:75], v[74:75], v[74:75], v[104:105]
	v_mov_b32_e32 v103, v109
	v_mul_f32_e32 v100, v111, v111
	v_pk_add_f32 v[4:5], v[4:5], v[74:75]
	v_mov_b32_e32 v74, v106
	v_mov_b32_e32 v75, v108
	v_pk_mul_f32 v[102:103], v[102:103], v[102:103]
	v_pk_fma_f32 v[104:105], v[110:111], v[110:111], v[100:101] op_sel_hi:[1,1,0]
	v_mul_f32_e32 v100, v113, v113
	v_pk_fma_f32 v[74:75], v[74:75], v[74:75], v[102:103]
	v_pk_fma_f32 v[114:115], v[112:113], v[112:113], v[100:101] op_sel_hi:[1,1,0]
	s_waitcnt vmcnt(59)
	v_cvt_f32_f16_sdwa v101, v98 dst_sel:DWORD dst_unused:UNUSED_PAD src0_sel:WORD_1
	v_cvt_f32_f16_e32 v100, v98
	v_cvt_f32_f16_sdwa v103, v99 dst_sel:DWORD dst_unused:UNUSED_PAD src0_sel:WORD_1
	v_cvt_f32_f16_e32 v102, v99
	v_pk_add_f32 v[4:5], v[4:5], v[4:5] op_sel:[0,1] op_sel_hi:[1,0]
	v_pk_add_f32 v[74:75], v[74:75], v[74:75] op_sel:[0,1] op_sel_hi:[1,0]
	v_pk_mul_f32 v[98:99], v[100:101], v[100:101]
	v_pk_mul_f32 v[124:125], v[102:103], v[102:103]
	v_mov_b32_e32 v5, v98
	v_mov_b32_e32 v75, v99
	v_mov_b32_e32 v105, v124
	v_mov_b32_e32 v115, v125
	v_pk_add_f32 v[4:5], v[4:5], v[74:75]
	v_pk_add_f32 v[74:75], v[104:105], v[114:115]
	s_waitcnt vmcnt(58)
	v_cvt_f32_f16_sdwa v99, v96 dst_sel:DWORD dst_unused:UNUSED_PAD src0_sel:WORD_1
	v_cvt_f32_f16_sdwa v105, v97 dst_sel:DWORD dst_unused:UNUSED_PAD src0_sel:WORD_1
	v_cvt_f32_f16_e32 v98, v96
	v_cvt_f32_f16_e32 v104, v97
	v_pk_add_f32 v[4:5], v[4:5], v[74:75]
	v_mov_b32_e32 v74, v99
	v_mov_b32_e32 v75, v105
	v_pk_add_f32 v[114:115], v[4:5], v[4:5] op_sel:[0,1] op_sel_hi:[1,0]
	v_mov_b32_e32 v4, v98
	v_mov_b32_e32 v5, v104
	v_pk_mul_f32 v[74:75], v[74:75], v[74:75]
	s_waitcnt vmcnt(57)
	v_cvt_f32_f16_sdwa v97, v95 dst_sel:DWORD dst_unused:UNUSED_PAD src0_sel:WORD_1
	v_pk_fma_f32 v[4:5], v[4:5], v[4:5], v[74:75]
	v_cvt_f32_f16_e32 v96, v95
	v_pk_add_f32 v[124:125], v[4:5], v[4:5] op_sel:[0,1] op_sel_hi:[1,0]
	v_cvt_f32_f16_sdwa v5, v94 dst_sel:DWORD dst_unused:UNUSED_PAD src0_sel:WORD_1
	v_cvt_f32_f16_e32 v4, v94
	s_waitcnt vmcnt(56)
	v_cvt_f32_f16_sdwa v95, v93 dst_sel:DWORD dst_unused:UNUSED_PAD src0_sel:WORD_1
	v_cvt_f32_f16_e32 v94, v93
	v_mul_f32_e32 v74, v5, v5
	v_pk_fma_f32 v[126:127], v[4:5], v[4:5], v[74:75] op_sel_hi:[1,1,0]
	v_mul_f32_e32 v74, v97, v97
	v_pk_fma_f32 v[128:129], v[96:97], v[96:97], v[74:75] op_sel_hi:[1,1,0]
	v_cvt_f32_f16_sdwa v75, v92 dst_sel:DWORD dst_unused:UNUSED_PAD src0_sel:WORD_1
	v_cvt_f32_f16_e32 v74, v92
	v_pk_mul_f32 v[130:131], v[94:95], v[94:95]
	v_pk_mul_f32 v[92:93], v[74:75], v[74:75]
	s_nop 0
	v_mov_b32_e32 v115, v92
	v_mov_b32_e32 v125, v93
	v_mov_b32_e32 v127, v130
	v_mov_b32_e32 v129, v131
	v_pk_add_f32 v[92:93], v[114:115], v[124:125]
	v_pk_add_f32 v[114:115], v[126:127], v[128:129]
	s_nop 0
	v_pk_add_f32 v[92:93], v[92:93], v[114:115]
	s_nop 0
	v_add_f32_e32 v92, v92, v93
	s_nop 1
	v_add_f32_dpp v92, v92, v92 quad_perm:[1,0,3,2] row_mask:0xf bank_mask:0xf bound_ctrl:1
	s_nop 1
	v_add_f32_dpp v92, v92, v92 quad_perm:[2,3,0,1] row_mask:0xf bank_mask:0xf bound_ctrl:1
	s_nop 1
	v_add_f32_dpp v92, v92, v92 row_half_mirror row_mask:0xf bank_mask:0xf bound_ctrl:1
	s_nop 1
	v_add_f32_dpp v92, v92, v92 row_mirror row_mask:0xf bank_mask:0xf bound_ctrl:1
	s_nop 0
	v_readlane_b32 s5, v92, 16
	v_readlane_b32 s11, v92, 48
	v_readlane_b32 s6, v92, 0
	v_readlane_b32 s7, v92, 32
	v_mov_b32_e32 v92, s5
	v_mov_b32_e32 v93, s11
	v_pk_add_f32 v[92:93], s[6:7], v[92:93]
	s_lshl_b32 s5, s30, 1
	v_add_f32_e32 v92, v92, v93
	v_fmamk_f32 v92, v92, 0x3a000000, v252
	v_cmp_gt_f32_e32 vcc, s55, v92
	v_mul_f32_e32 v93, 0x4f800000, v92
	s_and_b32 s5, s5, 0xffffe000
	v_cndmask_b32_e32 v92, v92, v93, vcc
	v_sqrt_f32_e32 v93, v92
	s_add_i32 s5, s5, 0
	v_add_u32_e32 v114, -1, v93
	v_fma_f32 v115, -v114, v93, v92
	v_cmp_ge_f32_e64 s[6:7], 0, v115
	v_add_u32_e32 v115, 1, v93
	s_nop 0
	v_cndmask_b32_e64 v114, v93, v114, s[6:7]
	v_fma_f32 v93, -v115, v93, v92
	v_cmp_lt_f32_e64 s[6:7], 0, v93
	s_nop 1
	v_cndmask_b32_e64 v93, v114, v115, s[6:7]
	v_mul_f32_e32 v114, 0x37800000, v93
	v_cndmask_b32_e32 v93, v93, v114, vcc
	v_cmp_class_f32_e32 vcc, v92, v253
	s_nop 1
	v_cndmask_b32_e32 v92, v93, v92, vcc
	v_div_scale_f32 v93, s[6:7], v92, v92, 1.0
	v_rcp_f32_e32 v114, v93
	s_nop 0
	v_fma_f32 v115, -v93, v114, 1.0
	v_fmac_f32_e32 v114, v115, v114
	v_div_scale_f32 v115, vcc, 1.0, v92, 1.0
	v_mul_f32_e32 v124, v115, v114
	v_fma_f32 v125, -v93, v124, v115
	v_fmac_f32_e32 v124, v125, v114
	v_fma_f32 v93, -v93, v124, v115
	v_div_fmas_f32 v93, v93, v114, v124
	v_div_fixup_f32 v114, v93, v92, 1.0
	v_pk_mul_f32 v[128:129], v[120:121], v[114:115] op_sel_hi:[1,0]
	v_pk_mul_f32 v[130:131], v[122:123], v[114:115] op_sel_hi:[1,0]
	v_add_u32_e32 v115, s5, v0
	ds_read_b128 v[120:123], v115
	ds_read_b128 v[124:127], v115 offset:40960
	v_lshl_add_u64 v[92:93], s[34:35], 1, v[2:3]
	v_lshl_add_u64 v[92:93], v[92:93], 0, v[6:7]
	v_pk_mul_f32 v[4:5], v[4:5], v[114:115] op_sel_hi:[1,0]
	s_waitcnt lgkmcnt(0)
	v_pk_fma_f32 v[122:123], v[122:123], v[130:131], v[126:127]
	v_pk_fma_f32 v[120:121], v[120:121], v[128:129], v[124:125]
	v_pk_mul_f32 v[124:125], v[116:117], v[114:115] op_sel_hi:[1,0]
	v_cvt_pk_bf16_f32 v120, v120, v121
	v_cvt_pk_bf16_f32 v121, v122, v123
	global_store_dwordx2 v[92:93], v[120:121], off
	v_pk_mul_f32 v[126:127], v[118:119], v[114:115] op_sel_hi:[1,0]
	ds_read_b128 v[116:119], v115 offset:1024
	ds_read_b128 v[120:123], v115 offset:41984
	s_waitcnt lgkmcnt(0)
	v_pk_fma_f32 v[118:119], v[118:119], v[126:127], v[122:123]
	v_pk_fma_f32 v[116:117], v[116:117], v[124:125], v[120:121]
	v_pk_mul_f32 v[120:121], v[106:107], v[114:115] op_sel_hi:[1,0]
	v_cvt_pk_bf16_f32 v116, v116, v117
	v_cvt_pk_bf16_f32 v117, v118, v119
	global_store_dwordx2 v[92:93], v[116:117], off offset:512
	v_pk_mul_f32 v[122:123], v[108:109], v[114:115] op_sel_hi:[1,0]
	ds_read_b128 v[106:109], v115 offset:2048
	ds_read_b128 v[116:119], v115 offset:43008
	s_waitcnt lgkmcnt(0)
	v_pk_fma_f32 v[108:109], v[108:109], v[122:123], v[118:119]
	v_pk_fma_f32 v[106:107], v[106:107], v[120:121], v[116:117]
	v_pk_mul_f32 v[116:117], v[110:111], v[114:115] op_sel_hi:[1,0]
	v_cvt_pk_bf16_f32 v106, v106, v107
	v_cvt_pk_bf16_f32 v107, v108, v109
	global_store_dwordx2 v[92:93], v[106:107], off offset:1024
	v_pk_mul_f32 v[118:119], v[112:113], v[114:115] op_sel_hi:[1,0]
	ds_read_b128 v[106:109], v115 offset:3072
	ds_read_b128 v[110:113], v115 offset:44032
	s_waitcnt lgkmcnt(0)
	v_pk_fma_f32 v[108:109], v[118:119], v[108:109], v[112:113]
	v_pk_fma_f32 v[106:107], v[116:117], v[106:107], v[110:111]
	v_pk_mul_f32 v[110:111], v[100:101], v[114:115] op_sel_hi:[1,0]
	v_cvt_pk_bf16_f32 v106, v106, v107
	v_cvt_pk_bf16_f32 v107, v108, v109
	global_store_dwordx2 v[92:93], v[106:107], off offset:1536
	v_pk_mul_f32 v[112:113], v[102:103], v[114:115] op_sel_hi:[1,0]
	ds_read_b128 v[100:103], v115 offset:4096
	ds_read_b128 v[106:109], v115 offset:45056
	s_waitcnt lgkmcnt(0)
	v_pk_fma_f32 v[102:103], v[112:113], v[102:103], v[108:109]
	v_pk_fma_f32 v[100:101], v[110:111], v[100:101], v[106:107]
	v_pk_mul_f32 v[106:107], v[98:99], v[114:115] op_sel_hi:[1,0]
	v_cvt_pk_bf16_f32 v100, v100, v101
	v_cvt_pk_bf16_f32 v101, v102, v103
	global_store_dwordx2 v[92:93], v[100:101], off offset:2048
	v_pk_mul_f32 v[108:109], v[104:105], v[114:115] op_sel_hi:[1,0]
	ds_read_b128 v[98:101], v115 offset:5120
	ds_read_b128 v[102:105], v115 offset:46080
	s_waitcnt lgkmcnt(0)
	v_pk_fma_f32 v[100:101], v[108:109], v[100:101], v[104:105]
	v_pk_fma_f32 v[98:99], v[106:107], v[98:99], v[102:103]
	v_pk_mul_f32 v[104:105], v[96:97], v[114:115] op_sel_hi:[1,0]
	v_cvt_pk_bf16_f32 v98, v98, v99
	v_cvt_pk_bf16_f32 v99, v100, v101
	global_store_dwordx2 v[92:93], v[98:99], off offset:2560
	ds_read_b128 v[96:99], v115 offset:6144
	ds_read_b128 v[100:103], v115 offset:47104
	s_waitcnt vmcnt(61)
	v_cvt_f32_f16_sdwa v107, v91 dst_sel:DWORD dst_unused:UNUSED_PAD src0_sel:WORD_1
	v_cvt_f32_f16_e32 v106, v91
	s_waitcnt vmcnt(59)
	v_cvt_f32_f16_sdwa v91, v86 dst_sel:DWORD dst_unused:UNUSED_PAD src0_sel:WORD_1
	s_waitcnt lgkmcnt(0)
	v_pk_fma_f32 v[98:99], v[104:105], v[98:99], v[102:103]
	v_pk_fma_f32 v[4:5], v[4:5], v[96:97], v[100:101]
	v_cvt_f32_f16_sdwa v105, v90 dst_sel:DWORD dst_unused:UNUSED_PAD src0_sel:WORD_1
	v_cvt_pk_bf16_f32 v4, v4, v5
	v_cvt_pk_bf16_f32 v5, v98, v99
	global_store_dwordx2 v[92:93], v[4:5], off offset:3072
	v_pk_mul_f32 v[4:5], v[74:75], v[114:115] op_sel_hi:[1,0]
	v_pk_mul_f32 v[74:75], v[94:95], v[114:115] op_sel_hi:[1,0]
	ds_read_b128 v[94:97], v115 offset:7168
	ds_read_b128 v[98:101], v115 offset:48128
	v_cvt_f32_f16_e32 v104, v90
	v_cvt_f32_f16_sdwa v103, v89 dst_sel:DWORD dst_unused:UNUSED_PAD src0_sel:WORD_1
	v_cvt_f32_f16_e32 v102, v89
	v_cvt_f32_f16_e32 v90, v86
	s_waitcnt lgkmcnt(0)
	v_pk_fma_f32 v[74:75], v[74:75], v[96:97], v[100:101]
	v_cvt_f32_f16_sdwa v101, v88 dst_sel:DWORD dst_unused:UNUSED_PAD src0_sel:WORD_1
	v_pk_fma_f32 v[4:5], v[4:5], v[94:95], v[98:99]
	v_cvt_f32_f16_e32 v100, v88
	v_cvt_pk_bf16_f32 v4, v4, v5
	v_cvt_pk_bf16_f32 v5, v74, v75
	global_store_dwordx2 v[92:93], v[4:5], off offset:3584
	v_cvt_f32_f16_sdwa v93, v87 dst_sel:DWORD dst_unused:UNUSED_PAD src0_sel:WORD_1
	s_waitcnt vmcnt(60)
	v_cvt_f32_f16_sdwa v95, v84 dst_sel:DWORD dst_unused:UNUSED_PAD src0_sel:WORD_1
	v_mov_b32_e32 v74, v105
	v_mov_b32_e32 v75, v101
	v_cvt_f32_f16_e32 v92, v87
	v_cvt_f32_f16_e32 v94, v84
	v_cvt_f32_f16_sdwa v97, v85 dst_sel:DWORD dst_unused:UNUSED_PAD src0_sel:WORD_1
	v_mov_b32_e32 v4, v104
	v_mov_b32_e32 v5, v100
	v_pk_mul_f32 v[74:75], v[74:75], v[74:75]
	v_mov_b32_e32 v88, v107
	v_mov_b32_e32 v89, v103
	v_cvt_f32_f16_e32 v96, v85
	v_pk_fma_f32 v[4:5], v[4:5], v[4:5], v[74:75]
	v_mov_b32_e32 v74, v106
	v_mov_b32_e32 v75, v102
	v_pk_mul_f32 v[88:89], v[88:89], v[88:89]
	v_mov_b32_e32 v86, v91
	v_pk_fma_f32 v[74:75], v[74:75], v[74:75], v[88:89]
	v_mov_b32_e32 v87, v93
	v_mul_f32_e32 v84, v95, v95
	v_pk_add_f32 v[4:5], v[4:5], v[74:75]
	v_mov_b32_e32 v74, v90
	v_mov_b32_e32 v75, v92
	v_pk_mul_f32 v[86:87], v[86:87], v[86:87]
	v_pk_fma_f32 v[88:89], v[94:95], v[94:95], v[84:85] op_sel_hi:[1,1,0]
	v_mul_f32_e32 v84, v97, v97
	v_pk_fma_f32 v[74:75], v[74:75], v[74:75], v[86:87]
	v_pk_fma_f32 v[98:99], v[96:97], v[96:97], v[84:85] op_sel_hi:[1,1,0]
	s_waitcnt vmcnt(59)
	v_cvt_f32_f16_sdwa v85, v82 dst_sel:DWORD dst_unused:UNUSED_PAD src0_sel:WORD_1
	v_cvt_f32_f16_e32 v84, v82
	v_cvt_f32_f16_sdwa v87, v83 dst_sel:DWORD dst_unused:UNUSED_PAD src0_sel:WORD_1
	v_cvt_f32_f16_e32 v86, v83
	v_pk_add_f32 v[4:5], v[4:5], v[4:5] op_sel:[0,1] op_sel_hi:[1,0]
	v_pk_add_f32 v[74:75], v[74:75], v[74:75] op_sel:[0,1] op_sel_hi:[1,0]
	v_pk_mul_f32 v[82:83], v[84:85], v[84:85]
	v_pk_mul_f32 v[108:109], v[86:87], v[86:87]
	v_mov_b32_e32 v5, v82
	v_mov_b32_e32 v75, v83
	v_mov_b32_e32 v89, v108
	v_mov_b32_e32 v99, v109
	v_pk_add_f32 v[4:5], v[4:5], v[74:75]
	v_pk_add_f32 v[74:75], v[88:89], v[98:99]
	s_waitcnt vmcnt(58)
	v_cvt_f32_f16_sdwa v83, v80 dst_sel:DWORD dst_unused:UNUSED_PAD src0_sel:WORD_1
	v_cvt_f32_f16_sdwa v89, v81 dst_sel:DWORD dst_unused:UNUSED_PAD src0_sel:WORD_1
	v_cvt_f32_f16_e32 v82, v80
	v_cvt_f32_f16_e32 v88, v81
	v_pk_add_f32 v[4:5], v[4:5], v[74:75]
	v_mov_b32_e32 v74, v83
	v_mov_b32_e32 v75, v89
	v_pk_add_f32 v[98:99], v[4:5], v[4:5] op_sel:[0,1] op_sel_hi:[1,0]
	v_mov_b32_e32 v4, v82
	v_mov_b32_e32 v5, v88
	v_pk_mul_f32 v[74:75], v[74:75], v[74:75]
	s_waitcnt vmcnt(57)
	v_cvt_f32_f16_sdwa v81, v79 dst_sel:DWORD dst_unused:UNUSED_PAD src0_sel:WORD_1
	v_pk_fma_f32 v[4:5], v[4:5], v[4:5], v[74:75]
	v_cvt_f32_f16_e32 v80, v79
	v_pk_add_f32 v[108:109], v[4:5], v[4:5] op_sel:[0,1] op_sel_hi:[1,0]
	v_cvt_f32_f16_sdwa v5, v78 dst_sel:DWORD dst_unused:UNUSED_PAD src0_sel:WORD_1
	v_cvt_f32_f16_e32 v4, v78
	s_waitcnt vmcnt(56)
	v_cvt_f32_f16_sdwa v79, v77 dst_sel:DWORD dst_unused:UNUSED_PAD src0_sel:WORD_1
	v_cvt_f32_f16_e32 v78, v77
	v_mul_f32_e32 v74, v5, v5
	v_pk_fma_f32 v[110:111], v[4:5], v[4:5], v[74:75] op_sel_hi:[1,1,0]
	v_mul_f32_e32 v74, v81, v81
	v_pk_fma_f32 v[112:113], v[80:81], v[80:81], v[74:75] op_sel_hi:[1,1,0]
	v_cvt_f32_f16_sdwa v75, v76 dst_sel:DWORD dst_unused:UNUSED_PAD src0_sel:WORD_1
	v_cvt_f32_f16_e32 v74, v76
	v_pk_mul_f32 v[114:115], v[78:79], v[78:79]
	v_pk_mul_f32 v[76:77], v[74:75], v[74:75]
	s_nop 0
	v_mov_b32_e32 v99, v76
	v_mov_b32_e32 v109, v77
	v_mov_b32_e32 v111, v114
	v_mov_b32_e32 v113, v115
	v_pk_add_f32 v[76:77], v[98:99], v[108:109]
	v_pk_add_f32 v[98:99], v[110:111], v[112:113]
	s_nop 0
	v_pk_add_f32 v[76:77], v[76:77], v[98:99]
	s_nop 0
	v_add_f32_e32 v76, v76, v77
	s_nop 1
	v_add_f32_dpp v76, v76, v76 quad_perm:[1,0,3,2] row_mask:0xf bank_mask:0xf bound_ctrl:1
	s_nop 1
	v_add_f32_dpp v76, v76, v76 quad_perm:[2,3,0,1] row_mask:0xf bank_mask:0xf bound_ctrl:1
	s_nop 1
	v_add_f32_dpp v76, v76, v76 row_half_mirror row_mask:0xf bank_mask:0xf bound_ctrl:1
	s_nop 1
	v_add_f32_dpp v76, v76, v76 row_mirror row_mask:0xf bank_mask:0xf bound_ctrl:1
	s_nop 0
	v_readlane_b32 s5, v76, 16
	v_readlane_b32 s11, v76, 48
	v_readlane_b32 s6, v76, 0
	v_readlane_b32 s7, v76, 32
	v_mov_b32_e32 v76, s5
	v_mov_b32_e32 v77, s11
	v_pk_add_f32 v[76:77], s[6:7], v[76:77]
	s_lshl_b32 s5, s26, 1
	v_add_f32_e32 v76, v76, v77
	v_fmamk_f32 v76, v76, 0x3a000000, v252
	v_cmp_gt_f32_e32 vcc, s55, v76
	v_mul_f32_e32 v77, 0x4f800000, v76
	s_and_b32 s5, s5, 0xffffe000
	v_cndmask_b32_e32 v76, v76, v77, vcc
	v_sqrt_f32_e32 v77, v76
	s_add_i32 s5, s5, 0
	v_add_u32_e32 v98, -1, v77
	v_fma_f32 v99, -v98, v77, v76
	v_cmp_ge_f32_e64 s[6:7], 0, v99
	v_add_u32_e32 v99, 1, v77
	s_nop 0
	v_cndmask_b32_e64 v98, v77, v98, s[6:7]
	v_fma_f32 v77, -v99, v77, v76
	v_cmp_lt_f32_e64 s[6:7], 0, v77
	s_nop 1
	v_cndmask_b32_e64 v77, v98, v99, s[6:7]
	v_mul_f32_e32 v98, 0x37800000, v77
	v_cndmask_b32_e32 v77, v77, v98, vcc
	v_cmp_class_f32_e32 vcc, v76, v253
	s_nop 1
	v_cndmask_b32_e32 v76, v77, v76, vcc
	v_div_scale_f32 v77, s[6:7], v76, v76, 1.0
	v_rcp_f32_e32 v98, v77
	s_nop 0
	v_fma_f32 v99, -v77, v98, 1.0
	v_fmac_f32_e32 v98, v99, v98
	v_div_scale_f32 v99, vcc, 1.0, v76, 1.0
	v_mul_f32_e32 v108, v99, v98
	v_fma_f32 v109, -v77, v108, v99
	v_fmac_f32_e32 v108, v109, v98
	v_fma_f32 v77, -v77, v108, v99
	v_div_fmas_f32 v77, v77, v98, v108
	v_div_fixup_f32 v98, v77, v76, 1.0
	v_pk_mul_f32 v[112:113], v[104:105], v[98:99] op_sel_hi:[1,0]
	v_pk_mul_f32 v[114:115], v[106:107], v[98:99] op_sel_hi:[1,0]
	v_add_u32_e32 v99, s5, v0
	ds_read_b128 v[104:107], v99
	ds_read_b128 v[108:111], v99 offset:40960
	v_lshl_add_u64 v[76:77], s[28:29], 1, v[2:3]
	v_lshl_add_u64 v[76:77], v[76:77], 0, v[6:7]
	v_pk_mul_f32 v[4:5], v[4:5], v[98:99] op_sel_hi:[1,0]
	s_waitcnt lgkmcnt(0)
	v_pk_fma_f32 v[106:107], v[106:107], v[114:115], v[110:111]
	v_pk_fma_f32 v[104:105], v[104:105], v[112:113], v[108:109]
	v_pk_mul_f32 v[108:109], v[100:101], v[98:99] op_sel_hi:[1,0]
	v_cvt_pk_bf16_f32 v104, v104, v105
	v_cvt_pk_bf16_f32 v105, v106, v107
	global_store_dwordx2 v[76:77], v[104:105], off
	v_pk_mul_f32 v[110:111], v[102:103], v[98:99] op_sel_hi:[1,0]
	ds_read_b128 v[100:103], v99 offset:1024
	ds_read_b128 v[104:107], v99 offset:41984
	s_waitcnt lgkmcnt(0)
	v_pk_fma_f32 v[102:103], v[102:103], v[110:111], v[106:107]
	v_pk_fma_f32 v[100:101], v[100:101], v[108:109], v[104:105]
	v_pk_mul_f32 v[104:105], v[90:91], v[98:99] op_sel_hi:[1,0]
	v_cvt_pk_bf16_f32 v100, v100, v101
	v_cvt_pk_bf16_f32 v101, v102, v103
	global_store_dwordx2 v[76:77], v[100:101], off offset:512
	v_pk_mul_f32 v[106:107], v[92:93], v[98:99] op_sel_hi:[1,0]
	ds_read_b128 v[90:93], v99 offset:2048
	ds_read_b128 v[100:103], v99 offset:43008
	s_waitcnt lgkmcnt(0)
	v_pk_fma_f32 v[92:93], v[92:93], v[106:107], v[102:103]
	v_pk_fma_f32 v[90:91], v[90:91], v[104:105], v[100:101]
	v_pk_mul_f32 v[100:101], v[94:95], v[98:99] op_sel_hi:[1,0]
	v_cvt_pk_bf16_f32 v90, v90, v91
	v_cvt_pk_bf16_f32 v91, v92, v93
	global_store_dwordx2 v[76:77], v[90:91], off offset:1024
	v_pk_mul_f32 v[102:103], v[96:97], v[98:99] op_sel_hi:[1,0]
	ds_read_b128 v[90:93], v99 offset:3072
	ds_read_b128 v[94:97], v99 offset:44032
	s_waitcnt lgkmcnt(0)
	v_pk_fma_f32 v[92:93], v[102:103], v[92:93], v[96:97]
	v_pk_fma_f32 v[90:91], v[100:101], v[90:91], v[94:95]
	v_pk_mul_f32 v[94:95], v[84:85], v[98:99] op_sel_hi:[1,0]
	v_cvt_pk_bf16_f32 v90, v90, v91
	v_cvt_pk_bf16_f32 v91, v92, v93
	global_store_dwordx2 v[76:77], v[90:91], off offset:1536
	v_pk_mul_f32 v[96:97], v[86:87], v[98:99] op_sel_hi:[1,0]
	ds_read_b128 v[84:87], v99 offset:4096
	ds_read_b128 v[90:93], v99 offset:45056
	s_waitcnt lgkmcnt(0)
	v_pk_fma_f32 v[86:87], v[96:97], v[86:87], v[92:93]
	v_pk_fma_f32 v[84:85], v[94:95], v[84:85], v[90:91]
	v_pk_mul_f32 v[90:91], v[82:83], v[98:99] op_sel_hi:[1,0]
	v_cvt_pk_bf16_f32 v84, v84, v85
	v_cvt_pk_bf16_f32 v85, v86, v87
	global_store_dwordx2 v[76:77], v[84:85], off offset:2048
	v_pk_mul_f32 v[92:93], v[88:89], v[98:99] op_sel_hi:[1,0]
	ds_read_b128 v[82:85], v99 offset:5120
	ds_read_b128 v[86:89], v99 offset:46080
	s_waitcnt lgkmcnt(0)
	v_pk_fma_f32 v[84:85], v[92:93], v[84:85], v[88:89]
	v_pk_fma_f32 v[82:83], v[90:91], v[82:83], v[86:87]
	v_pk_mul_f32 v[88:89], v[80:81], v[98:99] op_sel_hi:[1,0]
	v_cvt_pk_bf16_f32 v82, v82, v83
	v_cvt_pk_bf16_f32 v83, v84, v85
	global_store_dwordx2 v[76:77], v[82:83], off offset:2560
	ds_read_b128 v[80:83], v99 offset:6144
	ds_read_b128 v[84:87], v99 offset:47104
	s_waitcnt vmcnt(61)
	v_cvt_f32_f16_sdwa v91, v73 dst_sel:DWORD dst_unused:UNUSED_PAD src0_sel:WORD_1
	v_cvt_f32_f16_e32 v90, v73
	s_waitcnt lgkmcnt(0)
	v_pk_fma_f32 v[82:83], v[88:89], v[82:83], v[86:87]
	v_pk_fma_f32 v[4:5], v[4:5], v[80:81], v[84:85]
	v_cvt_f32_f16_sdwa v89, v72 dst_sel:DWORD dst_unused:UNUSED_PAD src0_sel:WORD_1
	v_cvt_pk_bf16_f32 v4, v4, v5
	v_cvt_pk_bf16_f32 v5, v82, v83
	global_store_dwordx2 v[76:77], v[4:5], off offset:3072
	v_pk_mul_f32 v[4:5], v[74:75], v[98:99] op_sel_hi:[1,0]
	v_pk_mul_f32 v[74:75], v[78:79], v[98:99] op_sel_hi:[1,0]
	ds_read_b128 v[78:81], v99 offset:7168
	ds_read_b128 v[82:85], v99 offset:48128
	v_cvt_f32_f16_e32 v88, v72
	s_waitcnt vmcnt(61)
	v_cvt_f32_f16_sdwa v87, v71 dst_sel:DWORD dst_unused:UNUSED_PAD src0_sel:WORD_1
	v_cvt_f32_f16_e32 v86, v71
	v_mov_b32_e32 v72, v91
	s_waitcnt lgkmcnt(0)
	v_pk_fma_f32 v[74:75], v[74:75], v[80:81], v[84:85]
	v_cvt_f32_f16_sdwa v85, v70 dst_sel:DWORD dst_unused:UNUSED_PAD src0_sel:WORD_1
	v_cvt_f32_f16_e32 v84, v70
	v_pk_fma_f32 v[4:5], v[4:5], v[78:79], v[82:83]
	v_mov_b32_e32 v70, v89
	v_cvt_pk_bf16_f32 v4, v4, v5
	v_cvt_pk_bf16_f32 v5, v74, v75
	global_store_dwordx2 v[76:77], v[4:5], off offset:3584
	v_mov_b32_e32 v71, v85
	s_waitcnt vmcnt(61)
	v_cvt_f32_f16_sdwa v75, v68 dst_sel:DWORD dst_unused:UNUSED_PAD src0_sel:WORD_1
	v_cvt_f32_f16_sdwa v77, v69 dst_sel:DWORD dst_unused:UNUSED_PAD src0_sel:WORD_1
	v_mov_b32_e32 v4, v88
	v_mov_b32_e32 v5, v84
	v_pk_mul_f32 v[70:71], v[70:71], v[70:71]
	v_mov_b32_e32 v73, v87
	v_cvt_f32_f16_e32 v74, v68
	v_cvt_f32_f16_e32 v76, v69
	s_waitcnt vmcnt(60)
	v_cvt_f32_f16_sdwa v79, v66 dst_sel:DWORD dst_unused:UNUSED_PAD src0_sel:WORD_1
	v_pk_fma_f32 v[4:5], v[4:5], v[4:5], v[70:71]
	v_mov_b32_e32 v70, v90
	v_mov_b32_e32 v71, v86
	v_pk_mul_f32 v[72:73], v[72:73], v[72:73]
	v_cvt_f32_f16_e32 v78, v66
	v_cvt_f32_f16_sdwa v81, v67 dst_sel:DWORD dst_unused:UNUSED_PAD src0_sel:WORD_1
	v_pk_fma_f32 v[70:71], v[70:71], v[70:71], v[72:73]
	v_cvt_f32_f16_e32 v80, v67
	v_pk_add_f32 v[4:5], v[4:5], v[70:71]
	v_mov_b32_e32 v70, v75
	v_mov_b32_e32 v71, v77
	v_mov_b32_e32 v68, v74
	v_mov_b32_e32 v69, v76
	v_pk_mul_f32 v[70:71], v[70:71], v[70:71]
	v_mul_f32_e32 v66, v79, v79
	v_pk_fma_f32 v[68:69], v[68:69], v[68:69], v[70:71]
	v_pk_fma_f32 v[72:73], v[78:79], v[78:79], v[66:67] op_sel_hi:[1,1,0]
	v_mul_f32_e32 v66, v81, v81
	v_pk_add_f32 v[70:71], v[68:69], v[68:69] op_sel:[0,1] op_sel_hi:[1,0]
	v_pk_fma_f32 v[82:83], v[80:81], v[80:81], v[66:67] op_sel_hi:[1,1,0]
	s_waitcnt vmcnt(59)
	v_cvt_f32_f16_sdwa v67, v64 dst_sel:DWORD dst_unused:UNUSED_PAD src0_sel:WORD_1
	v_cvt_f32_f16_e32 v66, v64
	v_cvt_f32_f16_sdwa v69, v65 dst_sel:DWORD dst_unused:UNUSED_PAD src0_sel:WORD_1
	v_cvt_f32_f16_e32 v68, v65
	v_pk_add_f32 v[4:5], v[4:5], v[4:5] op_sel:[0,1] op_sel_hi:[1,0]
	v_pk_mul_f32 v[64:65], v[66:67], v[66:67]
	v_pk_mul_f32 v[92:93], v[68:69], v[68:69]
	v_mov_b32_e32 v5, v64
	v_mov_b32_e32 v71, v65
	v_mov_b32_e32 v73, v92
	v_mov_b32_e32 v83, v93
	v_pk_add_f32 v[4:5], v[4:5], v[70:71]
	v_pk_add_f32 v[64:65], v[72:73], v[82:83]
	s_waitcnt vmcnt(58)
	v_cvt_f32_f16_sdwa v71, v62 dst_sel:DWORD dst_unused:UNUSED_PAD src0_sel:WORD_1
	v_cvt_f32_f16_sdwa v73, v63 dst_sel:DWORD dst_unused:UNUSED_PAD src0_sel:WORD_1
	v_cvt_f32_f16_e32 v70, v62
	v_cvt_f32_f16_e32 v72, v63
	v_pk_add_f32 v[4:5], v[4:5], v[64:65]
	v_mov_b32_e32 v62, v71
	v_mov_b32_e32 v63, v73
	v_pk_add_f32 v[82:83], v[4:5], v[4:5] op_sel:[0,1] op_sel_hi:[1,0]
	v_mov_b32_e32 v4, v70
	v_mov_b32_e32 v5, v72
	v_pk_mul_f32 v[62:63], v[62:63], v[62:63]
	s_waitcnt vmcnt(56)
	v_cvt_f32_f16_sdwa v65, v59 dst_sel:DWORD dst_unused:UNUSED_PAD src0_sel:WORD_1
	v_pk_fma_f32 v[4:5], v[4:5], v[4:5], v[62:63]
	v_cvt_f32_f16_sdwa v63, v61 dst_sel:DWORD dst_unused:UNUSED_PAD src0_sel:WORD_1
	v_pk_add_f32 v[92:93], v[4:5], v[4:5] op_sel:[0,1] op_sel_hi:[1,0]
	v_cvt_f32_f16_sdwa v5, v60 dst_sel:DWORD dst_unused:UNUSED_PAD src0_sel:WORD_1
	v_cvt_f32_f16_e32 v4, v60
	v_cvt_f32_f16_e32 v62, v61
	v_cvt_f32_f16_e32 v64, v59
	v_mul_f32_e32 v60, v5, v5
	v_pk_fma_f32 v[94:95], v[4:5], v[4:5], v[60:61] op_sel_hi:[1,1,0]
	v_mul_f32_e32 v60, v63, v63
	v_pk_fma_f32 v[96:97], v[62:63], v[62:63], v[60:61] op_sel_hi:[1,1,0]
	v_cvt_f32_f16_sdwa v61, v58 dst_sel:DWORD dst_unused:UNUSED_PAD src0_sel:WORD_1
	v_cvt_f32_f16_e32 v60, v58
	v_pk_mul_f32 v[98:99], v[64:65], v[64:65]
	v_pk_mul_f32 v[58:59], v[60:61], v[60:61]
	s_nop 0
	v_mov_b32_e32 v83, v58
	v_mov_b32_e32 v93, v59
	v_mov_b32_e32 v95, v98
	v_mov_b32_e32 v97, v99
	v_pk_add_f32 v[58:59], v[82:83], v[92:93]
	v_pk_add_f32 v[82:83], v[94:95], v[96:97]
	s_nop 0
	v_pk_add_f32 v[58:59], v[58:59], v[82:83]
	s_nop 0
	v_add_f32_e32 v58, v58, v59
	s_nop 1
	v_add_f32_dpp v58, v58, v58 quad_perm:[1,0,3,2] row_mask:0xf bank_mask:0xf bound_ctrl:1
	s_nop 1
	v_add_f32_dpp v58, v58, v58 quad_perm:[2,3,0,1] row_mask:0xf bank_mask:0xf bound_ctrl:1
	s_nop 1
	v_add_f32_dpp v58, v58, v58 row_half_mirror row_mask:0xf bank_mask:0xf bound_ctrl:1
	s_nop 1
	v_add_f32_dpp v58, v58, v58 row_mirror row_mask:0xf bank_mask:0xf bound_ctrl:1
	s_nop 0
	v_readlane_b32 s5, v58, 16
	v_readlane_b32 s11, v58, 48
	v_readlane_b32 s6, v58, 0
	v_readlane_b32 s7, v58, 32
	v_mov_b32_e32 v58, s5
	v_mov_b32_e32 v59, s11
	v_pk_add_f32 v[58:59], s[6:7], v[58:59]
	s_lshl_b32 s5, s22, 1
	v_add_f32_e32 v58, v58, v59
	v_fmamk_f32 v58, v58, 0x3a000000, v252
	v_cmp_gt_f32_e32 vcc, s55, v58
	v_mul_f32_e32 v59, 0x4f800000, v58
	s_and_b32 s5, s5, 0xffffe000
	v_cndmask_b32_e32 v58, v58, v59, vcc
	v_sqrt_f32_e32 v59, v58
	s_add_i32 s5, s5, 0
	v_add_u32_e32 v82, -1, v59
	v_fma_f32 v83, -v82, v59, v58
	v_cmp_ge_f32_e64 s[6:7], 0, v83
	v_add_u32_e32 v83, 1, v59
	s_nop 0
	v_cndmask_b32_e64 v82, v59, v82, s[6:7]
	v_fma_f32 v59, -v83, v59, v58
	v_cmp_lt_f32_e64 s[6:7], 0, v59
	s_nop 1
	v_cndmask_b32_e64 v59, v82, v83, s[6:7]
	v_mul_f32_e32 v82, 0x37800000, v59
	v_cndmask_b32_e32 v59, v59, v82, vcc
	v_cmp_class_f32_e32 vcc, v58, v253
	s_nop 1
	v_cndmask_b32_e32 v58, v59, v58, vcc
	v_div_scale_f32 v59, s[6:7], v58, v58, 1.0
	v_rcp_f32_e32 v82, v59
	s_nop 0
	v_fma_f32 v83, -v59, v82, 1.0
	v_fmac_f32_e32 v82, v83, v82
	v_div_scale_f32 v83, vcc, 1.0, v58, 1.0
	v_mul_f32_e32 v92, v83, v82
	v_fma_f32 v93, -v59, v92, v83
	v_fmac_f32_e32 v92, v93, v82
	v_fma_f32 v59, -v59, v92, v83
	v_div_fmas_f32 v59, v59, v82, v92
	v_div_fixup_f32 v82, v59, v58, 1.0
	v_pk_mul_f32 v[96:97], v[88:89], v[82:83] op_sel_hi:[1,0]
	v_pk_mul_f32 v[98:99], v[90:91], v[82:83] op_sel_hi:[1,0]
	v_add_u32_e32 v83, s5, v0
	ds_read_b128 v[88:91], v83
	ds_read_b128 v[92:95], v83 offset:40960
	v_lshl_add_u64 v[58:59], s[24:25], 1, v[2:3]
	v_lshl_add_u64 v[58:59], v[58:59], 0, v[6:7]
	v_pk_mul_f32 v[4:5], v[4:5], v[82:83] op_sel_hi:[1,0]
	v_pk_mul_f32 v[62:63], v[62:63], v[82:83] op_sel_hi:[1,0]
	s_waitcnt lgkmcnt(0)
	v_pk_fma_f32 v[90:91], v[90:91], v[98:99], v[94:95]
	v_pk_fma_f32 v[88:89], v[88:89], v[96:97], v[92:93]
	v_pk_mul_f32 v[92:93], v[84:85], v[82:83] op_sel_hi:[1,0]
	v_cvt_pk_bf16_f32 v88, v88, v89
	v_cvt_pk_bf16_f32 v89, v90, v91
	global_store_dwordx2 v[58:59], v[88:89], off
	v_pk_mul_f32 v[94:95], v[86:87], v[82:83] op_sel_hi:[1,0]
	ds_read_b128 v[84:87], v83 offset:1024
	ds_read_b128 v[88:91], v83 offset:41984
	s_waitcnt lgkmcnt(0)
	v_pk_fma_f32 v[86:87], v[86:87], v[94:95], v[90:91]
	v_pk_fma_f32 v[84:85], v[84:85], v[92:93], v[88:89]
	v_pk_mul_f32 v[88:89], v[74:75], v[82:83] op_sel_hi:[1,0]
	v_cvt_pk_bf16_f32 v84, v84, v85
	v_cvt_pk_bf16_f32 v85, v86, v87
	global_store_dwordx2 v[58:59], v[84:85], off offset:512
	v_pk_mul_f32 v[90:91], v[76:77], v[82:83] op_sel_hi:[1,0]
	ds_read_b128 v[74:77], v83 offset:2048
	ds_read_b128 v[84:87], v83 offset:43008
	s_waitcnt lgkmcnt(0)
	v_pk_fma_f32 v[76:77], v[76:77], v[90:91], v[86:87]
	v_pk_fma_f32 v[74:75], v[74:75], v[88:89], v[84:85]
	v_pk_mul_f32 v[84:85], v[78:79], v[82:83] op_sel_hi:[1,0]
	v_cvt_pk_bf16_f32 v74, v74, v75
	v_cvt_pk_bf16_f32 v75, v76, v77
	global_store_dwordx2 v[58:59], v[74:75], off offset:1024
	v_pk_mul_f32 v[86:87], v[80:81], v[82:83] op_sel_hi:[1,0]
	ds_read_b128 v[74:77], v83 offset:3072
	ds_read_b128 v[78:81], v83 offset:44032
	s_waitcnt lgkmcnt(0)
	v_pk_fma_f32 v[76:77], v[86:87], v[76:77], v[80:81]
	v_pk_fma_f32 v[74:75], v[84:85], v[74:75], v[78:79]
	v_pk_mul_f32 v[78:79], v[66:67], v[82:83] op_sel_hi:[1,0]
	v_cvt_pk_bf16_f32 v74, v74, v75
	v_cvt_pk_bf16_f32 v75, v76, v77
	global_store_dwordx2 v[58:59], v[74:75], off offset:1536
	v_pk_mul_f32 v[80:81], v[68:69], v[82:83] op_sel_hi:[1,0]
	ds_read_b128 v[66:69], v83 offset:4096
	ds_read_b128 v[74:77], v83 offset:45056
	s_waitcnt lgkmcnt(0)
	v_pk_fma_f32 v[68:69], v[80:81], v[68:69], v[76:77]
	v_pk_fma_f32 v[66:67], v[78:79], v[66:67], v[74:75]
	v_pk_mul_f32 v[74:75], v[70:71], v[82:83] op_sel_hi:[1,0]
	v_cvt_pk_bf16_f32 v66, v66, v67
	v_cvt_pk_bf16_f32 v67, v68, v69
	global_store_dwordx2 v[58:59], v[66:67], off offset:2048
	v_pk_mul_f32 v[76:77], v[72:73], v[82:83] op_sel_hi:[1,0]
	ds_read_b128 v[66:69], v83 offset:5120
	ds_read_b128 v[70:73], v83 offset:46080
	s_waitcnt lgkmcnt(0)
	v_pk_fma_f32 v[68:69], v[76:77], v[68:69], v[72:73]
	v_pk_fma_f32 v[66:67], v[74:75], v[66:67], v[70:71]
	s_waitcnt vmcnt(60)
	v_cvt_f32_f16_sdwa v75, v57 dst_sel:DWORD dst_unused:UNUSED_PAD src0_sel:WORD_1
	v_cvt_pk_bf16_f32 v66, v66, v67
	v_cvt_pk_bf16_f32 v67, v68, v69
	global_store_dwordx2 v[58:59], v[66:67], off offset:2560
	ds_read_b128 v[66:69], v83 offset:6144
	ds_read_b128 v[70:73], v83 offset:47104
	v_cvt_f32_f16_e32 v74, v57
	s_waitcnt lgkmcnt(0)
	v_pk_fma_f32 v[62:63], v[62:63], v[68:69], v[72:73]
	v_pk_fma_f32 v[4:5], v[4:5], v[66:67], v[70:71]
	v_pk_mul_f32 v[68:69], v[64:65], v[82:83] op_sel_hi:[1,0]
	v_cvt_pk_bf16_f32 v4, v4, v5
	v_cvt_pk_bf16_f32 v5, v62, v63
	global_store_dwordx2 v[58:59], v[4:5], off offset:3072
	v_pk_mul_f32 v[4:5], v[60:61], v[82:83] op_sel_hi:[1,0]
	ds_read_b128 v[60:63], v83 offset:7168
	ds_read_b128 v[64:67], v83 offset:48128
	v_cvt_f32_f16_sdwa v73, v56 dst_sel:DWORD dst_unused:UNUSED_PAD src0_sel:WORD_1
	v_cvt_f32_f16_e32 v72, v56
	s_waitcnt vmcnt(61)
	v_cvt_f32_f16_sdwa v71, v55 dst_sel:DWORD dst_unused:UNUSED_PAD src0_sel:WORD_1
	v_cvt_f32_f16_e32 v70, v55
	s_waitcnt lgkmcnt(0)
	v_pk_fma_f32 v[62:63], v[68:69], v[62:63], v[66:67]
	v_cvt_f32_f16_sdwa v69, v54 dst_sel:DWORD dst_unused:UNUSED_PAD src0_sel:WORD_1
	v_cvt_f32_f16_e32 v68, v54
	v_pk_fma_f32 v[4:5], v[4:5], v[60:61], v[64:65]
	v_mov_b32_e32 v54, v73
	v_cvt_pk_bf16_f32 v4, v4, v5
	v_cvt_pk_bf16_f32 v5, v62, v63
	global_store_dwordx2 v[58:59], v[4:5], off offset:3584
	v_mov_b32_e32 v55, v69
	s_waitcnt vmcnt(61)
	v_cvt_f32_f16_sdwa v59, v52 dst_sel:DWORD dst_unused:UNUSED_PAD src0_sel:WORD_1
	v_cvt_f32_f16_sdwa v61, v53 dst_sel:DWORD dst_unused:UNUSED_PAD src0_sel:WORD_1
	v_mov_b32_e32 v4, v72
	v_mov_b32_e32 v5, v68
	v_pk_mul_f32 v[54:55], v[54:55], v[54:55]
	v_mov_b32_e32 v56, v75
	v_mov_b32_e32 v57, v71
	v_cvt_f32_f16_e32 v58, v52
	v_cvt_f32_f16_e32 v60, v53
	s_waitcnt vmcnt(60)
	v_cvt_f32_f16_sdwa v63, v50 dst_sel:DWORD dst_unused:UNUSED_PAD src0_sel:WORD_1
	v_pk_fma_f32 v[4:5], v[4:5], v[4:5], v[54:55]
	v_mov_b32_e32 v54, v74
	v_mov_b32_e32 v55, v70
	v_pk_mul_f32 v[56:57], v[56:57], v[56:57]
	v_cvt_f32_f16_e32 v62, v50
	v_cvt_f32_f16_sdwa v65, v51 dst_sel:DWORD dst_unused:UNUSED_PAD src0_sel:WORD_1
	v_pk_fma_f32 v[54:55], v[54:55], v[54:55], v[56:57]
	v_cvt_f32_f16_e32 v64, v51
	v_pk_add_f32 v[4:5], v[4:5], v[54:55]
	v_mov_b32_e32 v54, v59
	v_mov_b32_e32 v55, v61
	v_mov_b32_e32 v52, v58
	v_mov_b32_e32 v53, v60
	v_pk_mul_f32 v[54:55], v[54:55], v[54:55]
	v_mul_f32_e32 v50, v63, v63
	v_pk_fma_f32 v[52:53], v[52:53], v[52:53], v[54:55]
	v_pk_fma_f32 v[56:57], v[62:63], v[62:63], v[50:51] op_sel_hi:[1,1,0]
	v_mul_f32_e32 v50, v65, v65
	v_pk_add_f32 v[54:55], v[52:53], v[52:53] op_sel:[0,1] op_sel_hi:[1,0]
	v_pk_fma_f32 v[66:67], v[64:65], v[64:65], v[50:51] op_sel_hi:[1,1,0]
	s_waitcnt vmcnt(59)
	v_cvt_f32_f16_sdwa v51, v48 dst_sel:DWORD dst_unused:UNUSED_PAD src0_sel:WORD_1
	v_cvt_f32_f16_e32 v50, v48
	v_cvt_f32_f16_sdwa v53, v49 dst_sel:DWORD dst_unused:UNUSED_PAD src0_sel:WORD_1
	v_cvt_f32_f16_e32 v52, v49
	v_pk_add_f32 v[4:5], v[4:5], v[4:5] op_sel:[0,1] op_sel_hi:[1,0]
	v_pk_mul_f32 v[48:49], v[50:51], v[50:51]
	v_pk_mul_f32 v[76:77], v[52:53], v[52:53]
	v_mov_b32_e32 v5, v48
	v_mov_b32_e32 v55, v49
	v_mov_b32_e32 v57, v76
	v_mov_b32_e32 v67, v77
	v_pk_add_f32 v[4:5], v[4:5], v[54:55]
	v_pk_add_f32 v[48:49], v[56:57], v[66:67]
	s_waitcnt vmcnt(58)
	v_cvt_f32_f16_sdwa v55, v46 dst_sel:DWORD dst_unused:UNUSED_PAD src0_sel:WORD_1
	v_cvt_f32_f16_sdwa v57, v47 dst_sel:DWORD dst_unused:UNUSED_PAD src0_sel:WORD_1
	v_cvt_f32_f16_e32 v54, v46
	v_cvt_f32_f16_e32 v56, v47
	v_pk_add_f32 v[4:5], v[4:5], v[48:49]
	v_mov_b32_e32 v46, v55
	v_mov_b32_e32 v47, v57
	v_pk_add_f32 v[66:67], v[4:5], v[4:5] op_sel:[0,1] op_sel_hi:[1,0]
	v_mov_b32_e32 v4, v54
	v_mov_b32_e32 v5, v56
	v_pk_mul_f32 v[46:47], v[46:47], v[46:47]
	s_waitcnt vmcnt(56)
	v_cvt_f32_f16_sdwa v49, v43 dst_sel:DWORD dst_unused:UNUSED_PAD src0_sel:WORD_1
	v_pk_fma_f32 v[4:5], v[4:5], v[4:5], v[46:47]
	v_cvt_f32_f16_sdwa v47, v45 dst_sel:DWORD dst_unused:UNUSED_PAD src0_sel:WORD_1
	v_pk_add_f32 v[76:77], v[4:5], v[4:5] op_sel:[0,1] op_sel_hi:[1,0]
	v_cvt_f32_f16_sdwa v5, v44 dst_sel:DWORD dst_unused:UNUSED_PAD src0_sel:WORD_1
	v_cvt_f32_f16_e32 v4, v44
	v_cvt_f32_f16_e32 v46, v45
	v_cvt_f32_f16_e32 v48, v43
	v_mul_f32_e32 v44, v5, v5
	v_pk_fma_f32 v[78:79], v[4:5], v[4:5], v[44:45] op_sel_hi:[1,1,0]
	v_mul_f32_e32 v44, v47, v47
	v_pk_fma_f32 v[80:81], v[46:47], v[46:47], v[44:45] op_sel_hi:[1,1,0]
	v_cvt_f32_f16_sdwa v45, v42 dst_sel:DWORD dst_unused:UNUSED_PAD src0_sel:WORD_1
	v_cvt_f32_f16_e32 v44, v42
	v_pk_mul_f32 v[82:83], v[48:49], v[48:49]
	v_pk_mul_f32 v[42:43], v[44:45], v[44:45]
	s_nop 0
	v_mov_b32_e32 v67, v42
	v_mov_b32_e32 v77, v43
	v_mov_b32_e32 v79, v82
	v_mov_b32_e32 v81, v83
	v_pk_add_f32 v[42:43], v[66:67], v[76:77]
	v_pk_add_f32 v[66:67], v[78:79], v[80:81]
	s_nop 0
	v_pk_add_f32 v[42:43], v[42:43], v[66:67]
	s_nop 0
	v_add_f32_e32 v42, v42, v43
	s_nop 1
	v_add_f32_dpp v42, v42, v42 quad_perm:[1,0,3,2] row_mask:0xf bank_mask:0xf bound_ctrl:1
	s_nop 1
	v_add_f32_dpp v42, v42, v42 quad_perm:[2,3,0,1] row_mask:0xf bank_mask:0xf bound_ctrl:1
	s_nop 1
	v_add_f32_dpp v42, v42, v42 row_half_mirror row_mask:0xf bank_mask:0xf bound_ctrl:1
	s_nop 1
	v_add_f32_dpp v42, v42, v42 row_mirror row_mask:0xf bank_mask:0xf bound_ctrl:1
	s_nop 0
	v_readlane_b32 s5, v42, 16
	v_readlane_b32 s11, v42, 48
	v_readlane_b32 s6, v42, 0
	v_readlane_b32 s7, v42, 32
	v_mov_b32_e32 v42, s5
	v_mov_b32_e32 v43, s11
	v_pk_add_f32 v[42:43], s[6:7], v[42:43]
	s_lshl_b32 s5, s18, 1
	v_add_f32_e32 v42, v42, v43
	v_fmamk_f32 v42, v42, 0x3a000000, v252
	v_cmp_gt_f32_e32 vcc, s55, v42
	v_mul_f32_e32 v43, 0x4f800000, v42
	s_and_b32 s5, s5, 0xffffe000
	v_cndmask_b32_e32 v42, v42, v43, vcc
	v_sqrt_f32_e32 v43, v42
	s_add_i32 s5, s5, 0
	v_add_u32_e32 v66, -1, v43
	v_fma_f32 v67, -v66, v43, v42
	v_cmp_ge_f32_e64 s[6:7], 0, v67
	v_add_u32_e32 v67, 1, v43
	s_nop 0
	v_cndmask_b32_e64 v66, v43, v66, s[6:7]
	v_fma_f32 v43, -v67, v43, v42
	v_cmp_lt_f32_e64 s[6:7], 0, v43
	s_nop 1
	v_cndmask_b32_e64 v43, v66, v67, s[6:7]
	v_mul_f32_e32 v66, 0x37800000, v43
	v_cndmask_b32_e32 v43, v43, v66, vcc
	v_cmp_class_f32_e32 vcc, v42, v253
	s_nop 1
	v_cndmask_b32_e32 v42, v43, v42, vcc
	v_div_scale_f32 v43, s[6:7], v42, v42, 1.0
	v_rcp_f32_e32 v66, v43
	s_nop 0
	v_fma_f32 v67, -v43, v66, 1.0
	v_fmac_f32_e32 v66, v67, v66
	v_div_scale_f32 v67, vcc, 1.0, v42, 1.0
	v_mul_f32_e32 v76, v67, v66
	v_fma_f32 v77, -v43, v76, v67
	v_fmac_f32_e32 v76, v77, v66
	v_fma_f32 v43, -v43, v76, v67
	v_div_fmas_f32 v43, v43, v66, v76
	v_div_fixup_f32 v66, v43, v42, 1.0
	v_pk_mul_f32 v[80:81], v[72:73], v[66:67] op_sel_hi:[1,0]
	v_pk_mul_f32 v[82:83], v[74:75], v[66:67] op_sel_hi:[1,0]
	v_add_u32_e32 v67, s5, v0
	ds_read_b128 v[72:75], v67
	ds_read_b128 v[76:79], v67 offset:40960
	v_lshl_add_u64 v[42:43], s[20:21], 1, v[2:3]
	v_lshl_add_u64 v[42:43], v[42:43], 0, v[6:7]
	v_pk_mul_f32 v[4:5], v[4:5], v[66:67] op_sel_hi:[1,0]
	v_pk_mul_f32 v[46:47], v[46:47], v[66:67] op_sel_hi:[1,0]
	s_waitcnt lgkmcnt(0)
	v_pk_fma_f32 v[74:75], v[74:75], v[82:83], v[78:79]
	v_pk_fma_f32 v[72:73], v[72:73], v[80:81], v[76:77]
	v_pk_mul_f32 v[76:77], v[68:69], v[66:67] op_sel_hi:[1,0]
	v_cvt_pk_bf16_f32 v72, v72, v73
	v_cvt_pk_bf16_f32 v73, v74, v75
	global_store_dwordx2 v[42:43], v[72:73], off
	v_pk_mul_f32 v[78:79], v[70:71], v[66:67] op_sel_hi:[1,0]
	ds_read_b128 v[68:71], v67 offset:1024
	ds_read_b128 v[72:75], v67 offset:41984
	s_waitcnt lgkmcnt(0)
	v_pk_fma_f32 v[70:71], v[70:71], v[78:79], v[74:75]
	v_pk_fma_f32 v[68:69], v[68:69], v[76:77], v[72:73]
	v_pk_mul_f32 v[72:73], v[58:59], v[66:67] op_sel_hi:[1,0]
	v_cvt_pk_bf16_f32 v68, v68, v69
	v_cvt_pk_bf16_f32 v69, v70, v71
	global_store_dwordx2 v[42:43], v[68:69], off offset:512
	v_pk_mul_f32 v[74:75], v[60:61], v[66:67] op_sel_hi:[1,0]
	ds_read_b128 v[58:61], v67 offset:2048
	ds_read_b128 v[68:71], v67 offset:43008
	s_waitcnt lgkmcnt(0)
	v_pk_fma_f32 v[60:61], v[60:61], v[74:75], v[70:71]
	v_pk_fma_f32 v[58:59], v[58:59], v[72:73], v[68:69]
	v_pk_mul_f32 v[68:69], v[62:63], v[66:67] op_sel_hi:[1,0]
	v_cvt_pk_bf16_f32 v58, v58, v59
	v_cvt_pk_bf16_f32 v59, v60, v61
	global_store_dwordx2 v[42:43], v[58:59], off offset:1024
	v_pk_mul_f32 v[70:71], v[64:65], v[66:67] op_sel_hi:[1,0]
	ds_read_b128 v[58:61], v67 offset:3072
	ds_read_b128 v[62:65], v67 offset:44032
	s_waitcnt lgkmcnt(0)
	v_pk_fma_f32 v[60:61], v[70:71], v[60:61], v[64:65]
	v_pk_fma_f32 v[58:59], v[68:69], v[58:59], v[62:63]
	v_pk_mul_f32 v[62:63], v[50:51], v[66:67] op_sel_hi:[1,0]
	v_cvt_pk_bf16_f32 v58, v58, v59
	v_cvt_pk_bf16_f32 v59, v60, v61
	global_store_dwordx2 v[42:43], v[58:59], off offset:1536
	v_pk_mul_f32 v[64:65], v[52:53], v[66:67] op_sel_hi:[1,0]
	ds_read_b128 v[50:53], v67 offset:4096
	ds_read_b128 v[58:61], v67 offset:45056
	s_waitcnt lgkmcnt(0)
	v_pk_fma_f32 v[52:53], v[64:65], v[52:53], v[60:61]
	v_pk_fma_f32 v[50:51], v[62:63], v[50:51], v[58:59]
	v_pk_mul_f32 v[58:59], v[54:55], v[66:67] op_sel_hi:[1,0]
	v_cvt_pk_bf16_f32 v50, v50, v51
	v_cvt_pk_bf16_f32 v51, v52, v53
	global_store_dwordx2 v[42:43], v[50:51], off offset:2048
	v_pk_mul_f32 v[60:61], v[56:57], v[66:67] op_sel_hi:[1,0]
	ds_read_b128 v[50:53], v67 offset:5120
	ds_read_b128 v[54:57], v67 offset:46080
	s_waitcnt lgkmcnt(0)
	v_pk_fma_f32 v[52:53], v[60:61], v[52:53], v[56:57]
	v_pk_fma_f32 v[50:51], v[58:59], v[50:51], v[54:55]
	s_waitcnt vmcnt(60)
	v_cvt_f32_f16_sdwa v59, v41 dst_sel:DWORD dst_unused:UNUSED_PAD src0_sel:WORD_1
	v_cvt_pk_bf16_f32 v50, v50, v51
	v_cvt_pk_bf16_f32 v51, v52, v53
	global_store_dwordx2 v[42:43], v[50:51], off offset:2560
	ds_read_b128 v[50:53], v67 offset:6144
	ds_read_b128 v[54:57], v67 offset:47104
	v_cvt_f32_f16_e32 v58, v41
	s_waitcnt lgkmcnt(0)
	v_pk_fma_f32 v[46:47], v[46:47], v[52:53], v[56:57]
	v_pk_fma_f32 v[4:5], v[4:5], v[50:51], v[54:55]
	v_pk_mul_f32 v[52:53], v[48:49], v[66:67] op_sel_hi:[1,0]
	v_cvt_pk_bf16_f32 v4, v4, v5
	v_cvt_pk_bf16_f32 v5, v46, v47
	global_store_dwordx2 v[42:43], v[4:5], off offset:3072
	v_pk_mul_f32 v[4:5], v[44:45], v[66:67] op_sel_hi:[1,0]
	ds_read_b128 v[44:47], v67 offset:7168
	ds_read_b128 v[48:51], v67 offset:48128
	v_cvt_f32_f16_sdwa v57, v40 dst_sel:DWORD dst_unused:UNUSED_PAD src0_sel:WORD_1
	v_cvt_f32_f16_e32 v56, v40
	s_waitcnt vmcnt(61)
	v_cvt_f32_f16_sdwa v55, v39 dst_sel:DWORD dst_unused:UNUSED_PAD src0_sel:WORD_1
	v_cvt_f32_f16_e32 v54, v39
	s_waitcnt lgkmcnt(0)
	v_pk_fma_f32 v[46:47], v[52:53], v[46:47], v[50:51]
	v_cvt_f32_f16_sdwa v53, v38 dst_sel:DWORD dst_unused:UNUSED_PAD src0_sel:WORD_1
	v_cvt_f32_f16_e32 v52, v38
	v_pk_fma_f32 v[4:5], v[4:5], v[44:45], v[48:49]
	v_mov_b32_e32 v38, v57
	v_cvt_pk_bf16_f32 v4, v4, v5
	v_cvt_pk_bf16_f32 v5, v46, v47
	global_store_dwordx2 v[42:43], v[4:5], off offset:3584
	v_mov_b32_e32 v39, v53
	s_waitcnt vmcnt(61)
	v_cvt_f32_f16_sdwa v43, v36 dst_sel:DWORD dst_unused:UNUSED_PAD src0_sel:WORD_1
	v_cvt_f32_f16_sdwa v45, v37 dst_sel:DWORD dst_unused:UNUSED_PAD src0_sel:WORD_1
	v_mov_b32_e32 v4, v56
	v_mov_b32_e32 v5, v52
	v_pk_mul_f32 v[38:39], v[38:39], v[38:39]
	v_mov_b32_e32 v40, v59
	v_mov_b32_e32 v41, v55
	v_cvt_f32_f16_e32 v42, v36
	v_cvt_f32_f16_e32 v44, v37
	s_waitcnt vmcnt(60)
	v_cvt_f32_f16_sdwa v47, v34 dst_sel:DWORD dst_unused:UNUSED_PAD src0_sel:WORD_1
	v_pk_fma_f32 v[4:5], v[4:5], v[4:5], v[38:39]
	v_mov_b32_e32 v38, v58
	v_mov_b32_e32 v39, v54
	v_pk_mul_f32 v[40:41], v[40:41], v[40:41]
	v_cvt_f32_f16_e32 v46, v34
	v_cvt_f32_f16_sdwa v49, v35 dst_sel:DWORD dst_unused:UNUSED_PAD src0_sel:WORD_1
	v_pk_fma_f32 v[38:39], v[38:39], v[38:39], v[40:41]
	v_cvt_f32_f16_e32 v48, v35
	v_pk_add_f32 v[4:5], v[4:5], v[38:39]
	v_mov_b32_e32 v38, v43
	v_mov_b32_e32 v39, v45
	v_mov_b32_e32 v36, v42
	v_mov_b32_e32 v37, v44
	v_pk_mul_f32 v[38:39], v[38:39], v[38:39]
	v_mul_f32_e32 v34, v47, v47
	v_pk_fma_f32 v[36:37], v[36:37], v[36:37], v[38:39]
	v_pk_fma_f32 v[40:41], v[46:47], v[46:47], v[34:35] op_sel_hi:[1,1,0]
	v_mul_f32_e32 v34, v49, v49
	v_pk_add_f32 v[38:39], v[36:37], v[36:37] op_sel:[0,1] op_sel_hi:[1,0]
	v_pk_fma_f32 v[50:51], v[48:49], v[48:49], v[34:35] op_sel_hi:[1,1,0]
	s_waitcnt vmcnt(59)
	v_cvt_f32_f16_sdwa v35, v32 dst_sel:DWORD dst_unused:UNUSED_PAD src0_sel:WORD_1
	v_cvt_f32_f16_e32 v34, v32
	v_cvt_f32_f16_sdwa v37, v33 dst_sel:DWORD dst_unused:UNUSED_PAD src0_sel:WORD_1
	v_cvt_f32_f16_e32 v36, v33
	v_pk_add_f32 v[4:5], v[4:5], v[4:5] op_sel:[0,1] op_sel_hi:[1,0]
	v_pk_mul_f32 v[32:33], v[34:35], v[34:35]
	v_pk_mul_f32 v[60:61], v[36:37], v[36:37]
	v_mov_b32_e32 v5, v32
	v_mov_b32_e32 v39, v33
	v_mov_b32_e32 v41, v60
	v_mov_b32_e32 v51, v61
	v_pk_add_f32 v[4:5], v[4:5], v[38:39]
	v_pk_add_f32 v[32:33], v[40:41], v[50:51]
	s_waitcnt vmcnt(58)
	v_cvt_f32_f16_sdwa v39, v30 dst_sel:DWORD dst_unused:UNUSED_PAD src0_sel:WORD_1
	v_cvt_f32_f16_sdwa v41, v31 dst_sel:DWORD dst_unused:UNUSED_PAD src0_sel:WORD_1
	v_cvt_f32_f16_e32 v38, v30
	v_cvt_f32_f16_e32 v40, v31
	v_pk_add_f32 v[4:5], v[4:5], v[32:33]
	v_mov_b32_e32 v30, v39
	v_mov_b32_e32 v31, v41
	v_pk_add_f32 v[50:51], v[4:5], v[4:5] op_sel:[0,1] op_sel_hi:[1,0]
	v_mov_b32_e32 v4, v38
	v_mov_b32_e32 v5, v40
	v_pk_mul_f32 v[30:31], v[30:31], v[30:31]
	s_waitcnt vmcnt(56)
	v_cvt_f32_f16_sdwa v33, v27 dst_sel:DWORD dst_unused:UNUSED_PAD src0_sel:WORD_1
	v_pk_fma_f32 v[4:5], v[4:5], v[4:5], v[30:31]
	v_cvt_f32_f16_sdwa v31, v29 dst_sel:DWORD dst_unused:UNUSED_PAD src0_sel:WORD_1
	v_pk_add_f32 v[60:61], v[4:5], v[4:5] op_sel:[0,1] op_sel_hi:[1,0]
	v_cvt_f32_f16_sdwa v5, v28 dst_sel:DWORD dst_unused:UNUSED_PAD src0_sel:WORD_1
	v_cvt_f32_f16_e32 v4, v28
	v_cvt_f32_f16_e32 v30, v29
	v_cvt_f32_f16_e32 v32, v27
	v_mul_f32_e32 v28, v5, v5
	v_pk_fma_f32 v[62:63], v[4:5], v[4:5], v[28:29] op_sel_hi:[1,1,0]
	v_mul_f32_e32 v28, v31, v31
	v_pk_fma_f32 v[64:65], v[30:31], v[30:31], v[28:29] op_sel_hi:[1,1,0]
	v_cvt_f32_f16_sdwa v29, v26 dst_sel:DWORD dst_unused:UNUSED_PAD src0_sel:WORD_1
	v_cvt_f32_f16_e32 v28, v26
	v_pk_mul_f32 v[66:67], v[32:33], v[32:33]
	v_pk_mul_f32 v[26:27], v[28:29], v[28:29]
	s_nop 0
	v_mov_b32_e32 v51, v26
	v_mov_b32_e32 v61, v27
	v_mov_b32_e32 v63, v66
	v_mov_b32_e32 v65, v67
	v_pk_add_f32 v[26:27], v[50:51], v[60:61]
	v_pk_add_f32 v[50:51], v[62:63], v[64:65]
	s_nop 0
	v_pk_add_f32 v[26:27], v[26:27], v[50:51]
	s_nop 0
	v_add_f32_e32 v26, v26, v27
	s_nop 1
	v_add_f32_dpp v26, v26, v26 quad_perm:[1,0,3,2] row_mask:0xf bank_mask:0xf bound_ctrl:1
	s_nop 1
	v_add_f32_dpp v26, v26, v26 quad_perm:[2,3,0,1] row_mask:0xf bank_mask:0xf bound_ctrl:1
	s_nop 1
	v_add_f32_dpp v26, v26, v26 row_half_mirror row_mask:0xf bank_mask:0xf bound_ctrl:1
	s_nop 1
	v_add_f32_dpp v26, v26, v26 row_mirror row_mask:0xf bank_mask:0xf bound_ctrl:1
	s_nop 0
	v_readlane_b32 s5, v26, 16
	v_readlane_b32 s11, v26, 48
	v_readlane_b32 s6, v26, 0
	v_readlane_b32 s7, v26, 32
	v_mov_b32_e32 v26, s5
	v_mov_b32_e32 v27, s11
	v_pk_add_f32 v[26:27], s[6:7], v[26:27]
	s_lshl_b32 s5, s14, 1
	v_add_f32_e32 v26, v26, v27
	v_fmamk_f32 v26, v26, 0x3a000000, v252
	v_cmp_gt_f32_e32 vcc, s55, v26
	v_mul_f32_e32 v27, 0x4f800000, v26
	s_and_b32 s5, s5, 0xffffe000
	v_cndmask_b32_e32 v26, v26, v27, vcc
	v_sqrt_f32_e32 v27, v26
	s_add_i32 s5, s5, 0
	v_add_u32_e32 v50, -1, v27
	v_fma_f32 v51, -v50, v27, v26
	v_cmp_ge_f32_e64 s[6:7], 0, v51
	v_add_u32_e32 v51, 1, v27
	s_nop 0
	v_cndmask_b32_e64 v50, v27, v50, s[6:7]
	v_fma_f32 v27, -v51, v27, v26
	v_cmp_lt_f32_e64 s[6:7], 0, v27
	s_nop 1
	v_cndmask_b32_e64 v27, v50, v51, s[6:7]
	v_mul_f32_e32 v50, 0x37800000, v27
	v_cndmask_b32_e32 v27, v27, v50, vcc
	v_cmp_class_f32_e32 vcc, v26, v253
	s_nop 1
	v_cndmask_b32_e32 v26, v27, v26, vcc
	v_div_scale_f32 v27, s[6:7], v26, v26, 1.0
	v_rcp_f32_e32 v50, v27
	s_nop 0
	v_fma_f32 v51, -v27, v50, 1.0
	v_fmac_f32_e32 v50, v51, v50
	v_div_scale_f32 v51, vcc, 1.0, v26, 1.0
	v_mul_f32_e32 v60, v51, v50
	v_fma_f32 v61, -v27, v60, v51
	v_fmac_f32_e32 v60, v61, v50
	v_fma_f32 v27, -v27, v60, v51
	v_div_fmas_f32 v27, v27, v50, v60
	v_div_fixup_f32 v50, v27, v26, 1.0
	v_pk_mul_f32 v[64:65], v[56:57], v[50:51] op_sel_hi:[1,0]
	v_pk_mul_f32 v[66:67], v[58:59], v[50:51] op_sel_hi:[1,0]
	v_add_u32_e32 v51, s5, v0
	ds_read_b128 v[56:59], v51
	ds_read_b128 v[60:63], v51 offset:40960
	v_lshl_add_u64 v[26:27], s[16:17], 1, v[2:3]
	v_lshl_add_u64 v[26:27], v[26:27], 0, v[6:7]
	v_pk_mul_f32 v[4:5], v[4:5], v[50:51] op_sel_hi:[1,0]
	v_pk_mul_f32 v[30:31], v[30:31], v[50:51] op_sel_hi:[1,0]
	s_waitcnt lgkmcnt(0)
	v_pk_fma_f32 v[58:59], v[58:59], v[66:67], v[62:63]
	v_pk_fma_f32 v[56:57], v[56:57], v[64:65], v[60:61]
	v_pk_mul_f32 v[60:61], v[52:53], v[50:51] op_sel_hi:[1,0]
	v_cvt_pk_bf16_f32 v56, v56, v57
	v_cvt_pk_bf16_f32 v57, v58, v59
	global_store_dwordx2 v[26:27], v[56:57], off
	v_pk_mul_f32 v[62:63], v[54:55], v[50:51] op_sel_hi:[1,0]
	ds_read_b128 v[52:55], v51 offset:1024
	ds_read_b128 v[56:59], v51 offset:41984
	s_waitcnt lgkmcnt(0)
	v_pk_fma_f32 v[54:55], v[54:55], v[62:63], v[58:59]
	v_pk_fma_f32 v[52:53], v[52:53], v[60:61], v[56:57]
	v_pk_mul_f32 v[56:57], v[42:43], v[50:51] op_sel_hi:[1,0]
	v_cvt_pk_bf16_f32 v52, v52, v53
	v_cvt_pk_bf16_f32 v53, v54, v55
	global_store_dwordx2 v[26:27], v[52:53], off offset:512
	v_pk_mul_f32 v[58:59], v[44:45], v[50:51] op_sel_hi:[1,0]
	ds_read_b128 v[42:45], v51 offset:2048
	ds_read_b128 v[52:55], v51 offset:43008
	s_waitcnt lgkmcnt(0)
	v_pk_fma_f32 v[44:45], v[44:45], v[58:59], v[54:55]
	v_pk_fma_f32 v[42:43], v[42:43], v[56:57], v[52:53]
	v_pk_mul_f32 v[52:53], v[46:47], v[50:51] op_sel_hi:[1,0]
	v_cvt_pk_bf16_f32 v42, v42, v43
	v_cvt_pk_bf16_f32 v43, v44, v45
	global_store_dwordx2 v[26:27], v[42:43], off offset:1024
	v_pk_mul_f32 v[54:55], v[48:49], v[50:51] op_sel_hi:[1,0]
	ds_read_b128 v[42:45], v51 offset:3072
	ds_read_b128 v[46:49], v51 offset:44032
	s_waitcnt lgkmcnt(0)
	v_pk_fma_f32 v[44:45], v[54:55], v[44:45], v[48:49]
	v_pk_fma_f32 v[42:43], v[52:53], v[42:43], v[46:47]
	v_pk_mul_f32 v[46:47], v[34:35], v[50:51] op_sel_hi:[1,0]
	v_cvt_pk_bf16_f32 v42, v42, v43
	v_cvt_pk_bf16_f32 v43, v44, v45
	global_store_dwordx2 v[26:27], v[42:43], off offset:1536
	v_pk_mul_f32 v[48:49], v[36:37], v[50:51] op_sel_hi:[1,0]
	ds_read_b128 v[34:37], v51 offset:4096
	ds_read_b128 v[42:45], v51 offset:45056
	s_waitcnt lgkmcnt(0)
	v_pk_fma_f32 v[36:37], v[48:49], v[36:37], v[44:45]
	v_pk_fma_f32 v[34:35], v[46:47], v[34:35], v[42:43]
	v_pk_mul_f32 v[42:43], v[38:39], v[50:51] op_sel_hi:[1,0]
	v_cvt_pk_bf16_f32 v34, v34, v35
	v_cvt_pk_bf16_f32 v35, v36, v37
	global_store_dwordx2 v[26:27], v[34:35], off offset:2048
	v_pk_mul_f32 v[44:45], v[40:41], v[50:51] op_sel_hi:[1,0]
	ds_read_b128 v[34:37], v51 offset:5120
	ds_read_b128 v[38:41], v51 offset:46080
	s_waitcnt lgkmcnt(0)
	v_pk_fma_f32 v[36:37], v[44:45], v[36:37], v[40:41]
	v_pk_fma_f32 v[34:35], v[42:43], v[34:35], v[38:39]
	s_waitcnt vmcnt(60)
; __device__ __forceinline__ void norm_mod_phase2(const Args& a, Frame& F, const float* gain, const float* modl, int sh_off, int sc_off, int nrows, const float* slab_gate) {
;     ...
;     if (ML + nw < nrows) {
	v_cvt_f32_f16_sdwa v43, v25 dst_sel:DWORD dst_unused:UNUSED_PAD src0_sel:WORD_1
	v_cvt_pk_bf16_f32 v34, v34, v35
	v_cvt_pk_bf16_f32 v35, v36, v37
	global_store_dwordx2 v[26:27], v[34:35], off offset:2560
	ds_read_b128 v[34:37], v51 offset:6144
	ds_read_b128 v[38:41], v51 offset:47104
	v_cvt_f32_f16_e32 v42, v25
	s_waitcnt lgkmcnt(0)
	v_pk_fma_f32 v[30:31], v[30:31], v[36:37], v[40:41]
	v_pk_fma_f32 v[4:5], v[4:5], v[34:35], v[38:39]
	v_pk_mul_f32 v[36:37], v[32:33], v[50:51] op_sel_hi:[1,0]
	v_cvt_pk_bf16_f32 v4, v4, v5
	v_cvt_pk_bf16_f32 v5, v30, v31
	global_store_dwordx2 v[26:27], v[4:5], off offset:3072
	v_pk_mul_f32 v[4:5], v[28:29], v[50:51] op_sel_hi:[1,0]
	ds_read_b128 v[28:31], v51 offset:7168
	ds_read_b128 v[32:35], v51 offset:48128
	v_cvt_f32_f16_sdwa v41, v24 dst_sel:DWORD dst_unused:UNUSED_PAD src0_sel:WORD_1
	v_cvt_f32_f16_e32 v40, v24
	s_waitcnt vmcnt(61)
	v_cvt_f32_f16_sdwa v39, v23 dst_sel:DWORD dst_unused:UNUSED_PAD src0_sel:WORD_1
	v_cvt_f32_f16_e32 v38, v23
	s_waitcnt lgkmcnt(0)
	v_pk_fma_f32 v[30:31], v[36:37], v[30:31], v[34:35]
	v_cvt_f32_f16_sdwa v37, v22 dst_sel:DWORD dst_unused:UNUSED_PAD src0_sel:WORD_1
	v_cvt_f32_f16_e32 v36, v22
	v_pk_fma_f32 v[4:5], v[4:5], v[28:29], v[32:33]
	v_mov_b32_e32 v22, v41
	v_cvt_pk_bf16_f32 v4, v4, v5
	v_cvt_pk_bf16_f32 v5, v30, v31
	global_store_dwordx2 v[26:27], v[4:5], off offset:3584
	v_mov_b32_e32 v23, v37
	s_waitcnt vmcnt(61)
	v_cvt_f32_f16_sdwa v27, v20 dst_sel:DWORD dst_unused:UNUSED_PAD src0_sel:WORD_1
	v_cvt_f32_f16_sdwa v29, v21 dst_sel:DWORD dst_unused:UNUSED_PAD src0_sel:WORD_1
	v_mov_b32_e32 v4, v40
	v_mov_b32_e32 v5, v36
	v_pk_mul_f32 v[22:23], v[22:23], v[22:23]
	v_mov_b32_e32 v24, v43
	v_mov_b32_e32 v25, v39
	v_cvt_f32_f16_e32 v26, v20
	v_cvt_f32_f16_e32 v28, v21
	s_waitcnt vmcnt(60)
	v_cvt_f32_f16_sdwa v31, v18 dst_sel:DWORD dst_unused:UNUSED_PAD src0_sel:WORD_1
	v_pk_fma_f32 v[4:5], v[4:5], v[4:5], v[22:23]
	v_mov_b32_e32 v22, v42
	v_mov_b32_e32 v23, v38
	v_pk_mul_f32 v[24:25], v[24:25], v[24:25]
	v_cvt_f32_f16_e32 v30, v18
	v_cvt_f32_f16_sdwa v33, v19 dst_sel:DWORD dst_unused:UNUSED_PAD src0_sel:WORD_1
	v_pk_fma_f32 v[22:23], v[22:23], v[22:23], v[24:25]
	v_cvt_f32_f16_e32 v32, v19
	v_pk_add_f32 v[4:5], v[4:5], v[22:23]
	v_mov_b32_e32 v22, v27
	v_mov_b32_e32 v23, v29
	v_mov_b32_e32 v20, v26
	v_mov_b32_e32 v21, v28
	v_pk_mul_f32 v[22:23], v[22:23], v[22:23]
	v_mul_f32_e32 v18, v31, v31
	v_pk_fma_f32 v[20:21], v[20:21], v[20:21], v[22:23]
	v_pk_fma_f32 v[24:25], v[30:31], v[30:31], v[18:19] op_sel_hi:[1,1,0]
	v_mul_f32_e32 v18, v33, v33
	v_pk_add_f32 v[22:23], v[20:21], v[20:21] op_sel:[0,1] op_sel_hi:[1,0]
	v_pk_fma_f32 v[34:35], v[32:33], v[32:33], v[18:19] op_sel_hi:[1,1,0]
	s_waitcnt vmcnt(59)
	v_cvt_f32_f16_sdwa v19, v16 dst_sel:DWORD dst_unused:UNUSED_PAD src0_sel:WORD_1
	v_cvt_f32_f16_e32 v18, v16
	v_cvt_f32_f16_sdwa v21, v17 dst_sel:DWORD dst_unused:UNUSED_PAD src0_sel:WORD_1
	v_cvt_f32_f16_e32 v20, v17
	v_pk_add_f32 v[4:5], v[4:5], v[4:5] op_sel:[0,1] op_sel_hi:[1,0]
	v_pk_mul_f32 v[16:17], v[18:19], v[18:19]
	v_pk_mul_f32 v[44:45], v[20:21], v[20:21]
	v_mov_b32_e32 v5, v16
	v_mov_b32_e32 v23, v17
	v_mov_b32_e32 v25, v44
	v_mov_b32_e32 v35, v45
	v_pk_add_f32 v[4:5], v[4:5], v[22:23]
	v_pk_add_f32 v[16:17], v[24:25], v[34:35]
	s_waitcnt vmcnt(58)
	v_cvt_f32_f16_sdwa v23, v14 dst_sel:DWORD dst_unused:UNUSED_PAD src0_sel:WORD_1
	v_cvt_f32_f16_sdwa v25, v15 dst_sel:DWORD dst_unused:UNUSED_PAD src0_sel:WORD_1
	v_cvt_f32_f16_e32 v22, v14
	v_cvt_f32_f16_e32 v24, v15
	v_pk_add_f32 v[4:5], v[4:5], v[16:17]
	v_mov_b32_e32 v14, v23
	v_mov_b32_e32 v15, v25
	v_pk_add_f32 v[34:35], v[4:5], v[4:5] op_sel:[0,1] op_sel_hi:[1,0]
	v_mov_b32_e32 v4, v22
	v_mov_b32_e32 v5, v24
	v_pk_mul_f32 v[14:15], v[14:15], v[14:15]
	s_waitcnt vmcnt(56)
	v_cvt_f32_f16_sdwa v17, v11 dst_sel:DWORD dst_unused:UNUSED_PAD src0_sel:WORD_1
	v_pk_fma_f32 v[4:5], v[4:5], v[4:5], v[14:15]
	v_cvt_f32_f16_sdwa v15, v13 dst_sel:DWORD dst_unused:UNUSED_PAD src0_sel:WORD_1
	v_pk_add_f32 v[44:45], v[4:5], v[4:5] op_sel:[0,1] op_sel_hi:[1,0]
	v_cvt_f32_f16_sdwa v5, v12 dst_sel:DWORD dst_unused:UNUSED_PAD src0_sel:WORD_1
	v_cvt_f32_f16_e32 v4, v12
	v_cvt_f32_f16_e32 v14, v13
	v_cvt_f32_f16_e32 v16, v11
	v_mul_f32_e32 v12, v5, v5
	v_pk_fma_f32 v[46:47], v[4:5], v[4:5], v[12:13] op_sel_hi:[1,1,0]
	v_mul_f32_e32 v12, v15, v15
	v_pk_fma_f32 v[48:49], v[14:15], v[14:15], v[12:13] op_sel_hi:[1,1,0]
	v_cvt_f32_f16_sdwa v13, v10 dst_sel:DWORD dst_unused:UNUSED_PAD src0_sel:WORD_1
	v_cvt_f32_f16_e32 v12, v10
	v_pk_mul_f32 v[50:51], v[16:17], v[16:17]
	v_pk_mul_f32 v[10:11], v[12:13], v[12:13]
	s_nop 0
	v_mov_b32_e32 v35, v10
	v_mov_b32_e32 v45, v11
	v_mov_b32_e32 v47, v50
	v_mov_b32_e32 v49, v51
	v_pk_add_f32 v[10:11], v[34:35], v[44:45]
	v_pk_add_f32 v[34:35], v[46:47], v[48:49]
	s_nop 0
	v_pk_add_f32 v[10:11], v[10:11], v[34:35]
	s_nop 0
	v_add_f32_e32 v10, v10, v11
	s_nop 1
	v_add_f32_dpp v10, v10, v10 quad_perm:[1,0,3,2] row_mask:0xf bank_mask:0xf bound_ctrl:1
	s_nop 1
	v_add_f32_dpp v10, v10, v10 quad_perm:[2,3,0,1] row_mask:0xf bank_mask:0xf bound_ctrl:1
	s_nop 1
	v_add_f32_dpp v10, v10, v10 row_half_mirror row_mask:0xf bank_mask:0xf bound_ctrl:1
	s_nop 1
	v_add_f32_dpp v10, v10, v10 row_mirror row_mask:0xf bank_mask:0xf bound_ctrl:1
	s_nop 0
	v_readlane_b32 s5, v10, 16
	v_readlane_b32 s11, v10, 48
	v_readlane_b32 s6, v10, 0
	v_readlane_b32 s7, v10, 32
	v_mov_b32_e32 v10, s5
	v_mov_b32_e32 v11, s11
	v_pk_add_f32 v[10:11], s[6:7], v[10:11]
	s_lshl_b32 s5, s10, 1
	v_add_f32_e32 v10, v10, v11
	v_fmamk_f32 v10, v10, 0x3a000000, v252
	v_cmp_gt_f32_e32 vcc, s55, v10
	v_mul_f32_e32 v11, 0x4f800000, v10
	s_and_b32 s5, s5, 0xffffe000
	v_cndmask_b32_e32 v10, v10, v11, vcc
	v_sqrt_f32_e32 v11, v10
	s_add_i32 s5, s5, 0
	s_cmpk_lt_i32 s4, 0x400
	v_add_u32_e32 v34, -1, v11
	v_fma_f32 v35, -v34, v11, v10
	v_cmp_ge_f32_e64 s[6:7], 0, v35
	v_add_u32_e32 v35, 1, v11
	s_nop 0
	v_cndmask_b32_e64 v34, v11, v34, s[6:7]
	v_fma_f32 v11, -v35, v11, v10
	v_cmp_lt_f32_e64 s[6:7], 0, v11
	s_nop 1
	v_cndmask_b32_e64 v11, v34, v35, s[6:7]
	v_mul_f32_e32 v34, 0x37800000, v11
	v_cndmask_b32_e32 v11, v11, v34, vcc
	v_cmp_class_f32_e32 vcc, v10, v253
	s_nop 1
	v_cndmask_b32_e32 v10, v11, v10, vcc
	v_div_scale_f32 v11, s[6:7], v10, v10, 1.0
	v_rcp_f32_e32 v34, v11
	s_nop 0
	v_fma_f32 v35, -v11, v34, 1.0
	v_fmac_f32_e32 v34, v35, v34
	v_div_scale_f32 v35, vcc, 1.0, v10, 1.0
	v_mul_f32_e32 v44, v35, v34
	v_fma_f32 v45, -v11, v44, v35
	v_fmac_f32_e32 v44, v45, v34
	v_fma_f32 v11, -v11, v44, v35
	v_div_fmas_f32 v11, v11, v34, v44
	v_div_fixup_f32 v34, v11, v10, 1.0
	v_pk_mul_f32 v[48:49], v[40:41], v[34:35] op_sel_hi:[1,0]
	v_pk_mul_f32 v[50:51], v[42:43], v[34:35] op_sel_hi:[1,0]
	v_add_u32_e32 v35, s5, v0
	ds_read_b128 v[40:43], v35
	ds_read_b128 v[44:47], v35 offset:40960
	v_lshl_add_u64 v[10:11], s[12:13], 1, v[2:3]
	v_lshl_add_u64 v[10:11], v[10:11], 0, v[6:7]
	v_pk_mul_f32 v[4:5], v[4:5], v[34:35] op_sel_hi:[1,0]
	v_pk_mul_f32 v[14:15], v[14:15], v[34:35] op_sel_hi:[1,0]
	s_waitcnt lgkmcnt(0)
; #define GAS __attribute__((address_space(1)))
; __device__ __forceinline__ unsigned xpk2(float lo, float hi) { if (XRES_F16) { const f32x2_t v = {lo, hi}; const f16x2_t h = __builtin_convertvector(v, f16x2_t); return __builtin_bit_cast(unsigned, h); } return pk2(lo, hi); }
; __device__ __forceinline__ float xlo(unsigned w) { if (XRES_F16) { const f16x2_t h = __builtin_bit_cast(f16x2_t, w); return (float)h[0]; } return __builtin_bit_cast(float, w << 16); }
; __device__ __forceinline__ float xhi(unsigned w) { if (XRES_F16) { const f16x2_t h = __builtin_bit_cast(f16x2_t, w); return (float)h[1]; } return __builtin_bit_cast(float, w & 0xffff0000u); }
; __device__ __forceinline__ void norm_mod_phase2(const Args& a, Frame& F, const float* gain, const float* modl, int sh_off, int sc_off, int nrows, const float* slab_gate) {
;     ...
;     if (ML + nw < nrows) {
;         const int r = ML + nw, rc = nw;
;         const GAS v2u* xr = (const GAS v2u*)(X + (size_t)r * D) + F.lane;
; #pragma unroll
;         for (int j = 0; j < 8; ++j) r0[j] = xr[64 * j];
;         if (slab_gate != nullptr) { const GAS f32x4* sl = (const GAS f32x4*)((const float*)(a.ws + WS_SLAB) + (size_t)rc * D) + F.lane;
; #pragma unroll
;             for (int j = 0; j < 8; ++j) { const f32x4 p = (sl[64 * j] + sl[64 * j + (size_t)MC * D / 4]) + (sl[64 * j + 2 * ((size_t)MC * D / 4)] + sl[64 * j + 3 * ((size_t)MC * D / 4)]);
;                 const f32x4 x = (f32x4){xlo(r0[j].x), xhi(r0[j].x), xlo(r0[j].y), xhi(r0[j].y)} + *(const GAS f32x4*)(slab_gate + 256 * j + 4 * F.lane) * p;
;                 v2u w; w.x = xpk2(x[0], x[1]); w.y = xpk2(x[2], x[3]); ((GAS v2u*)(X + (size_t)r * D) + F.lane)[64 * j] = w; r0[j] = w; } }
	v_pk_fma_f32 v[42:43], v[42:43], v[50:51], v[46:47]
	v_pk_fma_f32 v[40:41], v[40:41], v[48:49], v[44:45]
	v_pk_mul_f32 v[44:45], v[36:37], v[34:35] op_sel_hi:[1,0]
	v_cvt_pk_bf16_f32 v40, v40, v41
	v_cvt_pk_bf16_f32 v41, v42, v43
	global_store_dwordx2 v[10:11], v[40:41], off
	v_pk_mul_f32 v[46:47], v[38:39], v[34:35] op_sel_hi:[1,0]
	ds_read_b128 v[36:39], v35 offset:1024
	ds_read_b128 v[40:43], v35 offset:41984
	s_waitcnt lgkmcnt(0)
	v_pk_fma_f32 v[38:39], v[38:39], v[46:47], v[42:43]
	v_pk_fma_f32 v[36:37], v[36:37], v[44:45], v[40:41]
	v_pk_mul_f32 v[40:41], v[26:27], v[34:35] op_sel_hi:[1,0]
	v_cvt_pk_bf16_f32 v36, v36, v37
	v_cvt_pk_bf16_f32 v37, v38, v39
	global_store_dwordx2 v[10:11], v[36:37], off offset:512
	v_pk_mul_f32 v[42:43], v[28:29], v[34:35] op_sel_hi:[1,0]
	ds_read_b128 v[26:29], v35 offset:2048
	ds_read_b128 v[36:39], v35 offset:43008
	s_waitcnt lgkmcnt(0)
	v_pk_fma_f32 v[28:29], v[28:29], v[42:43], v[38:39]
	v_pk_fma_f32 v[26:27], v[26:27], v[40:41], v[36:37]
	v_pk_mul_f32 v[36:37], v[30:31], v[34:35] op_sel_hi:[1,0]
	v_cvt_pk_bf16_f32 v26, v26, v27
	v_cvt_pk_bf16_f32 v27, v28, v29
	global_store_dwordx2 v[10:11], v[26:27], off offset:1024
	v_pk_mul_f32 v[38:39], v[32:33], v[34:35] op_sel_hi:[1,0]
	ds_read_b128 v[26:29], v35 offset:3072
	ds_read_b128 v[30:33], v35 offset:44032
	s_waitcnt lgkmcnt(0)
	v_pk_fma_f32 v[28:29], v[38:39], v[28:29], v[32:33]
	v_pk_fma_f32 v[26:27], v[36:37], v[26:27], v[30:31]
	v_pk_mul_f32 v[30:31], v[18:19], v[34:35] op_sel_hi:[1,0]
	v_cvt_pk_bf16_f32 v26, v26, v27
	v_cvt_pk_bf16_f32 v27, v28, v29
	global_store_dwordx2 v[10:11], v[26:27], off offset:1536
	v_pk_mul_f32 v[32:33], v[20:21], v[34:35] op_sel_hi:[1,0]
	ds_read_b128 v[18:21], v35 offset:4096
	ds_read_b128 v[26:29], v35 offset:45056
	s_waitcnt lgkmcnt(0)
	v_pk_fma_f32 v[20:21], v[32:33], v[20:21], v[28:29]
	v_pk_fma_f32 v[18:19], v[30:31], v[18:19], v[26:27]
	v_pk_mul_f32 v[26:27], v[22:23], v[34:35] op_sel_hi:[1,0]
	v_cvt_pk_bf16_f32 v18, v18, v19
	v_cvt_pk_bf16_f32 v19, v20, v21
	global_store_dwordx2 v[10:11], v[18:19], off offset:2048
	v_pk_mul_f32 v[28:29], v[24:25], v[34:35] op_sel_hi:[1,0]
	ds_read_b128 v[18:21], v35 offset:5120
	ds_read_b128 v[22:25], v35 offset:46080
	s_waitcnt lgkmcnt(0)
	v_pk_fma_f32 v[20:21], v[28:29], v[20:21], v[24:25]
	v_pk_fma_f32 v[18:19], v[26:27], v[18:19], v[22:23]
	s_nop 0
	v_cvt_pk_bf16_f32 v18, v18, v19
	v_cvt_pk_bf16_f32 v19, v20, v21
	global_store_dwordx2 v[10:11], v[18:19], off offset:2560
	ds_read_b128 v[18:21], v35 offset:6144
	ds_read_b128 v[22:25], v35 offset:47104
	s_waitcnt lgkmcnt(0)
	v_pk_fma_f32 v[14:15], v[14:15], v[20:21], v[24:25]
	v_pk_fma_f32 v[4:5], v[4:5], v[18:19], v[22:23]
	v_pk_mul_f32 v[20:21], v[16:17], v[34:35] op_sel_hi:[1,0]
	v_cvt_pk_bf16_f32 v4, v4, v5
	v_cvt_pk_bf16_f32 v5, v14, v15
	global_store_dwordx2 v[10:11], v[4:5], off offset:3072
	v_pk_mul_f32 v[4:5], v[12:13], v[34:35] op_sel_hi:[1,0]
	ds_read_b128 v[12:15], v35 offset:7168
	ds_read_b128 v[16:19], v35 offset:48128
	s_waitcnt lgkmcnt(0)
	v_pk_fma_f32 v[14:15], v[20:21], v[14:15], v[18:19]
	v_pk_fma_f32 v[4:5], v[4:5], v[12:13], v[16:17]
	s_nop 0
	v_cvt_pk_bf16_f32 v4, v4, v5
	v_cvt_pk_bf16_f32 v5, v14, v15
	global_store_dwordx2 v[10:11], v[4:5], off offset:3584
	s_cbranch_scc0 .LBB0_223
	s_addk_i32 s4, 0x4000
	s_ashr_i32 s5, s4, 31
	s_lshl_b64 s[6:7], s[4:5], 12
	v_lshl_add_u64 v[4:5], v[8:9], 0, s[6:7]
	v_lshl_add_u64 v[18:19], v[4:5], 0, v[6:7]
	global_load_dwordx2 v[22:23], v[18:19], off
	global_load_dwordx2 v[20:21], v[18:19], off offset:512
	global_load_dwordx2 v[16:17], v[18:19], off offset:1024
	global_load_dwordx2 v[12:13], v[18:19], off offset:1536
	global_load_dwordx2 v[14:15], v[18:19], off offset:2048
	global_load_dwordx2 v[10:11], v[18:19], off offset:2560
	global_load_dwordx2 v[8:9], v[18:19], off offset:3072
	global_load_dwordx2 v[4:5], v[18:19], off offset:3584
	v_lshlrev_b32_e32 v40, 2, v143
	s_cmp_eq_u32 s76, 0
	s_cbranch_scc1 .LBB0_222
	v_mov_b32_e32 v24, s72
	v_mov_b32_e32 v25, s73
	v_lshl_add_u64 v[24:25], s[8:9], 2, v[24:25]
	v_lshl_add_u64 v[24:25], v[24:25], 0, v[0:1]
	v_lshlrev_b32_e32 v0, 2, v40
	v_lshl_add_u64 v[26:27], s[86:87], 0, v[0:1]
	v_add_co_u32_e32 v28, vcc, 0x58400000, v24
	s_nop 1
	v_addc_co_u32_e32 v29, vcc, 0, v25, vcc
	v_add_co_u32_e32 v30, vcc, 0x58c00000, v24
	s_nop 1
	v_addc_co_u32_e32 v31, vcc, 0, v25, vcc
	v_add_co_u32_e32 v32, vcc, 0x59400000, v24
	s_nop 1
	v_addc_co_u32_e32 v33, vcc, 0, v25, vcc
	v_add_co_u32_e32 v34, vcc, 0x59c00000, v24
	s_nop 1
	v_addc_co_u32_e32 v35, vcc, 0, v25, vcc
	v_add_co_u32_e32 v36, vcc, 0x58401000, v24
	s_nop 1
	v_addc_co_u32_e32 v37, vcc, 0, v25, vcc
	v_add_co_u32_e32 v38, vcc, 0x58c01000, v24
	s_nop 1
	v_addc_co_u32_e32 v39, vcc, 0, v25, vcc
	v_add_co_u32_e32 v42, vcc, 0x59401000, v24
	s_nop 1
	v_addc_co_u32_e32 v43, vcc, 0, v25, vcc
	v_add_co_u32_e32 v44, vcc, 0x59c01000, v24
	s_nop 1
	v_addc_co_u32_e32 v45, vcc, 0, v25, vcc
	v_add_co_u32_e32 v48, vcc, 0xffffe000, v26
	s_nop 1
	v_addc_co_u32_e32 v49, vcc, -1, v27, vcc
	v_add_co_u32_e32 v50, vcc, 0xfffff000, v26
	s_nop 1
	v_addc_co_u32_e32 v51, vcc, -1, v27, vcc
	global_load_dwordx4 v[94:97], v[28:29], off
	global_load_dwordx4 v[98:101], v[30:31], off
	global_load_dwordx4 v[102:105], v[32:33], off
	global_load_dwordx4 v[106:109], v[34:35], off
	global_load_dwordx4 v[110:113], v[48:49], off
	global_load_dwordx4 v[114:117], v[28:29], off offset:1024
	global_load_dwordx4 v[118:121], v[30:31], off offset:1024
	global_load_dwordx4 v[122:125], v[32:33], off offset:1024
	global_load_dwordx4 v[126:129], v[34:35], off offset:1024
	global_load_dwordx4 v[130:133], v[48:49], off offset:1024
	global_load_dwordx4 v[134:137], v[28:29], off offset:2048
	global_load_dwordx4 v[138:141], v[30:31], off offset:2048
	global_load_dwordx4 v[142:145], v[32:33], off offset:2048
	global_load_dwordx4 v[146:149], v[34:35], off offset:2048
	global_load_dwordx4 v[150:153], v[48:49], off offset:2048
	global_load_dwordx4 v[154:157], v[28:29], off offset:3072
	global_load_dwordx4 v[158:161], v[30:31], off offset:3072
	global_load_dwordx4 v[162:165], v[32:33], off offset:3072
	global_load_dwordx4 v[170:173], v[34:35], off offset:3072
	global_load_dwordx4 v[174:177], v[48:49], off offset:3072
	s_waitcnt vmcnt(15)
; #define GAS __attribute__((address_space(1)))
; __device__ __forceinline__ unsigned xpk2(float lo, float hi) { if (XRES_F16) { const f32x2_t v = {lo, hi}; const f16x2_t h = __builtin_convertvector(v, f16x2_t); return __builtin_bit_cast(unsigned, h); } return pk2(lo, hi); }
; __device__ __forceinline__ float xlo(unsigned w) { if (XRES_F16) { const f16x2_t h = __builtin_bit_cast(f16x2_t, w); return (float)h[0]; } return __builtin_bit_cast(float, w << 16); }
; __device__ __forceinline__ float xhi(unsigned w) { if (XRES_F16) { const f16x2_t h = __builtin_bit_cast(f16x2_t, w); return (float)h[1]; } return __builtin_bit_cast(float, w & 0xffff0000u); }
; __device__ __forceinline__ void norm_mod_phase2(const Args& a, Frame& F, const float* gain, const float* modl, int sh_off, int sc_off, int nrows, const float* slab_gate) {
;     ...
;         if (slab_gate != nullptr) { const GAS f32x4* sl = (const GAS f32x4*)((const float*)(a.ws + WS_SLAB) + (size_t)rc * D) + F.lane;
; #pragma unroll
;             for (int j = 0; j < 8; ++j) { const f32x4 p = (sl[64 * j] + sl[64 * j + (size_t)MC * D / 4]) + (sl[64 * j + 2 * ((size_t)MC * D / 4)] + sl[64 * j + 3 * ((size_t)MC * D / 4)]);
;                 const f32x4 x = (f32x4){xlo(r0[j].x), xhi(r0[j].x), xlo(r0[j].y), xhi(r0[j].y)} + *(const GAS f32x4*)(slab_gate + 256 * j + 4 * F.lane) * p;
;                 v2u w; w.x = xpk2(x[0], x[1]); w.y = xpk2(x[2], x[3]); ((GAS v2u*)(X + (size_t)r * D) + F.lane)[64 * j] = w; r0[j] = w; } }
	v_pk_add_f32 v[220:221], v[94:95], v[98:99]
	v_pk_add_f32 v[222:223], v[96:97], v[100:101]
	v_pk_add_f32 v[224:225], v[102:103], v[106:107]
	v_pk_add_f32 v[226:227], v[104:105], v[108:109]
	v_cvt_f32_f16_e32 v232, v22
	v_cvt_f32_f16_sdwa v233, v22 dst_sel:DWORD dst_unused:UNUSED_PAD src0_sel:WORD_1
	v_cvt_f32_f16_e32 v234, v23
	v_cvt_f32_f16_sdwa v235, v23 dst_sel:DWORD dst_unused:UNUSED_PAD src0_sel:WORD_1
	v_pk_add_f32 v[228:229], v[220:221], v[224:225]
	v_pk_add_f32 v[230:231], v[222:223], v[226:227]
	s_nop 1
	v_pk_fma_f32 v[236:237], v[110:111], v[228:229], v[232:233]
	v_pk_fma_f32 v[238:239], v[112:113], v[230:231], v[234:235]
	s_nop 1
	v_cvt_pk_f16_f32 v22, v236, v237
	v_cvt_pk_f16_f32 v23, v238, v239
	global_store_dwordx2 v[18:19], v[22:23], off
	global_load_dwordx4 v[94:97], v[36:37], off
	global_load_dwordx4 v[98:101], v[38:39], off
	global_load_dwordx4 v[102:105], v[42:43], off
	global_load_dwordx4 v[106:109], v[44:45], off
	global_load_dwordx4 v[110:113], v[50:51], off
	s_waitcnt vmcnt(16)
	v_pk_add_f32 v[220:221], v[114:115], v[118:119]
	v_pk_add_f32 v[222:223], v[116:117], v[120:121]
	v_pk_add_f32 v[224:225], v[122:123], v[126:127]
	v_pk_add_f32 v[226:227], v[124:125], v[128:129]
	v_cvt_f32_f16_e32 v232, v20
	v_cvt_f32_f16_sdwa v233, v20 dst_sel:DWORD dst_unused:UNUSED_PAD src0_sel:WORD_1
	v_cvt_f32_f16_e32 v234, v21
	v_cvt_f32_f16_sdwa v235, v21 dst_sel:DWORD dst_unused:UNUSED_PAD src0_sel:WORD_1
	v_pk_add_f32 v[228:229], v[220:221], v[224:225]
	v_pk_add_f32 v[230:231], v[222:223], v[226:227]
	s_nop 1
	v_pk_fma_f32 v[236:237], v[130:131], v[228:229], v[232:233]
	v_pk_fma_f32 v[238:239], v[132:133], v[230:231], v[234:235]
	s_nop 1
	v_cvt_pk_f16_f32 v20, v236, v237
	v_cvt_pk_f16_f32 v21, v238, v239
	global_store_dwordx2 v[18:19], v[20:21], off offset:512
	global_load_dwordx4 v[114:117], v[36:37], off offset:1024
	global_load_dwordx4 v[118:121], v[38:39], off offset:1024
	global_load_dwordx4 v[122:125], v[42:43], off offset:1024
	global_load_dwordx4 v[126:129], v[44:45], off offset:1024
	global_load_dwordx4 v[130:133], v[50:51], off offset:1024
	s_waitcnt vmcnt(17)
	v_pk_add_f32 v[220:221], v[134:135], v[138:139]
	v_pk_add_f32 v[222:223], v[136:137], v[140:141]
	v_pk_add_f32 v[224:225], v[142:143], v[146:147]
	v_pk_add_f32 v[226:227], v[144:145], v[148:149]
	v_cvt_f32_f16_e32 v232, v16
	v_cvt_f32_f16_sdwa v233, v16 dst_sel:DWORD dst_unused:UNUSED_PAD src0_sel:WORD_1
	v_cvt_f32_f16_e32 v234, v17
	v_cvt_f32_f16_sdwa v235, v17 dst_sel:DWORD dst_unused:UNUSED_PAD src0_sel:WORD_1
	v_pk_add_f32 v[228:229], v[220:221], v[224:225]
	v_pk_add_f32 v[230:231], v[222:223], v[226:227]
	s_nop 1
	v_pk_fma_f32 v[236:237], v[150:151], v[228:229], v[232:233]
	v_pk_fma_f32 v[238:239], v[152:153], v[230:231], v[234:235]
	s_nop 1
	v_cvt_pk_f16_f32 v16, v236, v237
	v_cvt_pk_f16_f32 v17, v238, v239
	global_store_dwordx2 v[18:19], v[16:17], off offset:1024
	global_load_dwordx4 v[134:137], v[36:37], off offset:2048
	global_load_dwordx4 v[138:141], v[38:39], off offset:2048
	global_load_dwordx4 v[142:145], v[42:43], off offset:2048
	global_load_dwordx4 v[146:149], v[44:45], off offset:2048
	global_load_dwordx4 v[150:153], v[50:51], off offset:2048
	s_waitcnt vmcnt(18)
; #define GAS __attribute__((address_space(1)))
; __device__ __forceinline__ unsigned xpk2(float lo, float hi) { if (XRES_F16) { const f32x2_t v = {lo, hi}; const f16x2_t h = __builtin_convertvector(v, f16x2_t); return __builtin_bit_cast(unsigned, h); } return pk2(lo, hi); }
; __device__ __forceinline__ float xlo(unsigned w) { if (XRES_F16) { const f16x2_t h = __builtin_bit_cast(f16x2_t, w); return (float)h[0]; } return __builtin_bit_cast(float, w << 16); }
; __device__ __forceinline__ float xhi(unsigned w) { if (XRES_F16) { const f16x2_t h = __builtin_bit_cast(f16x2_t, w); return (float)h[1]; } return __builtin_bit_cast(float, w & 0xffff0000u); }
; __device__ __forceinline__ void norm_mod_phase2(const Args& a, Frame& F, const float* gain, const float* modl, int sh_off, int sc_off, int nrows, const float* slab_gate) {
;     ...
;         if (slab_gate != nullptr) { const GAS f32x4* sl = (const GAS f32x4*)((const float*)(a.ws + WS_SLAB) + (size_t)rc * D) + F.lane;
; #pragma unroll
;             for (int j = 0; j < 8; ++j) { const f32x4 p = (sl[64 * j] + sl[64 * j + (size_t)MC * D / 4]) + (sl[64 * j + 2 * ((size_t)MC * D / 4)] + sl[64 * j + 3 * ((size_t)MC * D / 4)]);
;                 const f32x4 x = (f32x4){xlo(r0[j].x), xhi(r0[j].x), xlo(r0[j].y), xhi(r0[j].y)} + *(const GAS f32x4*)(slab_gate + 256 * j + 4 * F.lane) * p;
;                 v2u w; w.x = xpk2(x[0], x[1]); w.y = xpk2(x[2], x[3]); ((GAS v2u*)(X + (size_t)r * D) + F.lane)[64 * j] = w; r0[j] = w; } }
	v_pk_add_f32 v[220:221], v[154:155], v[158:159]
	v_pk_add_f32 v[222:223], v[156:157], v[160:161]
	v_pk_add_f32 v[224:225], v[162:163], v[170:171]
	v_pk_add_f32 v[226:227], v[164:165], v[172:173]
	v_cvt_f32_f16_e32 v232, v12
	v_cvt_f32_f16_sdwa v233, v12 dst_sel:DWORD dst_unused:UNUSED_PAD src0_sel:WORD_1
	v_cvt_f32_f16_e32 v234, v13
	v_cvt_f32_f16_sdwa v235, v13 dst_sel:DWORD dst_unused:UNUSED_PAD src0_sel:WORD_1
	v_pk_add_f32 v[228:229], v[220:221], v[224:225]
	v_pk_add_f32 v[230:231], v[222:223], v[226:227]
	s_nop 1
	v_pk_fma_f32 v[236:237], v[174:175], v[228:229], v[232:233]
	v_pk_fma_f32 v[238:239], v[176:177], v[230:231], v[234:235]
	s_nop 1
	v_cvt_pk_f16_f32 v12, v236, v237
	v_cvt_pk_f16_f32 v13, v238, v239
	global_store_dwordx2 v[18:19], v[12:13], off offset:1536
	global_load_dwordx4 v[154:157], v[36:37], off offset:3072
	global_load_dwordx4 v[158:161], v[38:39], off offset:3072
	global_load_dwordx4 v[162:165], v[42:43], off offset:3072
	global_load_dwordx4 v[170:173], v[44:45], off offset:3072
	global_load_dwordx4 v[174:177], v[50:51], off offset:3072
	s_waitcnt vmcnt(18)
	v_pk_add_f32 v[220:221], v[94:95], v[98:99]
	v_pk_add_f32 v[222:223], v[96:97], v[100:101]
	v_pk_add_f32 v[224:225], v[102:103], v[106:107]
	v_pk_add_f32 v[226:227], v[104:105], v[108:109]
	v_cvt_f32_f16_e32 v232, v14
	v_cvt_f32_f16_sdwa v233, v14 dst_sel:DWORD dst_unused:UNUSED_PAD src0_sel:WORD_1
	v_cvt_f32_f16_e32 v234, v15
	v_cvt_f32_f16_sdwa v235, v15 dst_sel:DWORD dst_unused:UNUSED_PAD src0_sel:WORD_1
	v_pk_add_f32 v[228:229], v[220:221], v[224:225]
	v_pk_add_f32 v[230:231], v[222:223], v[226:227]
	s_nop 1
	v_pk_fma_f32 v[236:237], v[110:111], v[228:229], v[232:233]
	v_pk_fma_f32 v[238:239], v[112:113], v[230:231], v[234:235]
	s_nop 1
	v_cvt_pk_f16_f32 v14, v236, v237
	v_cvt_pk_f16_f32 v15, v238, v239
	global_store_dwordx2 v[18:19], v[14:15], off offset:2048
	s_waitcnt vmcnt(13)
	v_pk_add_f32 v[220:221], v[114:115], v[118:119]
	v_pk_add_f32 v[222:223], v[116:117], v[120:121]
	v_pk_add_f32 v[224:225], v[122:123], v[126:127]
	v_pk_add_f32 v[226:227], v[124:125], v[128:129]
	v_cvt_f32_f16_e32 v232, v10
	v_cvt_f32_f16_sdwa v233, v10 dst_sel:DWORD dst_unused:UNUSED_PAD src0_sel:WORD_1
	v_cvt_f32_f16_e32 v234, v11
	v_cvt_f32_f16_sdwa v235, v11 dst_sel:DWORD dst_unused:UNUSED_PAD src0_sel:WORD_1
	v_pk_add_f32 v[228:229], v[220:221], v[224:225]
	v_pk_add_f32 v[230:231], v[222:223], v[226:227]
	s_nop 1
	v_pk_fma_f32 v[236:237], v[130:131], v[228:229], v[232:233]
	v_pk_fma_f32 v[238:239], v[132:133], v[230:231], v[234:235]
	s_nop 1
	v_cvt_pk_f16_f32 v10, v236, v237
	v_cvt_pk_f16_f32 v11, v238, v239
	global_store_dwordx2 v[18:19], v[10:11], off offset:2560
	s_waitcnt vmcnt(8)
	v_pk_add_f32 v[220:221], v[134:135], v[138:139]
	v_pk_add_f32 v[222:223], v[136:137], v[140:141]
	v_pk_add_f32 v[224:225], v[142:143], v[146:147]
	v_pk_add_f32 v[226:227], v[144:145], v[148:149]
	v_cvt_f32_f16_e32 v232, v8
	v_cvt_f32_f16_sdwa v233, v8 dst_sel:DWORD dst_unused:UNUSED_PAD src0_sel:WORD_1
	v_cvt_f32_f16_e32 v234, v9
	v_cvt_f32_f16_sdwa v235, v9 dst_sel:DWORD dst_unused:UNUSED_PAD src0_sel:WORD_1
	v_pk_add_f32 v[228:229], v[220:221], v[224:225]
	v_pk_add_f32 v[230:231], v[222:223], v[226:227]
	s_nop 1
	v_pk_fma_f32 v[236:237], v[150:151], v[228:229], v[232:233]
	v_pk_fma_f32 v[238:239], v[152:153], v[230:231], v[234:235]
	s_nop 1
	v_cvt_pk_f16_f32 v8, v236, v237
	v_cvt_pk_f16_f32 v9, v238, v239
	global_store_dwordx2 v[18:19], v[8:9], off offset:3072
	s_waitcnt vmcnt(3)
	v_pk_add_f32 v[220:221], v[154:155], v[158:159]
	v_pk_add_f32 v[222:223], v[156:157], v[160:161]
	v_pk_add_f32 v[224:225], v[162:163], v[170:171]
	v_pk_add_f32 v[226:227], v[164:165], v[172:173]
	v_cvt_f32_f16_e32 v232, v4
	v_cvt_f32_f16_sdwa v233, v4 dst_sel:DWORD dst_unused:UNUSED_PAD src0_sel:WORD_1
	v_cvt_f32_f16_e32 v234, v5
	v_cvt_f32_f16_sdwa v235, v5 dst_sel:DWORD dst_unused:UNUSED_PAD src0_sel:WORD_1
	v_pk_add_f32 v[228:229], v[220:221], v[224:225]
	v_pk_add_f32 v[230:231], v[222:223], v[226:227]
	s_nop 1
	v_pk_fma_f32 v[236:237], v[174:175], v[228:229], v[232:233]
	v_pk_fma_f32 v[238:239], v[176:177], v[230:231], v[234:235]
	s_nop 1
	v_cvt_pk_f16_f32 v4, v236, v237
	v_cvt_pk_f16_f32 v5, v238, v239
	global_store_dwordx2 v[18:19], v[4:5], off offset:3584

; #define GAS __attribute__((address_space(1)))
; #define LAS __attribute__((address_space(3)))
; #define NR_LOAD(dst, k_) do { const GAS v2u* xr_ = (const GAS v2u*)(X + (size_t)(nw + 2048 * (k_)) * D) + F.lane; \
;         _Pragma("unroll") for (int j = 0; j < 8; ++j) dst[j] = __builtin_nontemporal_load(xr_ + 64 * j); } while (0)
; __device__ __forceinline__ void norm_mod_phase2(const Args& a, Frame& F, const float* gain, const float* modl, int sh_off, int sc_off, int nrows, const float* slab_gate) {
;     ...
;     NR_LOAD(r0, 0); NR_LOAD(r1, 1); NR_LOAD(r2, 2); NR_LOAD(r3, 3); NR_LOAD(r4, 4); NR_LOAD(r5, 5); NR_LOAD(r6, 6); NR_LOAD(r7, 7);
;     { const GAS f32x4* g4 = (const GAS f32x4*)gain;
;       for (int q = F.tid; q < 5 * D / 4; q += NWAVES * 64) { const int bq = q >> 9, cq = q & 511; const GAS f32x4* mb4 = (const GAS f32x4*)(modl + (size_t)bq * MOD_LD);
;           ((LAS f32x4*)CA)[q] = g4[cq] * (mb4[sc_off / 4 + cq] + 1.0f); ((LAS f32x4*)CB)[q] = mb4[sh_off / 4 + cq]; } }
;     asm volatile("s_waitcnt lgkmcnt(0)" ::: "memory"); __builtin_amdgcn_s_barrier(); asm volatile("" ::: "memory");
.LBB0_1046:
	s_or_b64 exec, exec, s[8:9]
	s_waitcnt vmcnt(62)
	v_cvt_f32_f16_sdwa v153, v140 dst_sel:DWORD dst_unused:UNUSED_PAD src0_sel:WORD_1
	v_cvt_f32_f16_sdwa v149, v138 dst_sel:DWORD dst_unused:UNUSED_PAD src0_sel:WORD_1
	v_cvt_f32_f16_e32 v152, v140
	v_cvt_f32_f16_sdwa v155, v141 dst_sel:DWORD dst_unused:UNUSED_PAD src0_sel:WORD_1
	v_cvt_f32_f16_e32 v148, v138
	v_cvt_f32_f16_sdwa v151, v139 dst_sel:DWORD dst_unused:UNUSED_PAD src0_sel:WORD_1
	v_cvt_f32_f16_e32 v154, v141
	v_cvt_f32_f16_e32 v150, v139
	s_waitcnt vmcnt(61)
	v_cvt_f32_f16_sdwa v139, v134 dst_sel:DWORD dst_unused:UNUSED_PAD src0_sel:WORD_1
	v_cvt_f32_f16_sdwa v141, v135 dst_sel:DWORD dst_unused:UNUSED_PAD src0_sel:WORD_1
	s_mov_b64 s[6:7], 0x8c00000
	v_mov_b32_e32 v74, v153
	v_mov_b32_e32 v75, v149
	v_cvt_f32_f16_e32 v138, v134
	v_cvt_f32_f16_e32 v140, v135
	v_lshl_add_u64 v[2:3], v[136:137], 0, s[6:7]
	v_mov_b32_e32 v4, v152
	v_mov_b32_e32 v5, v148
	v_pk_mul_f32 v[74:75], v[74:75], v[74:75]
	v_mov_b32_e32 v136, v155
	v_mov_b32_e32 v137, v151
	v_pk_fma_f32 v[4:5], v[4:5], v[4:5], v[74:75]
	v_mov_b32_e32 v74, v154
	v_mov_b32_e32 v75, v150
	v_pk_mul_f32 v[136:137], v[136:137], v[136:137]
	v_mov_b32_e32 v134, v139
	v_pk_fma_f32 v[74:75], v[74:75], v[74:75], v[136:137]
	v_mov_b32_e32 v135, v141
	s_waitcnt vmcnt(60)
	v_cvt_f32_f16_sdwa v143, v132 dst_sel:DWORD dst_unused:UNUSED_PAD src0_sel:WORD_1
	v_pk_add_f32 v[4:5], v[4:5], v[74:75]
	v_mov_b32_e32 v74, v138
	v_mov_b32_e32 v75, v140
	v_pk_mul_f32 v[134:135], v[134:135], v[134:135]
	v_cvt_f32_f16_e32 v142, v132
	v_cvt_f32_f16_sdwa v145, v133 dst_sel:DWORD dst_unused:UNUSED_PAD src0_sel:WORD_1
	v_pk_fma_f32 v[74:75], v[74:75], v[74:75], v[134:135]
	v_cvt_f32_f16_e32 v144, v133
	s_waitcnt vmcnt(59)
	v_cvt_f32_f16_sdwa v133, v130 dst_sel:DWORD dst_unused:UNUSED_PAD src0_sel:WORD_1
	v_cvt_f32_f16_e32 v132, v130
	v_cvt_f32_f16_sdwa v135, v131 dst_sel:DWORD dst_unused:UNUSED_PAD src0_sel:WORD_1
	v_cvt_f32_f16_e32 v134, v131
	v_mul_f32_e32 v0, v143, v143
	v_pk_fma_f32 v[136:137], v[142:143], v[142:143], v[0:1] op_sel_hi:[1,1,0]
	v_mul_f32_e32 v0, v145, v145
	v_pk_add_f32 v[4:5], v[4:5], v[4:5] op_sel:[0,1] op_sel_hi:[1,0]
	v_pk_add_f32 v[74:75], v[74:75], v[74:75] op_sel:[0,1] op_sel_hi:[1,0]
	v_pk_fma_f32 v[156:157], v[144:145], v[144:145], v[0:1] op_sel_hi:[1,1,0]
	v_pk_mul_f32 v[130:131], v[132:133], v[132:133]
	v_pk_mul_f32 v[158:159], v[134:135], v[134:135]
	v_mov_b32_e32 v5, v130
	v_mov_b32_e32 v75, v131
	v_mov_b32_e32 v137, v158
	v_mov_b32_e32 v157, v159
	v_pk_add_f32 v[4:5], v[4:5], v[74:75]
	v_pk_add_f32 v[74:75], v[136:137], v[156:157]
	s_waitcnt vmcnt(58)
	v_cvt_f32_f16_sdwa v131, v128 dst_sel:DWORD dst_unused:UNUSED_PAD src0_sel:WORD_1
	v_cvt_f32_f16_sdwa v137, v129 dst_sel:DWORD dst_unused:UNUSED_PAD src0_sel:WORD_1
	v_cvt_f32_f16_e32 v130, v128
	v_cvt_f32_f16_e32 v136, v129
	v_pk_add_f32 v[4:5], v[4:5], v[74:75]
	v_mov_b32_e32 v74, v131
	v_mov_b32_e32 v75, v137
	v_pk_add_f32 v[156:157], v[4:5], v[4:5] op_sel:[0,1] op_sel_hi:[1,0]
	v_mov_b32_e32 v4, v130
	v_mov_b32_e32 v5, v136
	v_pk_mul_f32 v[74:75], v[74:75], v[74:75]
	s_waitcnt vmcnt(57)
	v_cvt_f32_f16_sdwa v129, v127 dst_sel:DWORD dst_unused:UNUSED_PAD src0_sel:WORD_1
	v_pk_fma_f32 v[4:5], v[4:5], v[4:5], v[74:75]
	v_cvt_f32_f16_e32 v128, v127
	v_pk_add_f32 v[158:159], v[4:5], v[4:5] op_sel:[0,1] op_sel_hi:[1,0]
	v_cvt_f32_f16_sdwa v5, v126 dst_sel:DWORD dst_unused:UNUSED_PAD src0_sel:WORD_1
	v_cvt_f32_f16_e32 v4, v126
	s_waitcnt vmcnt(56)
	v_cvt_f32_f16_sdwa v75, v124 dst_sel:DWORD dst_unused:UNUSED_PAD src0_sel:WORD_1
	v_cvt_f32_f16_e32 v74, v124
	v_cvt_f32_f16_sdwa v127, v125 dst_sel:DWORD dst_unused:UNUSED_PAD src0_sel:WORD_1
	v_cvt_f32_f16_e32 v126, v125
	v_mul_f32_e32 v0, v5, v5
	v_pk_fma_f32 v[160:161], v[4:5], v[4:5], v[0:1] op_sel_hi:[1,1,0]
	v_mul_f32_e32 v0, v129, v129
	v_pk_fma_f32 v[162:163], v[128:129], v[128:129], v[0:1] op_sel_hi:[1,1,0]
	v_pk_mul_f32 v[124:125], v[74:75], v[74:75]
	v_pk_mul_f32 v[164:165], v[126:127], v[126:127]
	v_mov_b32_e32 v157, v124
	v_mov_b32_e32 v159, v125
	v_mov_b32_e32 v161, v164
	v_mov_b32_e32 v163, v165
	v_pk_add_f32 v[124:125], v[156:157], v[158:159]
	v_pk_add_f32 v[156:157], v[160:161], v[162:163]
	s_waitcnt lgkmcnt(0)
	s_barrier
	v_pk_add_f32 v[124:125], v[124:125], v[156:157]
	s_lshl_b64 s[12:13], s[10:11], 11
	v_add_f32_e32 v0, v124, v125
	s_lshl_b64 s[48:49], s[78:79], 11
	s_lshl_b64 s[40:41], s[36:37], 11
	v_add_f32_dpp v0, v0, v0 quad_perm:[1,0,3,2] row_mask:0xf bank_mask:0xf bound_ctrl:1
	s_lshl_b64 s[34:35], s[30:31], 11
	s_lshl_b64 s[28:29], s[26:27], 11
	v_add_f32_dpp v0, v0, v0 quad_perm:[2,3,0,1] row_mask:0xf bank_mask:0xf bound_ctrl:1
	s_lshl_b64 s[24:25], s[22:23], 11
	s_lshl_b64 s[20:21], s[18:19], 11
	v_add_f32_dpp v0, v0, v0 row_half_mirror row_mask:0xf bank_mask:0xf bound_ctrl:1
	s_lshl_b64 s[16:17], s[14:15], 11
	s_nop 0
	v_add_f32_dpp v0, v0, v0 row_mirror row_mask:0xf bank_mask:0xf bound_ctrl:1
	s_nop 0
	v_readlane_b32 s8, v0, 16
	v_readlane_b32 s9, v0, 48
	v_readlane_b32 s6, v0, 0
	v_readlane_b32 s7, v0, 32
	v_mov_b32_e32 v124, s8
	v_mov_b32_e32 v125, s9
	v_pk_add_f32 v[124:125], s[6:7], v[124:125]
	s_nop 0
	v_add_f32_e32 v0, v124, v125
	v_fmamk_f32 v0, v0, 0x3a000000, v252
	v_cmp_gt_f32_e32 vcc, s55, v0
	v_mul_f32_e32 v7, 0x4f800000, v0
	s_nop 0
	v_cndmask_b32_e32 v0, v0, v7, vcc
	v_sqrt_f32_e32 v7, v0
	s_nop 0
	v_add_u32_e32 v124, -1, v7
	v_fma_f32 v125, -v124, v7, v0
	v_cmp_ge_f32_e64 s[8:9], 0, v125
	v_add_u32_e32 v125, 1, v7
	s_nop 0
	v_cndmask_b32_e64 v124, v7, v124, s[8:9]
	v_fma_f32 v7, -v125, v7, v0
	v_cmp_lt_f32_e64 s[8:9], 0, v7
	s_nop 1
	v_cndmask_b32_e64 v7, v124, v125, s[8:9]
	v_mul_f32_e32 v124, 0x37800000, v7
	v_cndmask_b32_e32 v7, v7, v124, vcc
	v_cmp_class_f32_e32 vcc, v0, v253
	s_nop 1
	v_cndmask_b32_e32 v0, v7, v0, vcc
	v_div_scale_f32 v7, s[6:7], v0, v0, 1.0
	v_rcp_f32_e32 v124, v7
	s_lshl_b32 s6, s10, 1
	s_and_b32 s6, s6, 0xffffe000
	s_add_i32 s6, s6, 0
	v_fma_f32 v125, -v7, v124, 1.0
	v_fmac_f32_e32 v124, v125, v124
	v_div_scale_f32 v125, vcc, 1.0, v0, 1.0
	v_mul_f32_e32 v146, v125, v124
	v_fma_f32 v156, -v7, v146, v125
	v_fmac_f32_e32 v146, v156, v124
	v_fma_f32 v7, -v7, v146, v125
	v_div_fmas_f32 v7, v7, v124, v146
	v_div_fixup_f32 v146, v7, v0, 1.0
	v_lshlrev_b32_e32 v0, 4, v147
	v_add_u32_e32 v164, s6, v0
	v_pk_mul_f32 v[160:161], v[152:153], v[146:147] op_sel_hi:[1,0]
	v_pk_mul_f32 v[162:163], v[154:155], v[146:147] op_sel_hi:[1,0]
	ds_read_b128 v[152:155], v164
	ds_read_b128 v[156:159], v164 offset:40960
	v_lshl_add_u64 v[124:125], s[12:13], 1, v[2:3]
	v_mov_b32_e32 v7, v1
	v_lshl_add_u64 v[124:125], v[124:125], 0, v[6:7]
	v_pk_mul_f32 v[4:5], v[4:5], v[146:147] op_sel_hi:[1,0]
	s_waitcnt lgkmcnt(0)
	v_pk_fma_f32 v[154:155], v[154:155], v[162:163], v[158:159]
	v_pk_fma_f32 v[152:153], v[152:153], v[160:161], v[156:157]
	v_pk_mul_f32 v[156:157], v[148:149], v[146:147] op_sel_hi:[1,0]
	v_cvt_pk_bf16_f32 v152, v152, v153
	v_cvt_pk_bf16_f32 v153, v154, v155
	global_store_dwordx2 v[124:125], v[152:153], off
	v_pk_mul_f32 v[158:159], v[150:151], v[146:147] op_sel_hi:[1,0]
	ds_read_b128 v[148:151], v164 offset:1024
	ds_read_b128 v[152:155], v164 offset:41984
	s_waitcnt lgkmcnt(0)
	v_pk_fma_f32 v[150:151], v[150:151], v[158:159], v[154:155]
	v_pk_fma_f32 v[148:149], v[148:149], v[156:157], v[152:153]
	v_pk_mul_f32 v[152:153], v[138:139], v[146:147] op_sel_hi:[1,0]
	v_cvt_pk_bf16_f32 v148, v148, v149
	v_cvt_pk_bf16_f32 v149, v150, v151
	global_store_dwordx2 v[124:125], v[148:149], off offset:512
	v_pk_mul_f32 v[154:155], v[140:141], v[146:147] op_sel_hi:[1,0]
	ds_read_b128 v[138:141], v164 offset:2048
	ds_read_b128 v[148:151], v164 offset:43008
	s_waitcnt lgkmcnt(0)
	v_pk_fma_f32 v[140:141], v[140:141], v[154:155], v[150:151]
	v_pk_fma_f32 v[138:139], v[138:139], v[152:153], v[148:149]
	v_pk_mul_f32 v[148:149], v[142:143], v[146:147] op_sel_hi:[1,0]
	v_cvt_pk_bf16_f32 v138, v138, v139
	v_cvt_pk_bf16_f32 v139, v140, v141
	global_store_dwordx2 v[124:125], v[138:139], off offset:1024
	v_pk_mul_f32 v[150:151], v[144:145], v[146:147] op_sel_hi:[1,0]
	ds_read_b128 v[138:141], v164 offset:3072
	ds_read_b128 v[142:145], v164 offset:44032
	s_waitcnt lgkmcnt(0)
	v_pk_fma_f32 v[140:141], v[150:151], v[140:141], v[144:145]
	v_pk_fma_f32 v[138:139], v[148:149], v[138:139], v[142:143]
	v_pk_mul_f32 v[142:143], v[132:133], v[146:147] op_sel_hi:[1,0]
	v_cvt_pk_bf16_f32 v138, v138, v139
	v_cvt_pk_bf16_f32 v139, v140, v141
	global_store_dwordx2 v[124:125], v[138:139], off offset:1536
	v_pk_mul_f32 v[144:145], v[134:135], v[146:147] op_sel_hi:[1,0]
	ds_read_b128 v[132:135], v164 offset:4096
	ds_read_b128 v[138:141], v164 offset:45056
	s_waitcnt lgkmcnt(0)
	v_pk_fma_f32 v[134:135], v[144:145], v[134:135], v[140:141]
	v_pk_fma_f32 v[132:133], v[142:143], v[132:133], v[138:139]
	v_pk_mul_f32 v[138:139], v[130:131], v[146:147] op_sel_hi:[1,0]
	v_cvt_pk_bf16_f32 v132, v132, v133
	v_cvt_pk_bf16_f32 v133, v134, v135
	global_store_dwordx2 v[124:125], v[132:133], off offset:2048
	v_pk_mul_f32 v[140:141], v[136:137], v[146:147] op_sel_hi:[1,0]
	ds_read_b128 v[130:133], v164 offset:5120
	ds_read_b128 v[134:137], v164 offset:46080
	s_waitcnt lgkmcnt(0)
	v_pk_fma_f32 v[132:133], v[140:141], v[132:133], v[136:137]
	v_pk_fma_f32 v[130:131], v[138:139], v[130:131], v[134:135]
	v_pk_mul_f32 v[136:137], v[128:129], v[146:147] op_sel_hi:[1,0]
	v_cvt_pk_bf16_f32 v130, v130, v131
	v_cvt_pk_bf16_f32 v131, v132, v133
	global_store_dwordx2 v[124:125], v[130:131], off offset:2560
	ds_read_b128 v[128:131], v164 offset:6144
	ds_read_b128 v[132:135], v164 offset:47104
	s_waitcnt vmcnt(61)
	v_cvt_f32_f16_sdwa v139, v123 dst_sel:DWORD dst_unused:UNUSED_PAD src0_sel:WORD_1
	v_cvt_f32_f16_e32 v138, v123
	s_waitcnt vmcnt(59)
	v_cvt_f32_f16_sdwa v123, v118 dst_sel:DWORD dst_unused:UNUSED_PAD src0_sel:WORD_1
	s_waitcnt lgkmcnt(0)
; __device__ __forceinline__ void norm_mod_phase2(const Args& a, Frame& F, const float* gain, const float* modl, int sh_off, int sc_off, int nrows, const float* slab_gate) {
;     ...
;     NR_FINISH(r0, nw,            (nw) >> 12);
;     NR_FINISH(r1, nw + 2048,     (nw + 2048) >> 12);
	v_pk_fma_f32 v[130:131], v[136:137], v[130:131], v[134:135]
	v_pk_fma_f32 v[4:5], v[4:5], v[128:129], v[132:133]
	v_cvt_f32_f16_sdwa v137, v122 dst_sel:DWORD dst_unused:UNUSED_PAD src0_sel:WORD_1
	v_cvt_pk_bf16_f32 v4, v4, v5
	v_cvt_pk_bf16_f32 v5, v130, v131
	global_store_dwordx2 v[124:125], v[4:5], off offset:3072
	v_pk_mul_f32 v[4:5], v[74:75], v[146:147] op_sel_hi:[1,0]
	v_pk_mul_f32 v[74:75], v[126:127], v[146:147] op_sel_hi:[1,0]
	ds_read_b128 v[126:129], v164 offset:7168
	ds_read_b128 v[130:133], v164 offset:48128
	v_cvt_f32_f16_e32 v136, v122
	v_cvt_f32_f16_sdwa v135, v121 dst_sel:DWORD dst_unused:UNUSED_PAD src0_sel:WORD_1
	v_cvt_f32_f16_e32 v134, v121
	v_cvt_f32_f16_e32 v122, v118
	s_waitcnt lgkmcnt(0)
	v_pk_fma_f32 v[74:75], v[74:75], v[128:129], v[132:133]
	v_cvt_f32_f16_sdwa v133, v120 dst_sel:DWORD dst_unused:UNUSED_PAD src0_sel:WORD_1
	v_pk_fma_f32 v[4:5], v[4:5], v[126:127], v[130:131]
	v_cvt_f32_f16_e32 v132, v120
	v_cvt_pk_bf16_f32 v4, v4, v5
	v_cvt_pk_bf16_f32 v5, v74, v75
	global_store_dwordx2 v[124:125], v[4:5], off offset:3584
	v_cvt_f32_f16_sdwa v125, v119 dst_sel:DWORD dst_unused:UNUSED_PAD src0_sel:WORD_1
	s_waitcnt vmcnt(60)
	v_cvt_f32_f16_sdwa v127, v116 dst_sel:DWORD dst_unused:UNUSED_PAD src0_sel:WORD_1
	v_mov_b32_e32 v74, v137
	v_mov_b32_e32 v75, v133
	v_cvt_f32_f16_e32 v124, v119
	v_cvt_f32_f16_e32 v126, v116
	v_cvt_f32_f16_sdwa v129, v117 dst_sel:DWORD dst_unused:UNUSED_PAD src0_sel:WORD_1
	v_mov_b32_e32 v4, v136
	v_mov_b32_e32 v5, v132
	v_pk_mul_f32 v[74:75], v[74:75], v[74:75]
	v_mov_b32_e32 v120, v139
	v_mov_b32_e32 v121, v135
	v_cvt_f32_f16_e32 v128, v117
	v_pk_fma_f32 v[4:5], v[4:5], v[4:5], v[74:75]
	v_mov_b32_e32 v74, v138
	v_mov_b32_e32 v75, v134
	v_pk_mul_f32 v[120:121], v[120:121], v[120:121]
	v_mov_b32_e32 v118, v123
	v_pk_fma_f32 v[74:75], v[74:75], v[74:75], v[120:121]
	v_mov_b32_e32 v119, v125
	v_mul_f32_e32 v116, v127, v127
	v_pk_add_f32 v[4:5], v[4:5], v[74:75]
	v_mov_b32_e32 v74, v122
	v_mov_b32_e32 v75, v124
	v_pk_mul_f32 v[118:119], v[118:119], v[118:119]
	v_pk_fma_f32 v[120:121], v[126:127], v[126:127], v[116:117] op_sel_hi:[1,1,0]
	v_mul_f32_e32 v116, v129, v129
	v_pk_fma_f32 v[74:75], v[74:75], v[74:75], v[118:119]
	v_pk_fma_f32 v[130:131], v[128:129], v[128:129], v[116:117] op_sel_hi:[1,1,0]
	s_waitcnt vmcnt(59)
	v_cvt_f32_f16_sdwa v117, v114 dst_sel:DWORD dst_unused:UNUSED_PAD src0_sel:WORD_1
	v_cvt_f32_f16_e32 v116, v114
	v_cvt_f32_f16_sdwa v119, v115 dst_sel:DWORD dst_unused:UNUSED_PAD src0_sel:WORD_1
	v_cvt_f32_f16_e32 v118, v115
	v_pk_add_f32 v[4:5], v[4:5], v[4:5] op_sel:[0,1] op_sel_hi:[1,0]
	v_pk_add_f32 v[74:75], v[74:75], v[74:75] op_sel:[0,1] op_sel_hi:[1,0]
	v_pk_mul_f32 v[114:115], v[116:117], v[116:117]
	v_pk_mul_f32 v[140:141], v[118:119], v[118:119]
	v_mov_b32_e32 v5, v114
	v_mov_b32_e32 v75, v115
	v_mov_b32_e32 v121, v140
	v_mov_b32_e32 v131, v141
	v_pk_add_f32 v[4:5], v[4:5], v[74:75]
	v_pk_add_f32 v[74:75], v[120:121], v[130:131]
	s_waitcnt vmcnt(58)
	v_cvt_f32_f16_sdwa v115, v112 dst_sel:DWORD dst_unused:UNUSED_PAD src0_sel:WORD_1
	v_cvt_f32_f16_sdwa v121, v113 dst_sel:DWORD dst_unused:UNUSED_PAD src0_sel:WORD_1
	v_cvt_f32_f16_e32 v114, v112
	v_cvt_f32_f16_e32 v120, v113
	v_pk_add_f32 v[4:5], v[4:5], v[74:75]
	v_mov_b32_e32 v74, v115
	v_mov_b32_e32 v75, v121
	v_pk_add_f32 v[130:131], v[4:5], v[4:5] op_sel:[0,1] op_sel_hi:[1,0]
	v_mov_b32_e32 v4, v114
	v_mov_b32_e32 v5, v120
	v_pk_mul_f32 v[74:75], v[74:75], v[74:75]
	s_waitcnt vmcnt(57)
	v_cvt_f32_f16_sdwa v113, v111 dst_sel:DWORD dst_unused:UNUSED_PAD src0_sel:WORD_1
	v_pk_fma_f32 v[4:5], v[4:5], v[4:5], v[74:75]
	v_cvt_f32_f16_e32 v112, v111
	v_pk_add_f32 v[140:141], v[4:5], v[4:5] op_sel:[0,1] op_sel_hi:[1,0]
	v_cvt_f32_f16_sdwa v5, v110 dst_sel:DWORD dst_unused:UNUSED_PAD src0_sel:WORD_1
	v_cvt_f32_f16_e32 v4, v110
	s_waitcnt vmcnt(56)
	v_cvt_f32_f16_sdwa v111, v109 dst_sel:DWORD dst_unused:UNUSED_PAD src0_sel:WORD_1
	v_cvt_f32_f16_e32 v110, v109
	v_mul_f32_e32 v74, v5, v5
	v_pk_fma_f32 v[142:143], v[4:5], v[4:5], v[74:75] op_sel_hi:[1,1,0]
	v_mul_f32_e32 v74, v113, v113
	v_pk_fma_f32 v[144:145], v[112:113], v[112:113], v[74:75] op_sel_hi:[1,1,0]
	v_cvt_f32_f16_sdwa v75, v108 dst_sel:DWORD dst_unused:UNUSED_PAD src0_sel:WORD_1
	v_cvt_f32_f16_e32 v74, v108
	v_pk_mul_f32 v[148:149], v[110:111], v[110:111]
	v_pk_mul_f32 v[108:109], v[74:75], v[74:75]
	s_nop 0
	v_mov_b32_e32 v131, v108
	v_mov_b32_e32 v141, v109
	v_mov_b32_e32 v143, v148
	v_mov_b32_e32 v145, v149
	v_pk_add_f32 v[108:109], v[130:131], v[140:141]
	v_pk_add_f32 v[130:131], v[142:143], v[144:145]
	s_nop 0
	v_pk_add_f32 v[108:109], v[108:109], v[130:131]
	s_nop 0
	v_add_f32_e32 v108, v108, v109
	s_nop 1
	v_add_f32_dpp v108, v108, v108 quad_perm:[1,0,3,2] row_mask:0xf bank_mask:0xf bound_ctrl:1
	s_nop 1
	v_add_f32_dpp v108, v108, v108 quad_perm:[2,3,0,1] row_mask:0xf bank_mask:0xf bound_ctrl:1
	s_nop 1
	v_add_f32_dpp v108, v108, v108 row_half_mirror row_mask:0xf bank_mask:0xf bound_ctrl:1
	s_nop 1
	v_add_f32_dpp v108, v108, v108 row_mirror row_mask:0xf bank_mask:0xf bound_ctrl:1
	s_nop 0
	v_readlane_b32 s8, v108, 16
	v_readlane_b32 s9, v108, 48
	v_readlane_b32 s6, v108, 0
	v_readlane_b32 s7, v108, 32
	v_mov_b32_e32 v108, s8
	v_mov_b32_e32 v109, s9
	v_pk_add_f32 v[108:109], s[6:7], v[108:109]
	s_nop 0
	v_add_f32_e32 v108, v108, v109
	v_fmamk_f32 v108, v108, 0x3a000000, v252
	v_cmp_gt_f32_e32 vcc, s55, v108
	v_mul_f32_e32 v109, 0x4f800000, v108
	s_nop 0
	v_cndmask_b32_e32 v108, v108, v109, vcc
	v_sqrt_f32_e32 v109, v108
	s_nop 0
	v_add_u32_e32 v130, -1, v109
	v_fma_f32 v131, -v130, v109, v108
	v_cmp_ge_f32_e64 s[8:9], 0, v131
	v_add_u32_e32 v131, 1, v109
	s_nop 0
	v_cndmask_b32_e64 v130, v109, v130, s[8:9]
	v_fma_f32 v109, -v131, v109, v108
	v_cmp_lt_f32_e64 s[8:9], 0, v109
	s_nop 1
	v_cndmask_b32_e64 v109, v130, v131, s[8:9]
	v_mul_f32_e32 v130, 0x37800000, v109
	v_cndmask_b32_e32 v109, v109, v130, vcc
	v_cmp_class_f32_e32 vcc, v108, v253
	s_nop 1
	v_cndmask_b32_e32 v108, v109, v108, vcc
	v_div_scale_f32 v109, s[6:7], v108, v108, 1.0
	v_rcp_f32_e32 v130, v109
	s_lshl_b32 s6, s78, 1
	s_and_b32 s6, s6, 0xffffe000
	s_add_i32 s6, s6, 0
	v_fma_f32 v131, -v109, v130, 1.0
	v_fmac_f32_e32 v130, v131, v130
	v_div_scale_f32 v131, vcc, 1.0, v108, 1.0
	v_mul_f32_e32 v140, v131, v130
	v_fma_f32 v141, -v109, v140, v131
	v_fmac_f32_e32 v140, v141, v130
	v_fma_f32 v109, -v109, v140, v131
	v_div_fmas_f32 v109, v109, v130, v140
	v_div_fixup_f32 v130, v109, v108, 1.0
	v_pk_mul_f32 v[144:145], v[136:137], v[130:131] op_sel_hi:[1,0]
	v_pk_mul_f32 v[148:149], v[138:139], v[130:131] op_sel_hi:[1,0]
	v_add_u32_e32 v131, s6, v0
	ds_read_b128 v[136:139], v131
	ds_read_b128 v[140:143], v131 offset:40960
	v_lshl_add_u64 v[108:109], s[48:49], 1, v[2:3]
	v_lshl_add_u64 v[108:109], v[108:109], 0, v[6:7]
	v_pk_mul_f32 v[4:5], v[4:5], v[130:131] op_sel_hi:[1,0]
	s_waitcnt lgkmcnt(0)
	v_pk_fma_f32 v[138:139], v[138:139], v[148:149], v[142:143]
	v_pk_fma_f32 v[136:137], v[136:137], v[144:145], v[140:141]
	v_pk_mul_f32 v[140:141], v[132:133], v[130:131] op_sel_hi:[1,0]
	v_cvt_pk_bf16_f32 v136, v136, v137
	v_cvt_pk_bf16_f32 v137, v138, v139
	global_store_dwordx2 v[108:109], v[136:137], off
	v_pk_mul_f32 v[142:143], v[134:135], v[130:131] op_sel_hi:[1,0]
	ds_read_b128 v[132:135], v131 offset:1024
	ds_read_b128 v[136:139], v131 offset:41984
	s_waitcnt lgkmcnt(0)
	v_pk_fma_f32 v[134:135], v[134:135], v[142:143], v[138:139]
	v_pk_fma_f32 v[132:133], v[132:133], v[140:141], v[136:137]
	v_pk_mul_f32 v[136:137], v[122:123], v[130:131] op_sel_hi:[1,0]
	v_cvt_pk_bf16_f32 v132, v132, v133
	v_cvt_pk_bf16_f32 v133, v134, v135
	global_store_dwordx2 v[108:109], v[132:133], off offset:512
	v_pk_mul_f32 v[138:139], v[124:125], v[130:131] op_sel_hi:[1,0]
	ds_read_b128 v[122:125], v131 offset:2048
	ds_read_b128 v[132:135], v131 offset:43008
	s_waitcnt lgkmcnt(0)
	v_pk_fma_f32 v[124:125], v[124:125], v[138:139], v[134:135]
	v_pk_fma_f32 v[122:123], v[122:123], v[136:137], v[132:133]
	v_pk_mul_f32 v[132:133], v[126:127], v[130:131] op_sel_hi:[1,0]
	v_cvt_pk_bf16_f32 v122, v122, v123
	v_cvt_pk_bf16_f32 v123, v124, v125
	global_store_dwordx2 v[108:109], v[122:123], off offset:1024
	v_pk_mul_f32 v[134:135], v[128:129], v[130:131] op_sel_hi:[1,0]
	ds_read_b128 v[122:125], v131 offset:3072
	ds_read_b128 v[126:129], v131 offset:44032
	s_waitcnt lgkmcnt(0)
	v_pk_fma_f32 v[124:125], v[134:135], v[124:125], v[128:129]
	v_pk_fma_f32 v[122:123], v[132:133], v[122:123], v[126:127]
	v_pk_mul_f32 v[126:127], v[116:117], v[130:131] op_sel_hi:[1,0]
	v_cvt_pk_bf16_f32 v122, v122, v123
	v_cvt_pk_bf16_f32 v123, v124, v125
	global_store_dwordx2 v[108:109], v[122:123], off offset:1536
	v_pk_mul_f32 v[128:129], v[118:119], v[130:131] op_sel_hi:[1,0]
	ds_read_b128 v[116:119], v131 offset:4096
	ds_read_b128 v[122:125], v131 offset:45056
	s_waitcnt lgkmcnt(0)
	v_pk_fma_f32 v[118:119], v[128:129], v[118:119], v[124:125]
	v_pk_fma_f32 v[116:117], v[126:127], v[116:117], v[122:123]
	v_pk_mul_f32 v[122:123], v[114:115], v[130:131] op_sel_hi:[1,0]
	v_cvt_pk_bf16_f32 v116, v116, v117
	v_cvt_pk_bf16_f32 v117, v118, v119
	global_store_dwordx2 v[108:109], v[116:117], off offset:2048
	v_pk_mul_f32 v[124:125], v[120:121], v[130:131] op_sel_hi:[1,0]
	ds_read_b128 v[114:117], v131 offset:5120
	ds_read_b128 v[118:121], v131 offset:46080
	s_waitcnt lgkmcnt(0)
	v_pk_fma_f32 v[116:117], v[124:125], v[116:117], v[120:121]
	v_pk_fma_f32 v[114:115], v[122:123], v[114:115], v[118:119]
	v_pk_mul_f32 v[120:121], v[112:113], v[130:131] op_sel_hi:[1,0]
	v_cvt_pk_bf16_f32 v114, v114, v115
	v_cvt_pk_bf16_f32 v115, v116, v117
	global_store_dwordx2 v[108:109], v[114:115], off offset:2560
	ds_read_b128 v[112:115], v131 offset:6144
	ds_read_b128 v[116:119], v131 offset:47104
	s_waitcnt vmcnt(61)
	v_cvt_f32_f16_sdwa v123, v107 dst_sel:DWORD dst_unused:UNUSED_PAD src0_sel:WORD_1
	v_cvt_f32_f16_e32 v122, v107
	s_waitcnt vmcnt(59)
	v_cvt_f32_f16_sdwa v107, v102 dst_sel:DWORD dst_unused:UNUSED_PAD src0_sel:WORD_1
	s_waitcnt lgkmcnt(0)
	v_pk_fma_f32 v[114:115], v[120:121], v[114:115], v[118:119]
	v_pk_fma_f32 v[4:5], v[4:5], v[112:113], v[116:117]
	v_cvt_f32_f16_sdwa v121, v106 dst_sel:DWORD dst_unused:UNUSED_PAD src0_sel:WORD_1
	v_cvt_pk_bf16_f32 v4, v4, v5
	v_cvt_pk_bf16_f32 v5, v114, v115
	global_store_dwordx2 v[108:109], v[4:5], off offset:3072
	v_pk_mul_f32 v[4:5], v[74:75], v[130:131] op_sel_hi:[1,0]
	v_pk_mul_f32 v[74:75], v[110:111], v[130:131] op_sel_hi:[1,0]
	ds_read_b128 v[110:113], v131 offset:7168
	ds_read_b128 v[114:117], v131 offset:48128
	v_cvt_f32_f16_e32 v120, v106
	v_cvt_f32_f16_sdwa v119, v105 dst_sel:DWORD dst_unused:UNUSED_PAD src0_sel:WORD_1
	v_cvt_f32_f16_e32 v118, v105
	v_cvt_f32_f16_e32 v106, v102
	s_waitcnt lgkmcnt(0)
	v_pk_fma_f32 v[74:75], v[74:75], v[112:113], v[116:117]
	v_cvt_f32_f16_sdwa v117, v104 dst_sel:DWORD dst_unused:UNUSED_PAD src0_sel:WORD_1
	v_pk_fma_f32 v[4:5], v[4:5], v[110:111], v[114:115]
	v_cvt_f32_f16_e32 v116, v104
	v_cvt_pk_bf16_f32 v4, v4, v5
	v_cvt_pk_bf16_f32 v5, v74, v75
	global_store_dwordx2 v[108:109], v[4:5], off offset:3584
	v_cvt_f32_f16_sdwa v109, v103 dst_sel:DWORD dst_unused:UNUSED_PAD src0_sel:WORD_1
	s_waitcnt vmcnt(60)
	v_cvt_f32_f16_sdwa v111, v100 dst_sel:DWORD dst_unused:UNUSED_PAD src0_sel:WORD_1
	v_mov_b32_e32 v74, v121
	v_mov_b32_e32 v75, v117
	v_cvt_f32_f16_e32 v108, v103
	v_cvt_f32_f16_e32 v110, v100
	v_cvt_f32_f16_sdwa v113, v101 dst_sel:DWORD dst_unused:UNUSED_PAD src0_sel:WORD_1
	v_mov_b32_e32 v4, v120
	v_mov_b32_e32 v5, v116
	v_pk_mul_f32 v[74:75], v[74:75], v[74:75]
	v_mov_b32_e32 v104, v123
	v_mov_b32_e32 v105, v119
	v_cvt_f32_f16_e32 v112, v101
	v_pk_fma_f32 v[4:5], v[4:5], v[4:5], v[74:75]
	v_mov_b32_e32 v74, v122
	v_mov_b32_e32 v75, v118
	v_pk_mul_f32 v[104:105], v[104:105], v[104:105]
	v_mov_b32_e32 v102, v107
	v_pk_fma_f32 v[74:75], v[74:75], v[74:75], v[104:105]
	v_mov_b32_e32 v103, v109
	v_mul_f32_e32 v100, v111, v111
	v_pk_add_f32 v[4:5], v[4:5], v[74:75]
	v_mov_b32_e32 v74, v106
	v_mov_b32_e32 v75, v108
	v_pk_mul_f32 v[102:103], v[102:103], v[102:103]
	v_pk_fma_f32 v[104:105], v[110:111], v[110:111], v[100:101] op_sel_hi:[1,1,0]
	v_mul_f32_e32 v100, v113, v113
	v_pk_fma_f32 v[74:75], v[74:75], v[74:75], v[102:103]
	v_pk_fma_f32 v[114:115], v[112:113], v[112:113], v[100:101] op_sel_hi:[1,1,0]
	s_waitcnt vmcnt(59)
; __device__ __forceinline__ void norm_mod_phase2(const Args& a, Frame& F, const float* gain, const float* modl, int sh_off, int sc_off, int nrows, const float* slab_gate) {
;     ...
;     NR_FINISH(r2, nw + 2 * 2048, (nw + 2 * 2048) >> 12);
	v_cvt_f32_f16_sdwa v101, v98 dst_sel:DWORD dst_unused:UNUSED_PAD src0_sel:WORD_1
	v_cvt_f32_f16_e32 v100, v98
	v_cvt_f32_f16_sdwa v103, v99 dst_sel:DWORD dst_unused:UNUSED_PAD src0_sel:WORD_1
	v_cvt_f32_f16_e32 v102, v99
	v_pk_add_f32 v[4:5], v[4:5], v[4:5] op_sel:[0,1] op_sel_hi:[1,0]
	v_pk_add_f32 v[74:75], v[74:75], v[74:75] op_sel:[0,1] op_sel_hi:[1,0]
	v_pk_mul_f32 v[98:99], v[100:101], v[100:101]
	v_pk_mul_f32 v[124:125], v[102:103], v[102:103]
	v_mov_b32_e32 v5, v98
	v_mov_b32_e32 v75, v99
	v_mov_b32_e32 v105, v124
	v_mov_b32_e32 v115, v125
	v_pk_add_f32 v[4:5], v[4:5], v[74:75]
	v_pk_add_f32 v[74:75], v[104:105], v[114:115]
	s_waitcnt vmcnt(58)
	v_cvt_f32_f16_sdwa v99, v96 dst_sel:DWORD dst_unused:UNUSED_PAD src0_sel:WORD_1
	v_cvt_f32_f16_sdwa v105, v97 dst_sel:DWORD dst_unused:UNUSED_PAD src0_sel:WORD_1
	v_cvt_f32_f16_e32 v98, v96
	v_cvt_f32_f16_e32 v104, v97
	v_pk_add_f32 v[4:5], v[4:5], v[74:75]
	v_mov_b32_e32 v74, v99
	v_mov_b32_e32 v75, v105
	v_pk_add_f32 v[114:115], v[4:5], v[4:5] op_sel:[0,1] op_sel_hi:[1,0]
	v_mov_b32_e32 v4, v98
	v_mov_b32_e32 v5, v104
	v_pk_mul_f32 v[74:75], v[74:75], v[74:75]
	s_waitcnt vmcnt(57)
	v_cvt_f32_f16_sdwa v97, v95 dst_sel:DWORD dst_unused:UNUSED_PAD src0_sel:WORD_1
	v_pk_fma_f32 v[4:5], v[4:5], v[4:5], v[74:75]
	v_cvt_f32_f16_e32 v96, v95
	v_pk_add_f32 v[124:125], v[4:5], v[4:5] op_sel:[0,1] op_sel_hi:[1,0]
	v_cvt_f32_f16_sdwa v5, v94 dst_sel:DWORD dst_unused:UNUSED_PAD src0_sel:WORD_1
	v_cvt_f32_f16_e32 v4, v94
	s_waitcnt vmcnt(56)
	v_cvt_f32_f16_sdwa v95, v93 dst_sel:DWORD dst_unused:UNUSED_PAD src0_sel:WORD_1
	v_cvt_f32_f16_e32 v94, v93
	v_mul_f32_e32 v74, v5, v5
	v_pk_fma_f32 v[126:127], v[4:5], v[4:5], v[74:75] op_sel_hi:[1,1,0]
	v_mul_f32_e32 v74, v97, v97
	v_pk_fma_f32 v[128:129], v[96:97], v[96:97], v[74:75] op_sel_hi:[1,1,0]
	v_cvt_f32_f16_sdwa v75, v92 dst_sel:DWORD dst_unused:UNUSED_PAD src0_sel:WORD_1
	v_cvt_f32_f16_e32 v74, v92
	v_pk_mul_f32 v[130:131], v[94:95], v[94:95]
	v_pk_mul_f32 v[92:93], v[74:75], v[74:75]
	s_nop 0
	v_mov_b32_e32 v115, v92
	v_mov_b32_e32 v125, v93
	v_mov_b32_e32 v127, v130
	v_mov_b32_e32 v129, v131
	v_pk_add_f32 v[92:93], v[114:115], v[124:125]
	v_pk_add_f32 v[114:115], v[126:127], v[128:129]
	s_nop 0
	v_pk_add_f32 v[92:93], v[92:93], v[114:115]
	s_nop 0
	v_add_f32_e32 v92, v92, v93
	s_nop 1
	v_add_f32_dpp v92, v92, v92 quad_perm:[1,0,3,2] row_mask:0xf bank_mask:0xf bound_ctrl:1
	s_nop 1
	v_add_f32_dpp v92, v92, v92 quad_perm:[2,3,0,1] row_mask:0xf bank_mask:0xf bound_ctrl:1
	s_nop 1
	v_add_f32_dpp v92, v92, v92 row_half_mirror row_mask:0xf bank_mask:0xf bound_ctrl:1
	s_nop 1
	v_add_f32_dpp v92, v92, v92 row_mirror row_mask:0xf bank_mask:0xf bound_ctrl:1
	s_nop 0
	v_readlane_b32 s8, v92, 16
	v_readlane_b32 s9, v92, 48
	v_readlane_b32 s6, v92, 0
	v_readlane_b32 s7, v92, 32
	v_mov_b32_e32 v92, s8
	v_mov_b32_e32 v93, s9
	v_pk_add_f32 v[92:93], s[6:7], v[92:93]
	s_nop 0
	v_add_f32_e32 v92, v92, v93
	v_fmamk_f32 v92, v92, 0x3a000000, v252
	v_cmp_gt_f32_e32 vcc, s55, v92
	v_mul_f32_e32 v93, 0x4f800000, v92
	s_nop 0
	v_cndmask_b32_e32 v92, v92, v93, vcc
	v_sqrt_f32_e32 v93, v92
	s_nop 0
	v_add_u32_e32 v114, -1, v93
	v_fma_f32 v115, -v114, v93, v92
	v_cmp_ge_f32_e64 s[8:9], 0, v115
	v_add_u32_e32 v115, 1, v93
	s_nop 0
	v_cndmask_b32_e64 v114, v93, v114, s[8:9]
	v_fma_f32 v93, -v115, v93, v92
	v_cmp_lt_f32_e64 s[8:9], 0, v93
	s_nop 1
	v_cndmask_b32_e64 v93, v114, v115, s[8:9]
	v_mul_f32_e32 v114, 0x37800000, v93
	v_cndmask_b32_e32 v93, v93, v114, vcc
	v_cmp_class_f32_e32 vcc, v92, v253
	s_nop 1
	v_cndmask_b32_e32 v92, v93, v92, vcc
	v_div_scale_f32 v93, s[6:7], v92, v92, 1.0
	v_rcp_f32_e32 v114, v93
	s_lshl_b32 s6, s36, 1
	s_and_b32 s6, s6, 0xffffe000
	s_add_i32 s6, s6, 0
	v_fma_f32 v115, -v93, v114, 1.0
	v_fmac_f32_e32 v114, v115, v114
	v_div_scale_f32 v115, vcc, 1.0, v92, 1.0
	v_mul_f32_e32 v124, v115, v114
	v_fma_f32 v125, -v93, v124, v115
	v_fmac_f32_e32 v124, v125, v114
	v_fma_f32 v93, -v93, v124, v115
	v_div_fmas_f32 v93, v93, v114, v124
	v_div_fixup_f32 v114, v93, v92, 1.0
	v_pk_mul_f32 v[128:129], v[120:121], v[114:115] op_sel_hi:[1,0]
	v_pk_mul_f32 v[130:131], v[122:123], v[114:115] op_sel_hi:[1,0]
	v_add_u32_e32 v115, s6, v0
	ds_read_b128 v[120:123], v115
	ds_read_b128 v[124:127], v115 offset:40960
	v_lshl_add_u64 v[92:93], s[40:41], 1, v[2:3]
	v_lshl_add_u64 v[92:93], v[92:93], 0, v[6:7]
	v_pk_mul_f32 v[4:5], v[4:5], v[114:115] op_sel_hi:[1,0]
	s_waitcnt lgkmcnt(0)
	v_pk_fma_f32 v[122:123], v[122:123], v[130:131], v[126:127]
	v_pk_fma_f32 v[120:121], v[120:121], v[128:129], v[124:125]
	v_pk_mul_f32 v[124:125], v[116:117], v[114:115] op_sel_hi:[1,0]
	v_cvt_pk_bf16_f32 v120, v120, v121
	v_cvt_pk_bf16_f32 v121, v122, v123
	global_store_dwordx2 v[92:93], v[120:121], off
	v_pk_mul_f32 v[126:127], v[118:119], v[114:115] op_sel_hi:[1,0]
	ds_read_b128 v[116:119], v115 offset:1024
	ds_read_b128 v[120:123], v115 offset:41984
	s_waitcnt lgkmcnt(0)
	v_pk_fma_f32 v[118:119], v[118:119], v[126:127], v[122:123]
	v_pk_fma_f32 v[116:117], v[116:117], v[124:125], v[120:121]
	v_pk_mul_f32 v[120:121], v[106:107], v[114:115] op_sel_hi:[1,0]
	v_cvt_pk_bf16_f32 v116, v116, v117
	v_cvt_pk_bf16_f32 v117, v118, v119
	global_store_dwordx2 v[92:93], v[116:117], off offset:512
	v_pk_mul_f32 v[122:123], v[108:109], v[114:115] op_sel_hi:[1,0]
	ds_read_b128 v[106:109], v115 offset:2048
	ds_read_b128 v[116:119], v115 offset:43008
	s_waitcnt lgkmcnt(0)
	v_pk_fma_f32 v[108:109], v[108:109], v[122:123], v[118:119]
	v_pk_fma_f32 v[106:107], v[106:107], v[120:121], v[116:117]
	v_pk_mul_f32 v[116:117], v[110:111], v[114:115] op_sel_hi:[1,0]
	v_cvt_pk_bf16_f32 v106, v106, v107
	v_cvt_pk_bf16_f32 v107, v108, v109
	global_store_dwordx2 v[92:93], v[106:107], off offset:1024
	v_pk_mul_f32 v[118:119], v[112:113], v[114:115] op_sel_hi:[1,0]
	ds_read_b128 v[106:109], v115 offset:3072
	ds_read_b128 v[110:113], v115 offset:44032
	s_waitcnt lgkmcnt(0)
	v_pk_fma_f32 v[108:109], v[118:119], v[108:109], v[112:113]
	v_pk_fma_f32 v[106:107], v[116:117], v[106:107], v[110:111]
	v_pk_mul_f32 v[110:111], v[100:101], v[114:115] op_sel_hi:[1,0]
	v_cvt_pk_bf16_f32 v106, v106, v107
	v_cvt_pk_bf16_f32 v107, v108, v109
	global_store_dwordx2 v[92:93], v[106:107], off offset:1536
	v_pk_mul_f32 v[112:113], v[102:103], v[114:115] op_sel_hi:[1,0]
	ds_read_b128 v[100:103], v115 offset:4096
	ds_read_b128 v[106:109], v115 offset:45056
	s_waitcnt lgkmcnt(0)
	v_pk_fma_f32 v[102:103], v[112:113], v[102:103], v[108:109]
	v_pk_fma_f32 v[100:101], v[110:111], v[100:101], v[106:107]
	v_pk_mul_f32 v[106:107], v[98:99], v[114:115] op_sel_hi:[1,0]
	v_cvt_pk_bf16_f32 v100, v100, v101
	v_cvt_pk_bf16_f32 v101, v102, v103
	global_store_dwordx2 v[92:93], v[100:101], off offset:2048
	v_pk_mul_f32 v[108:109], v[104:105], v[114:115] op_sel_hi:[1,0]
	ds_read_b128 v[98:101], v115 offset:5120
	ds_read_b128 v[102:105], v115 offset:46080
	s_waitcnt lgkmcnt(0)
	v_pk_fma_f32 v[100:101], v[108:109], v[100:101], v[104:105]
	v_pk_fma_f32 v[98:99], v[106:107], v[98:99], v[102:103]
	v_pk_mul_f32 v[104:105], v[96:97], v[114:115] op_sel_hi:[1,0]
	v_cvt_pk_bf16_f32 v98, v98, v99
	v_cvt_pk_bf16_f32 v99, v100, v101
	global_store_dwordx2 v[92:93], v[98:99], off offset:2560
	ds_read_b128 v[96:99], v115 offset:6144
	ds_read_b128 v[100:103], v115 offset:47104
	s_waitcnt vmcnt(61)
	v_cvt_f32_f16_sdwa v107, v91 dst_sel:DWORD dst_unused:UNUSED_PAD src0_sel:WORD_1
	v_cvt_f32_f16_e32 v106, v91
	s_waitcnt vmcnt(59)
	v_cvt_f32_f16_sdwa v91, v86 dst_sel:DWORD dst_unused:UNUSED_PAD src0_sel:WORD_1
	s_waitcnt lgkmcnt(0)
	v_pk_fma_f32 v[98:99], v[104:105], v[98:99], v[102:103]
	v_pk_fma_f32 v[4:5], v[4:5], v[96:97], v[100:101]
	v_cvt_f32_f16_sdwa v105, v90 dst_sel:DWORD dst_unused:UNUSED_PAD src0_sel:WORD_1
	v_cvt_pk_bf16_f32 v4, v4, v5
	v_cvt_pk_bf16_f32 v5, v98, v99
	global_store_dwordx2 v[92:93], v[4:5], off offset:3072
	v_pk_mul_f32 v[4:5], v[74:75], v[114:115] op_sel_hi:[1,0]
	v_pk_mul_f32 v[74:75], v[94:95], v[114:115] op_sel_hi:[1,0]
	ds_read_b128 v[94:97], v115 offset:7168
	ds_read_b128 v[98:101], v115 offset:48128
	v_cvt_f32_f16_e32 v104, v90
	v_cvt_f32_f16_sdwa v103, v89 dst_sel:DWORD dst_unused:UNUSED_PAD src0_sel:WORD_1
	v_cvt_f32_f16_e32 v102, v89
	v_cvt_f32_f16_e32 v90, v86
	s_waitcnt lgkmcnt(0)
	v_pk_fma_f32 v[74:75], v[74:75], v[96:97], v[100:101]
	v_cvt_f32_f16_sdwa v101, v88 dst_sel:DWORD dst_unused:UNUSED_PAD src0_sel:WORD_1
	v_pk_fma_f32 v[4:5], v[4:5], v[94:95], v[98:99]
	v_cvt_f32_f16_e32 v100, v88
	v_cvt_pk_bf16_f32 v4, v4, v5
	v_cvt_pk_bf16_f32 v5, v74, v75
	global_store_dwordx2 v[92:93], v[4:5], off offset:3584
	v_cvt_f32_f16_sdwa v93, v87 dst_sel:DWORD dst_unused:UNUSED_PAD src0_sel:WORD_1
	s_waitcnt vmcnt(60)
	v_cvt_f32_f16_sdwa v95, v84 dst_sel:DWORD dst_unused:UNUSED_PAD src0_sel:WORD_1
	v_mov_b32_e32 v74, v105
	v_mov_b32_e32 v75, v101
	v_cvt_f32_f16_e32 v92, v87
	v_cvt_f32_f16_e32 v94, v84
	v_cvt_f32_f16_sdwa v97, v85 dst_sel:DWORD dst_unused:UNUSED_PAD src0_sel:WORD_1
	v_mov_b32_e32 v4, v104
	v_mov_b32_e32 v5, v100
	v_pk_mul_f32 v[74:75], v[74:75], v[74:75]
	v_mov_b32_e32 v88, v107
	v_mov_b32_e32 v89, v103
	v_cvt_f32_f16_e32 v96, v85
	v_pk_fma_f32 v[4:5], v[4:5], v[4:5], v[74:75]
	v_mov_b32_e32 v74, v106
	v_mov_b32_e32 v75, v102
	v_pk_mul_f32 v[88:89], v[88:89], v[88:89]
	v_mov_b32_e32 v86, v91
	v_pk_fma_f32 v[74:75], v[74:75], v[74:75], v[88:89]
	v_mov_b32_e32 v87, v93
	v_mul_f32_e32 v84, v95, v95
	v_pk_add_f32 v[4:5], v[4:5], v[74:75]
	v_mov_b32_e32 v74, v90
	v_mov_b32_e32 v75, v92
	v_pk_mul_f32 v[86:87], v[86:87], v[86:87]
	v_pk_fma_f32 v[88:89], v[94:95], v[94:95], v[84:85] op_sel_hi:[1,1,0]
	v_mul_f32_e32 v84, v97, v97
	v_pk_fma_f32 v[74:75], v[74:75], v[74:75], v[86:87]
	v_pk_fma_f32 v[98:99], v[96:97], v[96:97], v[84:85] op_sel_hi:[1,1,0]
	s_waitcnt vmcnt(59)
	v_cvt_f32_f16_sdwa v85, v82 dst_sel:DWORD dst_unused:UNUSED_PAD src0_sel:WORD_1
	v_cvt_f32_f16_e32 v84, v82
	v_cvt_f32_f16_sdwa v87, v83 dst_sel:DWORD dst_unused:UNUSED_PAD src0_sel:WORD_1
	v_cvt_f32_f16_e32 v86, v83
	v_pk_add_f32 v[4:5], v[4:5], v[4:5] op_sel:[0,1] op_sel_hi:[1,0]
	v_pk_add_f32 v[74:75], v[74:75], v[74:75] op_sel:[0,1] op_sel_hi:[1,0]
	v_pk_mul_f32 v[82:83], v[84:85], v[84:85]
	v_pk_mul_f32 v[108:109], v[86:87], v[86:87]
	v_mov_b32_e32 v5, v82
	v_mov_b32_e32 v75, v83
	v_mov_b32_e32 v89, v108
	v_mov_b32_e32 v99, v109
	v_pk_add_f32 v[4:5], v[4:5], v[74:75]
	v_pk_add_f32 v[74:75], v[88:89], v[98:99]
	s_waitcnt vmcnt(58)
	v_cvt_f32_f16_sdwa v83, v80 dst_sel:DWORD dst_unused:UNUSED_PAD src0_sel:WORD_1
	v_cvt_f32_f16_sdwa v89, v81 dst_sel:DWORD dst_unused:UNUSED_PAD src0_sel:WORD_1
	v_cvt_f32_f16_e32 v82, v80
	v_cvt_f32_f16_e32 v88, v81
	v_pk_add_f32 v[4:5], v[4:5], v[74:75]
	v_mov_b32_e32 v74, v83
	v_mov_b32_e32 v75, v89
	v_pk_add_f32 v[98:99], v[4:5], v[4:5] op_sel:[0,1] op_sel_hi:[1,0]
	v_mov_b32_e32 v4, v82
	v_mov_b32_e32 v5, v88
	v_pk_mul_f32 v[74:75], v[74:75], v[74:75]
	s_waitcnt vmcnt(57)
; __device__ __forceinline__ void norm_mod_phase2(const Args& a, Frame& F, const float* gain, const float* modl, int sh_off, int sc_off, int nrows, const float* slab_gate) {
;     ...
;     NR_FINISH(r3, nw + 3 * 2048, (nw + 3 * 2048) >> 12);
	v_cvt_f32_f16_sdwa v81, v79 dst_sel:DWORD dst_unused:UNUSED_PAD src0_sel:WORD_1
	v_pk_fma_f32 v[4:5], v[4:5], v[4:5], v[74:75]
	v_cvt_f32_f16_e32 v80, v79
	v_pk_add_f32 v[108:109], v[4:5], v[4:5] op_sel:[0,1] op_sel_hi:[1,0]
	v_cvt_f32_f16_sdwa v5, v78 dst_sel:DWORD dst_unused:UNUSED_PAD src0_sel:WORD_1
	v_cvt_f32_f16_e32 v4, v78
	s_waitcnt vmcnt(56)
	v_cvt_f32_f16_sdwa v79, v77 dst_sel:DWORD dst_unused:UNUSED_PAD src0_sel:WORD_1
	v_cvt_f32_f16_e32 v78, v77
	v_mul_f32_e32 v74, v5, v5
	v_pk_fma_f32 v[110:111], v[4:5], v[4:5], v[74:75] op_sel_hi:[1,1,0]
	v_mul_f32_e32 v74, v81, v81
	v_pk_fma_f32 v[112:113], v[80:81], v[80:81], v[74:75] op_sel_hi:[1,1,0]
	v_cvt_f32_f16_sdwa v75, v76 dst_sel:DWORD dst_unused:UNUSED_PAD src0_sel:WORD_1
	v_cvt_f32_f16_e32 v74, v76
	v_pk_mul_f32 v[114:115], v[78:79], v[78:79]
	v_pk_mul_f32 v[76:77], v[74:75], v[74:75]
	s_nop 0
	v_mov_b32_e32 v99, v76
	v_mov_b32_e32 v109, v77
	v_mov_b32_e32 v111, v114
	v_mov_b32_e32 v113, v115
	v_pk_add_f32 v[76:77], v[98:99], v[108:109]
	v_pk_add_f32 v[98:99], v[110:111], v[112:113]
	s_nop 0
	v_pk_add_f32 v[76:77], v[76:77], v[98:99]
	s_nop 0
	v_add_f32_e32 v76, v76, v77
	s_nop 1
	v_add_f32_dpp v76, v76, v76 quad_perm:[1,0,3,2] row_mask:0xf bank_mask:0xf bound_ctrl:1
	s_nop 1
	v_add_f32_dpp v76, v76, v76 quad_perm:[2,3,0,1] row_mask:0xf bank_mask:0xf bound_ctrl:1
	s_nop 1
	v_add_f32_dpp v76, v76, v76 row_half_mirror row_mask:0xf bank_mask:0xf bound_ctrl:1
	s_nop 1
	v_add_f32_dpp v76, v76, v76 row_mirror row_mask:0xf bank_mask:0xf bound_ctrl:1
	s_nop 0
	v_readlane_b32 s8, v76, 16
	v_readlane_b32 s9, v76, 48
	v_readlane_b32 s6, v76, 0
	v_readlane_b32 s7, v76, 32
	v_mov_b32_e32 v76, s8
	v_mov_b32_e32 v77, s9
	v_pk_add_f32 v[76:77], s[6:7], v[76:77]
	s_nop 0
	v_add_f32_e32 v76, v76, v77
	v_fmamk_f32 v76, v76, 0x3a000000, v252
	v_cmp_gt_f32_e32 vcc, s55, v76
	v_mul_f32_e32 v77, 0x4f800000, v76
	s_nop 0
	v_cndmask_b32_e32 v76, v76, v77, vcc
	v_sqrt_f32_e32 v77, v76
	s_nop 0
	v_add_u32_e32 v98, -1, v77
	v_fma_f32 v99, -v98, v77, v76
	v_cmp_ge_f32_e64 s[8:9], 0, v99
	v_add_u32_e32 v99, 1, v77
	s_nop 0
	v_cndmask_b32_e64 v98, v77, v98, s[8:9]
	v_fma_f32 v77, -v99, v77, v76
	v_cmp_lt_f32_e64 s[8:9], 0, v77
	s_nop 1
	v_cndmask_b32_e64 v77, v98, v99, s[8:9]
	v_mul_f32_e32 v98, 0x37800000, v77
	v_cndmask_b32_e32 v77, v77, v98, vcc
	v_cmp_class_f32_e32 vcc, v76, v253
	s_nop 1
	v_cndmask_b32_e32 v76, v77, v76, vcc
	v_div_scale_f32 v77, s[6:7], v76, v76, 1.0
	v_rcp_f32_e32 v98, v77
	s_lshl_b32 s6, s30, 1
	s_and_b32 s6, s6, 0xffffe000
	s_add_i32 s6, s6, 0
	v_fma_f32 v99, -v77, v98, 1.0
	v_fmac_f32_e32 v98, v99, v98
	v_div_scale_f32 v99, vcc, 1.0, v76, 1.0
	v_mul_f32_e32 v108, v99, v98
	v_fma_f32 v109, -v77, v108, v99
	v_fmac_f32_e32 v108, v109, v98
	v_fma_f32 v77, -v77, v108, v99
	v_div_fmas_f32 v77, v77, v98, v108
	v_div_fixup_f32 v98, v77, v76, 1.0
	v_pk_mul_f32 v[112:113], v[104:105], v[98:99] op_sel_hi:[1,0]
	v_pk_mul_f32 v[114:115], v[106:107], v[98:99] op_sel_hi:[1,0]
	v_add_u32_e32 v99, s6, v0
	ds_read_b128 v[104:107], v99
	ds_read_b128 v[108:111], v99 offset:40960
	v_lshl_add_u64 v[76:77], s[34:35], 1, v[2:3]
	v_lshl_add_u64 v[76:77], v[76:77], 0, v[6:7]
	v_pk_mul_f32 v[4:5], v[4:5], v[98:99] op_sel_hi:[1,0]
	s_waitcnt lgkmcnt(0)
	v_pk_fma_f32 v[106:107], v[106:107], v[114:115], v[110:111]
	v_pk_fma_f32 v[104:105], v[104:105], v[112:113], v[108:109]
	v_pk_mul_f32 v[108:109], v[100:101], v[98:99] op_sel_hi:[1,0]
	v_cvt_pk_bf16_f32 v104, v104, v105
	v_cvt_pk_bf16_f32 v105, v106, v107
	global_store_dwordx2 v[76:77], v[104:105], off
	v_pk_mul_f32 v[110:111], v[102:103], v[98:99] op_sel_hi:[1,0]
	ds_read_b128 v[100:103], v99 offset:1024
	ds_read_b128 v[104:107], v99 offset:41984
	s_waitcnt lgkmcnt(0)
	v_pk_fma_f32 v[102:103], v[102:103], v[110:111], v[106:107]
	v_pk_fma_f32 v[100:101], v[100:101], v[108:109], v[104:105]
	v_pk_mul_f32 v[104:105], v[90:91], v[98:99] op_sel_hi:[1,0]
	v_cvt_pk_bf16_f32 v100, v100, v101
	v_cvt_pk_bf16_f32 v101, v102, v103
	global_store_dwordx2 v[76:77], v[100:101], off offset:512
	v_pk_mul_f32 v[106:107], v[92:93], v[98:99] op_sel_hi:[1,0]
	ds_read_b128 v[90:93], v99 offset:2048
	ds_read_b128 v[100:103], v99 offset:43008
	s_waitcnt lgkmcnt(0)
	v_pk_fma_f32 v[92:93], v[92:93], v[106:107], v[102:103]
	v_pk_fma_f32 v[90:91], v[90:91], v[104:105], v[100:101]
	v_pk_mul_f32 v[100:101], v[94:95], v[98:99] op_sel_hi:[1,0]
	v_cvt_pk_bf16_f32 v90, v90, v91
	v_cvt_pk_bf16_f32 v91, v92, v93
	global_store_dwordx2 v[76:77], v[90:91], off offset:1024
	v_pk_mul_f32 v[102:103], v[96:97], v[98:99] op_sel_hi:[1,0]
	ds_read_b128 v[90:93], v99 offset:3072
	ds_read_b128 v[94:97], v99 offset:44032
	s_waitcnt lgkmcnt(0)
	v_pk_fma_f32 v[92:93], v[102:103], v[92:93], v[96:97]
	v_pk_fma_f32 v[90:91], v[100:101], v[90:91], v[94:95]
	v_pk_mul_f32 v[94:95], v[84:85], v[98:99] op_sel_hi:[1,0]
	v_cvt_pk_bf16_f32 v90, v90, v91
	v_cvt_pk_bf16_f32 v91, v92, v93
	global_store_dwordx2 v[76:77], v[90:91], off offset:1536
	v_pk_mul_f32 v[96:97], v[86:87], v[98:99] op_sel_hi:[1,0]
	ds_read_b128 v[84:87], v99 offset:4096
	ds_read_b128 v[90:93], v99 offset:45056
	s_waitcnt lgkmcnt(0)
	v_pk_fma_f32 v[86:87], v[96:97], v[86:87], v[92:93]
	v_pk_fma_f32 v[84:85], v[94:95], v[84:85], v[90:91]
	v_pk_mul_f32 v[90:91], v[82:83], v[98:99] op_sel_hi:[1,0]
	v_cvt_pk_bf16_f32 v84, v84, v85
	v_cvt_pk_bf16_f32 v85, v86, v87
	global_store_dwordx2 v[76:77], v[84:85], off offset:2048
	v_pk_mul_f32 v[92:93], v[88:89], v[98:99] op_sel_hi:[1,0]
	ds_read_b128 v[82:85], v99 offset:5120
	ds_read_b128 v[86:89], v99 offset:46080
	s_waitcnt lgkmcnt(0)
; __device__ __forceinline__ void norm_mod_phase2(const Args& a, Frame& F, const float* gain, const float* modl, int sh_off, int sc_off, int nrows, const float* slab_gate) {
;     ...
;     NR_FINISH(r4, nw + 4 * 2048, (nw + 4 * 2048) >> 12);
	v_pk_fma_f32 v[84:85], v[92:93], v[84:85], v[88:89]
	v_pk_fma_f32 v[82:83], v[90:91], v[82:83], v[86:87]
	v_pk_mul_f32 v[88:89], v[80:81], v[98:99] op_sel_hi:[1,0]
	v_cvt_pk_bf16_f32 v82, v82, v83
	v_cvt_pk_bf16_f32 v83, v84, v85
	global_store_dwordx2 v[76:77], v[82:83], off offset:2560
	ds_read_b128 v[80:83], v99 offset:6144
	ds_read_b128 v[84:87], v99 offset:47104
	s_waitcnt vmcnt(61)
	v_cvt_f32_f16_sdwa v91, v73 dst_sel:DWORD dst_unused:UNUSED_PAD src0_sel:WORD_1
	v_cvt_f32_f16_e32 v90, v73
	s_waitcnt lgkmcnt(0)
	v_pk_fma_f32 v[82:83], v[88:89], v[82:83], v[86:87]
	v_pk_fma_f32 v[4:5], v[4:5], v[80:81], v[84:85]
	v_cvt_f32_f16_sdwa v89, v72 dst_sel:DWORD dst_unused:UNUSED_PAD src0_sel:WORD_1
	v_cvt_pk_bf16_f32 v4, v4, v5
	v_cvt_pk_bf16_f32 v5, v82, v83
	global_store_dwordx2 v[76:77], v[4:5], off offset:3072
	v_pk_mul_f32 v[4:5], v[74:75], v[98:99] op_sel_hi:[1,0]
	v_pk_mul_f32 v[74:75], v[78:79], v[98:99] op_sel_hi:[1,0]
	ds_read_b128 v[78:81], v99 offset:7168
	ds_read_b128 v[82:85], v99 offset:48128
	v_cvt_f32_f16_e32 v88, v72
	s_waitcnt vmcnt(61)
	v_cvt_f32_f16_sdwa v87, v71 dst_sel:DWORD dst_unused:UNUSED_PAD src0_sel:WORD_1
	v_cvt_f32_f16_e32 v86, v71
	v_mov_b32_e32 v72, v91
	s_waitcnt lgkmcnt(0)
	v_pk_fma_f32 v[74:75], v[74:75], v[80:81], v[84:85]
	v_cvt_f32_f16_sdwa v85, v70 dst_sel:DWORD dst_unused:UNUSED_PAD src0_sel:WORD_1
	v_cvt_f32_f16_e32 v84, v70
	v_pk_fma_f32 v[4:5], v[4:5], v[78:79], v[82:83]
	v_mov_b32_e32 v70, v89
	v_cvt_pk_bf16_f32 v4, v4, v5
	v_cvt_pk_bf16_f32 v5, v74, v75
	global_store_dwordx2 v[76:77], v[4:5], off offset:3584
	v_mov_b32_e32 v71, v85
	s_waitcnt vmcnt(61)
	v_cvt_f32_f16_sdwa v75, v68 dst_sel:DWORD dst_unused:UNUSED_PAD src0_sel:WORD_1
	v_cvt_f32_f16_sdwa v77, v69 dst_sel:DWORD dst_unused:UNUSED_PAD src0_sel:WORD_1
	v_mov_b32_e32 v4, v88
	v_mov_b32_e32 v5, v84
	v_pk_mul_f32 v[70:71], v[70:71], v[70:71]
	v_mov_b32_e32 v73, v87
	v_cvt_f32_f16_e32 v74, v68
	v_cvt_f32_f16_e32 v76, v69
	s_waitcnt vmcnt(60)
	v_cvt_f32_f16_sdwa v79, v66 dst_sel:DWORD dst_unused:UNUSED_PAD src0_sel:WORD_1
	v_pk_fma_f32 v[4:5], v[4:5], v[4:5], v[70:71]
	v_mov_b32_e32 v70, v90
	v_mov_b32_e32 v71, v86
	v_pk_mul_f32 v[72:73], v[72:73], v[72:73]
	v_cvt_f32_f16_e32 v78, v66
	v_cvt_f32_f16_sdwa v81, v67 dst_sel:DWORD dst_unused:UNUSED_PAD src0_sel:WORD_1
	v_pk_fma_f32 v[70:71], v[70:71], v[70:71], v[72:73]
	v_cvt_f32_f16_e32 v80, v67
	v_pk_add_f32 v[4:5], v[4:5], v[70:71]
	v_mov_b32_e32 v70, v75
	v_mov_b32_e32 v71, v77
	v_mov_b32_e32 v68, v74
	v_mov_b32_e32 v69, v76
	v_pk_mul_f32 v[70:71], v[70:71], v[70:71]
	v_mul_f32_e32 v66, v79, v79
	v_pk_fma_f32 v[68:69], v[68:69], v[68:69], v[70:71]
	v_pk_fma_f32 v[72:73], v[78:79], v[78:79], v[66:67] op_sel_hi:[1,1,0]
	v_mul_f32_e32 v66, v81, v81
	v_pk_add_f32 v[70:71], v[68:69], v[68:69] op_sel:[0,1] op_sel_hi:[1,0]
	v_pk_fma_f32 v[82:83], v[80:81], v[80:81], v[66:67] op_sel_hi:[1,1,0]
	s_waitcnt vmcnt(59)
	v_cvt_f32_f16_sdwa v67, v64 dst_sel:DWORD dst_unused:UNUSED_PAD src0_sel:WORD_1
	v_cvt_f32_f16_e32 v66, v64
	v_cvt_f32_f16_sdwa v69, v65 dst_sel:DWORD dst_unused:UNUSED_PAD src0_sel:WORD_1
	v_cvt_f32_f16_e32 v68, v65
	v_pk_add_f32 v[4:5], v[4:5], v[4:5] op_sel:[0,1] op_sel_hi:[1,0]
	v_pk_mul_f32 v[64:65], v[66:67], v[66:67]
	v_pk_mul_f32 v[92:93], v[68:69], v[68:69]
	v_mov_b32_e32 v5, v64
	v_mov_b32_e32 v71, v65
	v_mov_b32_e32 v73, v92
	v_mov_b32_e32 v83, v93
	v_pk_add_f32 v[4:5], v[4:5], v[70:71]
	v_pk_add_f32 v[64:65], v[72:73], v[82:83]
	s_waitcnt vmcnt(58)
	v_cvt_f32_f16_sdwa v71, v62 dst_sel:DWORD dst_unused:UNUSED_PAD src0_sel:WORD_1
	v_cvt_f32_f16_sdwa v73, v63 dst_sel:DWORD dst_unused:UNUSED_PAD src0_sel:WORD_1
	v_cvt_f32_f16_e32 v70, v62
	v_cvt_f32_f16_e32 v72, v63
	v_pk_add_f32 v[4:5], v[4:5], v[64:65]
	v_mov_b32_e32 v62, v71
	v_mov_b32_e32 v63, v73
	v_pk_add_f32 v[82:83], v[4:5], v[4:5] op_sel:[0,1] op_sel_hi:[1,0]
	v_mov_b32_e32 v4, v70
	v_mov_b32_e32 v5, v72
	v_pk_mul_f32 v[62:63], v[62:63], v[62:63]
	s_waitcnt vmcnt(56)
	v_cvt_f32_f16_sdwa v65, v59 dst_sel:DWORD dst_unused:UNUSED_PAD src0_sel:WORD_1
	v_pk_fma_f32 v[4:5], v[4:5], v[4:5], v[62:63]
	v_cvt_f32_f16_sdwa v63, v61 dst_sel:DWORD dst_unused:UNUSED_PAD src0_sel:WORD_1
	v_pk_add_f32 v[92:93], v[4:5], v[4:5] op_sel:[0,1] op_sel_hi:[1,0]
	v_cvt_f32_f16_sdwa v5, v60 dst_sel:DWORD dst_unused:UNUSED_PAD src0_sel:WORD_1
	v_cvt_f32_f16_e32 v4, v60
	v_cvt_f32_f16_e32 v62, v61
	v_cvt_f32_f16_e32 v64, v59
	v_mul_f32_e32 v60, v5, v5
	v_pk_fma_f32 v[94:95], v[4:5], v[4:5], v[60:61] op_sel_hi:[1,1,0]
	v_mul_f32_e32 v60, v63, v63
	v_pk_fma_f32 v[96:97], v[62:63], v[62:63], v[60:61] op_sel_hi:[1,1,0]
	v_cvt_f32_f16_sdwa v61, v58 dst_sel:DWORD dst_unused:UNUSED_PAD src0_sel:WORD_1
	v_cvt_f32_f16_e32 v60, v58
	v_pk_mul_f32 v[98:99], v[64:65], v[64:65]
	v_pk_mul_f32 v[58:59], v[60:61], v[60:61]
	s_nop 0
	v_mov_b32_e32 v83, v58
	v_mov_b32_e32 v93, v59
	v_mov_b32_e32 v95, v98
	v_mov_b32_e32 v97, v99
	v_pk_add_f32 v[58:59], v[82:83], v[92:93]
	v_pk_add_f32 v[82:83], v[94:95], v[96:97]
	s_nop 0
	v_pk_add_f32 v[58:59], v[58:59], v[82:83]
	s_nop 0
	v_add_f32_e32 v58, v58, v59
	s_nop 1
	v_add_f32_dpp v58, v58, v58 quad_perm:[1,0,3,2] row_mask:0xf bank_mask:0xf bound_ctrl:1
	s_nop 1
	v_add_f32_dpp v58, v58, v58 quad_perm:[2,3,0,1] row_mask:0xf bank_mask:0xf bound_ctrl:1
	s_nop 1
	v_add_f32_dpp v58, v58, v58 row_half_mirror row_mask:0xf bank_mask:0xf bound_ctrl:1
	s_nop 1
	v_add_f32_dpp v58, v58, v58 row_mirror row_mask:0xf bank_mask:0xf bound_ctrl:1
	s_nop 0
	v_readlane_b32 s8, v58, 16
	v_readlane_b32 s9, v58, 48
	v_readlane_b32 s6, v58, 0
	v_readlane_b32 s7, v58, 32
	v_mov_b32_e32 v58, s8
	v_mov_b32_e32 v59, s9
	v_pk_add_f32 v[58:59], s[6:7], v[58:59]
; __device__ __forceinline__ void norm_mod_phase2(const Args& a, Frame& F, const float* gain, const float* modl, int sh_off, int sc_off, int nrows, const float* slab_gate) {
;     ...
;     NR_FINISH(r4, nw + 4 * 2048, (nw + 4 * 2048) >> 12);
;     NR_FINISH(r5, nw + 5 * 2048, (nw + 5 * 2048) >> 12);
	s_nop 0
	v_add_f32_e32 v58, v58, v59
	v_fmamk_f32 v58, v58, 0x3a000000, v252
	v_cmp_gt_f32_e32 vcc, s55, v58
	v_mul_f32_e32 v59, 0x4f800000, v58
	s_nop 0
	v_cndmask_b32_e32 v58, v58, v59, vcc
	v_sqrt_f32_e32 v59, v58
	s_nop 0
	v_add_u32_e32 v82, -1, v59
	v_fma_f32 v83, -v82, v59, v58
	v_cmp_ge_f32_e64 s[8:9], 0, v83
	v_add_u32_e32 v83, 1, v59
	s_nop 0
	v_cndmask_b32_e64 v82, v59, v82, s[8:9]
	v_fma_f32 v59, -v83, v59, v58
	v_cmp_lt_f32_e64 s[8:9], 0, v59
	s_nop 1
	v_cndmask_b32_e64 v59, v82, v83, s[8:9]
	v_mul_f32_e32 v82, 0x37800000, v59
	v_cndmask_b32_e32 v59, v59, v82, vcc
	v_cmp_class_f32_e32 vcc, v58, v253
	s_nop 1
	v_cndmask_b32_e32 v58, v59, v58, vcc
	v_div_scale_f32 v59, s[6:7], v58, v58, 1.0
	v_rcp_f32_e32 v82, v59
	s_lshl_b32 s6, s26, 1
	s_and_b32 s6, s6, 0xffffe000
	s_add_i32 s6, s6, 0
	v_fma_f32 v83, -v59, v82, 1.0
	v_fmac_f32_e32 v82, v83, v82
	v_div_scale_f32 v83, vcc, 1.0, v58, 1.0
	v_mul_f32_e32 v92, v83, v82
	v_fma_f32 v93, -v59, v92, v83
	v_fmac_f32_e32 v92, v93, v82
	v_fma_f32 v59, -v59, v92, v83
	v_div_fmas_f32 v59, v59, v82, v92
	v_div_fixup_f32 v82, v59, v58, 1.0
	v_pk_mul_f32 v[96:97], v[88:89], v[82:83] op_sel_hi:[1,0]
	v_pk_mul_f32 v[98:99], v[90:91], v[82:83] op_sel_hi:[1,0]
	v_add_u32_e32 v83, s6, v0
	ds_read_b128 v[88:91], v83
	ds_read_b128 v[92:95], v83 offset:40960
	v_lshl_add_u64 v[58:59], s[28:29], 1, v[2:3]
	v_lshl_add_u64 v[58:59], v[58:59], 0, v[6:7]
	v_pk_mul_f32 v[4:5], v[4:5], v[82:83] op_sel_hi:[1,0]
	v_pk_mul_f32 v[62:63], v[62:63], v[82:83] op_sel_hi:[1,0]
	s_waitcnt lgkmcnt(0)
	v_pk_fma_f32 v[90:91], v[90:91], v[98:99], v[94:95]
	v_pk_fma_f32 v[88:89], v[88:89], v[96:97], v[92:93]
	v_pk_mul_f32 v[92:93], v[84:85], v[82:83] op_sel_hi:[1,0]
	v_cvt_pk_bf16_f32 v88, v88, v89
	v_cvt_pk_bf16_f32 v89, v90, v91
	global_store_dwordx2 v[58:59], v[88:89], off
	v_pk_mul_f32 v[94:95], v[86:87], v[82:83] op_sel_hi:[1,0]
	ds_read_b128 v[84:87], v83 offset:1024
	ds_read_b128 v[88:91], v83 offset:41984
	s_waitcnt lgkmcnt(0)
	v_pk_fma_f32 v[86:87], v[86:87], v[94:95], v[90:91]
	v_pk_fma_f32 v[84:85], v[84:85], v[92:93], v[88:89]
	v_pk_mul_f32 v[88:89], v[74:75], v[82:83] op_sel_hi:[1,0]
	v_cvt_pk_bf16_f32 v84, v84, v85
	v_cvt_pk_bf16_f32 v85, v86, v87
	global_store_dwordx2 v[58:59], v[84:85], off offset:512
	v_pk_mul_f32 v[90:91], v[76:77], v[82:83] op_sel_hi:[1,0]
	ds_read_b128 v[74:77], v83 offset:2048
	ds_read_b128 v[84:87], v83 offset:43008
	s_waitcnt lgkmcnt(0)
	v_pk_fma_f32 v[76:77], v[76:77], v[90:91], v[86:87]
	v_pk_fma_f32 v[74:75], v[74:75], v[88:89], v[84:85]
	v_pk_mul_f32 v[84:85], v[78:79], v[82:83] op_sel_hi:[1,0]
	v_cvt_pk_bf16_f32 v74, v74, v75
	v_cvt_pk_bf16_f32 v75, v76, v77
	global_store_dwordx2 v[58:59], v[74:75], off offset:1024
	v_pk_mul_f32 v[86:87], v[80:81], v[82:83] op_sel_hi:[1,0]
	ds_read_b128 v[74:77], v83 offset:3072
	ds_read_b128 v[78:81], v83 offset:44032
	s_waitcnt lgkmcnt(0)
	v_pk_fma_f32 v[76:77], v[86:87], v[76:77], v[80:81]
	v_pk_fma_f32 v[74:75], v[84:85], v[74:75], v[78:79]
	v_pk_mul_f32 v[78:79], v[66:67], v[82:83] op_sel_hi:[1,0]
	v_cvt_pk_bf16_f32 v74, v74, v75
	v_cvt_pk_bf16_f32 v75, v76, v77
	global_store_dwordx2 v[58:59], v[74:75], off offset:1536
	v_pk_mul_f32 v[80:81], v[68:69], v[82:83] op_sel_hi:[1,0]
	ds_read_b128 v[66:69], v83 offset:4096
	ds_read_b128 v[74:77], v83 offset:45056
	s_waitcnt lgkmcnt(0)
	v_pk_fma_f32 v[68:69], v[80:81], v[68:69], v[76:77]
	v_pk_fma_f32 v[66:67], v[78:79], v[66:67], v[74:75]
	v_pk_mul_f32 v[74:75], v[70:71], v[82:83] op_sel_hi:[1,0]
	v_cvt_pk_bf16_f32 v66, v66, v67
	v_cvt_pk_bf16_f32 v67, v68, v69
	global_store_dwordx2 v[58:59], v[66:67], off offset:2048
	v_pk_mul_f32 v[76:77], v[72:73], v[82:83] op_sel_hi:[1,0]
	ds_read_b128 v[66:69], v83 offset:5120
	ds_read_b128 v[70:73], v83 offset:46080
	s_waitcnt lgkmcnt(0)
	v_pk_fma_f32 v[68:69], v[76:77], v[68:69], v[72:73]
	v_pk_fma_f32 v[66:67], v[74:75], v[66:67], v[70:71]
	s_waitcnt vmcnt(60)
	v_cvt_f32_f16_sdwa v75, v57 dst_sel:DWORD dst_unused:UNUSED_PAD src0_sel:WORD_1
	v_cvt_pk_bf16_f32 v66, v66, v67
	v_cvt_pk_bf16_f32 v67, v68, v69
	global_store_dwordx2 v[58:59], v[66:67], off offset:2560
	ds_read_b128 v[66:69], v83 offset:6144
	ds_read_b128 v[70:73], v83 offset:47104
	v_cvt_f32_f16_e32 v74, v57
	s_waitcnt lgkmcnt(0)
	v_pk_fma_f32 v[62:63], v[62:63], v[68:69], v[72:73]
	v_pk_fma_f32 v[4:5], v[4:5], v[66:67], v[70:71]
	v_pk_mul_f32 v[68:69], v[64:65], v[82:83] op_sel_hi:[1,0]
	v_cvt_pk_bf16_f32 v4, v4, v5
	v_cvt_pk_bf16_f32 v5, v62, v63
	global_store_dwordx2 v[58:59], v[4:5], off offset:3072
	v_pk_mul_f32 v[4:5], v[60:61], v[82:83] op_sel_hi:[1,0]
	ds_read_b128 v[60:63], v83 offset:7168
	ds_read_b128 v[64:67], v83 offset:48128
	v_cvt_f32_f16_sdwa v73, v56 dst_sel:DWORD dst_unused:UNUSED_PAD src0_sel:WORD_1
	v_cvt_f32_f16_e32 v72, v56
	s_waitcnt vmcnt(61)
	v_cvt_f32_f16_sdwa v71, v55 dst_sel:DWORD dst_unused:UNUSED_PAD src0_sel:WORD_1
	v_cvt_f32_f16_e32 v70, v55
	s_waitcnt lgkmcnt(0)
	v_pk_fma_f32 v[62:63], v[68:69], v[62:63], v[66:67]
	v_cvt_f32_f16_sdwa v69, v54 dst_sel:DWORD dst_unused:UNUSED_PAD src0_sel:WORD_1
	v_cvt_f32_f16_e32 v68, v54
	v_pk_fma_f32 v[4:5], v[4:5], v[60:61], v[64:65]
	v_mov_b32_e32 v54, v73
	v_cvt_pk_bf16_f32 v4, v4, v5
	v_cvt_pk_bf16_f32 v5, v62, v63
	global_store_dwordx2 v[58:59], v[4:5], off offset:3584
	v_mov_b32_e32 v55, v69
	s_waitcnt vmcnt(61)
	v_cvt_f32_f16_sdwa v59, v52 dst_sel:DWORD dst_unused:UNUSED_PAD src0_sel:WORD_1
	v_cvt_f32_f16_sdwa v61, v53 dst_sel:DWORD dst_unused:UNUSED_PAD src0_sel:WORD_1
	v_mov_b32_e32 v4, v72
	v_mov_b32_e32 v5, v68
	v_pk_mul_f32 v[54:55], v[54:55], v[54:55]
	v_mov_b32_e32 v56, v75
	v_mov_b32_e32 v57, v71
	v_cvt_f32_f16_e32 v58, v52
	v_cvt_f32_f16_e32 v60, v53
	s_waitcnt vmcnt(60)
; __device__ __forceinline__ void norm_mod_phase2(const Args& a, Frame& F, const float* gain, const float* modl, int sh_off, int sc_off, int nrows, const float* slab_gate) {
;     ...
;     NR_FINISH(r5, nw + 5 * 2048, (nw + 5 * 2048) >> 12);
	v_cvt_f32_f16_sdwa v63, v50 dst_sel:DWORD dst_unused:UNUSED_PAD src0_sel:WORD_1
	v_pk_fma_f32 v[4:5], v[4:5], v[4:5], v[54:55]
	v_mov_b32_e32 v54, v74
	v_mov_b32_e32 v55, v70
	v_pk_mul_f32 v[56:57], v[56:57], v[56:57]
	v_cvt_f32_f16_e32 v62, v50
	v_cvt_f32_f16_sdwa v65, v51 dst_sel:DWORD dst_unused:UNUSED_PAD src0_sel:WORD_1
	v_pk_fma_f32 v[54:55], v[54:55], v[54:55], v[56:57]
	v_cvt_f32_f16_e32 v64, v51
	v_pk_add_f32 v[4:5], v[4:5], v[54:55]
	v_mov_b32_e32 v54, v59
	v_mov_b32_e32 v55, v61
	v_mov_b32_e32 v52, v58
	v_mov_b32_e32 v53, v60
	v_pk_mul_f32 v[54:55], v[54:55], v[54:55]
	v_mul_f32_e32 v50, v63, v63
	v_pk_fma_f32 v[52:53], v[52:53], v[52:53], v[54:55]
	v_pk_fma_f32 v[56:57], v[62:63], v[62:63], v[50:51] op_sel_hi:[1,1,0]
	v_mul_f32_e32 v50, v65, v65
	v_pk_add_f32 v[54:55], v[52:53], v[52:53] op_sel:[0,1] op_sel_hi:[1,0]
	v_pk_fma_f32 v[66:67], v[64:65], v[64:65], v[50:51] op_sel_hi:[1,1,0]
	s_waitcnt vmcnt(59)
	v_cvt_f32_f16_sdwa v51, v48 dst_sel:DWORD dst_unused:UNUSED_PAD src0_sel:WORD_1
	v_cvt_f32_f16_e32 v50, v48
	v_cvt_f32_f16_sdwa v53, v49 dst_sel:DWORD dst_unused:UNUSED_PAD src0_sel:WORD_1
	v_cvt_f32_f16_e32 v52, v49
	v_pk_add_f32 v[4:5], v[4:5], v[4:5] op_sel:[0,1] op_sel_hi:[1,0]
	v_pk_mul_f32 v[48:49], v[50:51], v[50:51]
	v_pk_mul_f32 v[76:77], v[52:53], v[52:53]
	v_mov_b32_e32 v5, v48
	v_mov_b32_e32 v55, v49
	v_mov_b32_e32 v57, v76
	v_mov_b32_e32 v67, v77
	v_pk_add_f32 v[4:5], v[4:5], v[54:55]
	v_pk_add_f32 v[48:49], v[56:57], v[66:67]
	s_waitcnt vmcnt(58)
	v_cvt_f32_f16_sdwa v55, v46 dst_sel:DWORD dst_unused:UNUSED_PAD src0_sel:WORD_1
	v_cvt_f32_f16_sdwa v57, v47 dst_sel:DWORD dst_unused:UNUSED_PAD src0_sel:WORD_1
	v_cvt_f32_f16_e32 v54, v46
	v_cvt_f32_f16_e32 v56, v47
	v_pk_add_f32 v[4:5], v[4:5], v[48:49]
	v_mov_b32_e32 v46, v55
	v_mov_b32_e32 v47, v57
	v_pk_add_f32 v[66:67], v[4:5], v[4:5] op_sel:[0,1] op_sel_hi:[1,0]
	v_mov_b32_e32 v4, v54
	v_mov_b32_e32 v5, v56
	v_pk_mul_f32 v[46:47], v[46:47], v[46:47]
	s_waitcnt vmcnt(56)
	v_cvt_f32_f16_sdwa v49, v43 dst_sel:DWORD dst_unused:UNUSED_PAD src0_sel:WORD_1
	v_pk_fma_f32 v[4:5], v[4:5], v[4:5], v[46:47]
	v_cvt_f32_f16_sdwa v47, v45 dst_sel:DWORD dst_unused:UNUSED_PAD src0_sel:WORD_1
	v_pk_add_f32 v[76:77], v[4:5], v[4:5] op_sel:[0,1] op_sel_hi:[1,0]
	v_cvt_f32_f16_sdwa v5, v44 dst_sel:DWORD dst_unused:UNUSED_PAD src0_sel:WORD_1
	v_cvt_f32_f16_e32 v4, v44
	v_cvt_f32_f16_e32 v46, v45
	v_cvt_f32_f16_e32 v48, v43
	v_mul_f32_e32 v44, v5, v5
	v_pk_fma_f32 v[78:79], v[4:5], v[4:5], v[44:45] op_sel_hi:[1,1,0]
	v_mul_f32_e32 v44, v47, v47
	v_pk_fma_f32 v[80:81], v[46:47], v[46:47], v[44:45] op_sel_hi:[1,1,0]
	v_cvt_f32_f16_sdwa v45, v42 dst_sel:DWORD dst_unused:UNUSED_PAD src0_sel:WORD_1
	v_cvt_f32_f16_e32 v44, v42
	v_pk_mul_f32 v[82:83], v[48:49], v[48:49]
	v_pk_mul_f32 v[42:43], v[44:45], v[44:45]
	s_nop 0
	v_mov_b32_e32 v67, v42
	v_mov_b32_e32 v77, v43
	v_mov_b32_e32 v79, v82
	v_mov_b32_e32 v81, v83
	v_pk_add_f32 v[42:43], v[66:67], v[76:77]
	v_pk_add_f32 v[66:67], v[78:79], v[80:81]
	s_nop 0
	v_pk_add_f32 v[42:43], v[42:43], v[66:67]
	s_nop 0
	v_add_f32_e32 v42, v42, v43
	s_nop 1
	v_add_f32_dpp v42, v42, v42 quad_perm:[1,0,3,2] row_mask:0xf bank_mask:0xf bound_ctrl:1
	s_nop 1
	v_add_f32_dpp v42, v42, v42 quad_perm:[2,3,0,1] row_mask:0xf bank_mask:0xf bound_ctrl:1
	s_nop 1
	v_add_f32_dpp v42, v42, v42 row_half_mirror row_mask:0xf bank_mask:0xf bound_ctrl:1
	s_nop 1
	v_add_f32_dpp v42, v42, v42 row_mirror row_mask:0xf bank_mask:0xf bound_ctrl:1
	s_nop 0
	v_readlane_b32 s8, v42, 16
	v_readlane_b32 s9, v42, 48
	v_readlane_b32 s6, v42, 0
	v_readlane_b32 s7, v42, 32
	v_mov_b32_e32 v42, s8
	v_mov_b32_e32 v43, s9
	v_pk_add_f32 v[42:43], s[6:7], v[42:43]
	s_nop 0
	v_add_f32_e32 v42, v42, v43
	v_fmamk_f32 v42, v42, 0x3a000000, v252
	v_cmp_gt_f32_e32 vcc, s55, v42
	v_mul_f32_e32 v43, 0x4f800000, v42
	s_nop 0
	v_cndmask_b32_e32 v42, v42, v43, vcc
	v_sqrt_f32_e32 v43, v42
	s_nop 0
	v_add_u32_e32 v66, -1, v43
	v_fma_f32 v67, -v66, v43, v42
	v_cmp_ge_f32_e64 s[8:9], 0, v67
	v_add_u32_e32 v67, 1, v43
	s_nop 0
	v_cndmask_b32_e64 v66, v43, v66, s[8:9]
	v_fma_f32 v43, -v67, v43, v42
	v_cmp_lt_f32_e64 s[8:9], 0, v43
	s_nop 1
	v_cndmask_b32_e64 v43, v66, v67, s[8:9]
	v_mul_f32_e32 v66, 0x37800000, v43
	v_cndmask_b32_e32 v43, v43, v66, vcc
	v_cmp_class_f32_e32 vcc, v42, v253
	s_nop 1
	v_cndmask_b32_e32 v42, v43, v42, vcc
	v_div_scale_f32 v43, s[6:7], v42, v42, 1.0
	v_rcp_f32_e32 v66, v43
	s_lshl_b32 s6, s22, 1
	s_and_b32 s6, s6, 0xffffe000
	s_add_i32 s6, s6, 0
	v_fma_f32 v67, -v43, v66, 1.0
	v_fmac_f32_e32 v66, v67, v66
	v_div_scale_f32 v67, vcc, 1.0, v42, 1.0
	v_mul_f32_e32 v76, v67, v66
	v_fma_f32 v77, -v43, v76, v67
	v_fmac_f32_e32 v76, v77, v66
	v_fma_f32 v43, -v43, v76, v67
	v_div_fmas_f32 v43, v43, v66, v76
	v_div_fixup_f32 v66, v43, v42, 1.0
	v_pk_mul_f32 v[80:81], v[72:73], v[66:67] op_sel_hi:[1,0]
	v_pk_mul_f32 v[82:83], v[74:75], v[66:67] op_sel_hi:[1,0]
	v_add_u32_e32 v67, s6, v0
	ds_read_b128 v[72:75], v67
	ds_read_b128 v[76:79], v67 offset:40960
	v_lshl_add_u64 v[42:43], s[24:25], 1, v[2:3]
	v_lshl_add_u64 v[42:43], v[42:43], 0, v[6:7]
	v_pk_mul_f32 v[4:5], v[4:5], v[66:67] op_sel_hi:[1,0]
	v_pk_mul_f32 v[46:47], v[46:47], v[66:67] op_sel_hi:[1,0]
	s_waitcnt lgkmcnt(0)
	v_pk_fma_f32 v[74:75], v[74:75], v[82:83], v[78:79]
	v_pk_fma_f32 v[72:73], v[72:73], v[80:81], v[76:77]
	v_pk_mul_f32 v[76:77], v[68:69], v[66:67] op_sel_hi:[1,0]
	v_cvt_pk_bf16_f32 v72, v72, v73
	v_cvt_pk_bf16_f32 v73, v74, v75
	global_store_dwordx2 v[42:43], v[72:73], off
	v_pk_mul_f32 v[78:79], v[70:71], v[66:67] op_sel_hi:[1,0]
	ds_read_b128 v[68:71], v67 offset:1024
	ds_read_b128 v[72:75], v67 offset:41984
	s_waitcnt lgkmcnt(0)
	v_pk_fma_f32 v[70:71], v[70:71], v[78:79], v[74:75]
	v_pk_fma_f32 v[68:69], v[68:69], v[76:77], v[72:73]
	v_pk_mul_f32 v[72:73], v[58:59], v[66:67] op_sel_hi:[1,0]
	v_cvt_pk_bf16_f32 v68, v68, v69
	v_cvt_pk_bf16_f32 v69, v70, v71
	global_store_dwordx2 v[42:43], v[68:69], off offset:512
	v_pk_mul_f32 v[74:75], v[60:61], v[66:67] op_sel_hi:[1,0]
	ds_read_b128 v[58:61], v67 offset:2048
	ds_read_b128 v[68:71], v67 offset:43008
	s_waitcnt lgkmcnt(0)
	v_pk_fma_f32 v[60:61], v[60:61], v[74:75], v[70:71]
	v_pk_fma_f32 v[58:59], v[58:59], v[72:73], v[68:69]
	v_pk_mul_f32 v[68:69], v[62:63], v[66:67] op_sel_hi:[1,0]
	v_cvt_pk_bf16_f32 v58, v58, v59
	v_cvt_pk_bf16_f32 v59, v60, v61
	global_store_dwordx2 v[42:43], v[58:59], off offset:1024
	v_pk_mul_f32 v[70:71], v[64:65], v[66:67] op_sel_hi:[1,0]
	ds_read_b128 v[58:61], v67 offset:3072
	ds_read_b128 v[62:65], v67 offset:44032
	s_waitcnt lgkmcnt(0)
	v_pk_fma_f32 v[60:61], v[70:71], v[60:61], v[64:65]
	v_pk_fma_f32 v[58:59], v[68:69], v[58:59], v[62:63]
	v_pk_mul_f32 v[62:63], v[50:51], v[66:67] op_sel_hi:[1,0]
	v_cvt_pk_bf16_f32 v58, v58, v59
	v_cvt_pk_bf16_f32 v59, v60, v61
	global_store_dwordx2 v[42:43], v[58:59], off offset:1536
	v_pk_mul_f32 v[64:65], v[52:53], v[66:67] op_sel_hi:[1,0]
	ds_read_b128 v[50:53], v67 offset:4096
	ds_read_b128 v[58:61], v67 offset:45056
	s_waitcnt lgkmcnt(0)
	v_pk_fma_f32 v[52:53], v[64:65], v[52:53], v[60:61]
	v_pk_fma_f32 v[50:51], v[62:63], v[50:51], v[58:59]
	v_pk_mul_f32 v[58:59], v[54:55], v[66:67] op_sel_hi:[1,0]
	v_cvt_pk_bf16_f32 v50, v50, v51
	v_cvt_pk_bf16_f32 v51, v52, v53
	global_store_dwordx2 v[42:43], v[50:51], off offset:2048
	v_pk_mul_f32 v[60:61], v[56:57], v[66:67] op_sel_hi:[1,0]
	ds_read_b128 v[50:53], v67 offset:5120
	ds_read_b128 v[54:57], v67 offset:46080
	s_waitcnt lgkmcnt(0)
	v_pk_fma_f32 v[52:53], v[60:61], v[52:53], v[56:57]
	v_pk_fma_f32 v[50:51], v[58:59], v[50:51], v[54:55]
	s_waitcnt vmcnt(60)
	v_cvt_f32_f16_sdwa v59, v41 dst_sel:DWORD dst_unused:UNUSED_PAD src0_sel:WORD_1
	v_cvt_pk_bf16_f32 v50, v50, v51
	v_cvt_pk_bf16_f32 v51, v52, v53
	global_store_dwordx2 v[42:43], v[50:51], off offset:2560
	ds_read_b128 v[50:53], v67 offset:6144
	ds_read_b128 v[54:57], v67 offset:47104
	v_cvt_f32_f16_e32 v58, v41
	s_waitcnt lgkmcnt(0)
	v_pk_fma_f32 v[46:47], v[46:47], v[52:53], v[56:57]
	v_pk_fma_f32 v[4:5], v[4:5], v[50:51], v[54:55]
	v_pk_mul_f32 v[52:53], v[48:49], v[66:67] op_sel_hi:[1,0]
	v_cvt_pk_bf16_f32 v4, v4, v5
	v_cvt_pk_bf16_f32 v5, v46, v47
	global_store_dwordx2 v[42:43], v[4:5], off offset:3072
	v_pk_mul_f32 v[4:5], v[44:45], v[66:67] op_sel_hi:[1,0]
	ds_read_b128 v[44:47], v67 offset:7168
	ds_read_b128 v[48:51], v67 offset:48128
	v_cvt_f32_f16_sdwa v57, v40 dst_sel:DWORD dst_unused:UNUSED_PAD src0_sel:WORD_1
	v_cvt_f32_f16_e32 v56, v40
	s_waitcnt vmcnt(61)
	v_cvt_f32_f16_sdwa v55, v39 dst_sel:DWORD dst_unused:UNUSED_PAD src0_sel:WORD_1
	v_cvt_f32_f16_e32 v54, v39
	s_waitcnt lgkmcnt(0)
	v_pk_fma_f32 v[46:47], v[52:53], v[46:47], v[50:51]
	v_cvt_f32_f16_sdwa v53, v38 dst_sel:DWORD dst_unused:UNUSED_PAD src0_sel:WORD_1
	v_cvt_f32_f16_e32 v52, v38
	v_pk_fma_f32 v[4:5], v[4:5], v[44:45], v[48:49]
	v_mov_b32_e32 v38, v57
	v_cvt_pk_bf16_f32 v4, v4, v5
	v_cvt_pk_bf16_f32 v5, v46, v47
	global_store_dwordx2 v[42:43], v[4:5], off offset:3584
	v_mov_b32_e32 v39, v53
	s_waitcnt vmcnt(61)
	v_cvt_f32_f16_sdwa v43, v36 dst_sel:DWORD dst_unused:UNUSED_PAD src0_sel:WORD_1
	v_cvt_f32_f16_sdwa v45, v37 dst_sel:DWORD dst_unused:UNUSED_PAD src0_sel:WORD_1
	v_mov_b32_e32 v4, v56
	v_mov_b32_e32 v5, v52
	v_pk_mul_f32 v[38:39], v[38:39], v[38:39]
	v_mov_b32_e32 v40, v59
	v_mov_b32_e32 v41, v55
	v_cvt_f32_f16_e32 v42, v36
	v_cvt_f32_f16_e32 v44, v37
	s_waitcnt vmcnt(60)
	v_cvt_f32_f16_sdwa v47, v34 dst_sel:DWORD dst_unused:UNUSED_PAD src0_sel:WORD_1
	v_pk_fma_f32 v[4:5], v[4:5], v[4:5], v[38:39]
	v_mov_b32_e32 v38, v58
	v_mov_b32_e32 v39, v54
	v_pk_mul_f32 v[40:41], v[40:41], v[40:41]
	v_cvt_f32_f16_e32 v46, v34
	v_cvt_f32_f16_sdwa v49, v35 dst_sel:DWORD dst_unused:UNUSED_PAD src0_sel:WORD_1
	v_pk_fma_f32 v[38:39], v[38:39], v[38:39], v[40:41]
	v_cvt_f32_f16_e32 v48, v35
	v_pk_add_f32 v[4:5], v[4:5], v[38:39]
	v_mov_b32_e32 v38, v43
	v_mov_b32_e32 v39, v45
	v_mov_b32_e32 v36, v42
	v_mov_b32_e32 v37, v44
	v_pk_mul_f32 v[38:39], v[38:39], v[38:39]
	v_mul_f32_e32 v34, v47, v47
	v_pk_fma_f32 v[36:37], v[36:37], v[36:37], v[38:39]
	v_pk_fma_f32 v[40:41], v[46:47], v[46:47], v[34:35] op_sel_hi:[1,1,0]
	v_mul_f32_e32 v34, v49, v49
	v_pk_add_f32 v[38:39], v[36:37], v[36:37] op_sel:[0,1] op_sel_hi:[1,0]
	v_pk_fma_f32 v[50:51], v[48:49], v[48:49], v[34:35] op_sel_hi:[1,1,0]
	s_waitcnt vmcnt(59)
	v_cvt_f32_f16_sdwa v35, v32 dst_sel:DWORD dst_unused:UNUSED_PAD src0_sel:WORD_1
	v_cvt_f32_f16_e32 v34, v32
	v_cvt_f32_f16_sdwa v37, v33 dst_sel:DWORD dst_unused:UNUSED_PAD src0_sel:WORD_1
	v_cvt_f32_f16_e32 v36, v33
	v_pk_add_f32 v[4:5], v[4:5], v[4:5] op_sel:[0,1] op_sel_hi:[1,0]
	v_pk_mul_f32 v[32:33], v[34:35], v[34:35]
	v_pk_mul_f32 v[60:61], v[36:37], v[36:37]
	v_mov_b32_e32 v5, v32
	v_mov_b32_e32 v39, v33
	v_mov_b32_e32 v41, v60
	v_mov_b32_e32 v51, v61
	v_pk_add_f32 v[4:5], v[4:5], v[38:39]
	v_pk_add_f32 v[32:33], v[40:41], v[50:51]
	s_waitcnt vmcnt(58)
	v_cvt_f32_f16_sdwa v39, v30 dst_sel:DWORD dst_unused:UNUSED_PAD src0_sel:WORD_1
	v_cvt_f32_f16_sdwa v41, v31 dst_sel:DWORD dst_unused:UNUSED_PAD src0_sel:WORD_1
	v_cvt_f32_f16_e32 v38, v30
	v_cvt_f32_f16_e32 v40, v31
	v_pk_add_f32 v[4:5], v[4:5], v[32:33]
	v_mov_b32_e32 v30, v39
	v_mov_b32_e32 v31, v41
	v_pk_add_f32 v[50:51], v[4:5], v[4:5] op_sel:[0,1] op_sel_hi:[1,0]
	v_mov_b32_e32 v4, v38
	v_mov_b32_e32 v5, v40
	v_pk_mul_f32 v[30:31], v[30:31], v[30:31]
	s_waitcnt vmcnt(56)
; __device__ __forceinline__ void norm_mod_phase2(const Args& a, Frame& F, const float* gain, const float* modl, int sh_off, int sc_off, int nrows, const float* slab_gate) {
;     ...
;     NR_FINISH(r6, nw + 6 * 2048, (nw + 6 * 2048) >> 12);
	v_cvt_f32_f16_sdwa v33, v27 dst_sel:DWORD dst_unused:UNUSED_PAD src0_sel:WORD_1
	v_pk_fma_f32 v[4:5], v[4:5], v[4:5], v[30:31]
	v_cvt_f32_f16_sdwa v31, v29 dst_sel:DWORD dst_unused:UNUSED_PAD src0_sel:WORD_1
	v_pk_add_f32 v[60:61], v[4:5], v[4:5] op_sel:[0,1] op_sel_hi:[1,0]
	v_cvt_f32_f16_sdwa v5, v28 dst_sel:DWORD dst_unused:UNUSED_PAD src0_sel:WORD_1
	v_cvt_f32_f16_e32 v4, v28
	v_cvt_f32_f16_e32 v30, v29
	v_cvt_f32_f16_e32 v32, v27
	v_mul_f32_e32 v28, v5, v5
	v_pk_fma_f32 v[62:63], v[4:5], v[4:5], v[28:29] op_sel_hi:[1,1,0]
	v_mul_f32_e32 v28, v31, v31
	v_pk_fma_f32 v[64:65], v[30:31], v[30:31], v[28:29] op_sel_hi:[1,1,0]
	v_cvt_f32_f16_sdwa v29, v26 dst_sel:DWORD dst_unused:UNUSED_PAD src0_sel:WORD_1
	v_cvt_f32_f16_e32 v28, v26
	v_pk_mul_f32 v[66:67], v[32:33], v[32:33]
	v_pk_mul_f32 v[26:27], v[28:29], v[28:29]
	s_nop 0
	v_mov_b32_e32 v51, v26
	v_mov_b32_e32 v61, v27
	v_mov_b32_e32 v63, v66
	v_mov_b32_e32 v65, v67
	v_pk_add_f32 v[26:27], v[50:51], v[60:61]
	v_pk_add_f32 v[50:51], v[62:63], v[64:65]
	s_nop 0
	v_pk_add_f32 v[26:27], v[26:27], v[50:51]
	s_nop 0
	v_add_f32_e32 v26, v26, v27
	s_nop 1
	v_add_f32_dpp v26, v26, v26 quad_perm:[1,0,3,2] row_mask:0xf bank_mask:0xf bound_ctrl:1
	s_nop 1
	v_add_f32_dpp v26, v26, v26 quad_perm:[2,3,0,1] row_mask:0xf bank_mask:0xf bound_ctrl:1
	s_nop 1
	v_add_f32_dpp v26, v26, v26 row_half_mirror row_mask:0xf bank_mask:0xf bound_ctrl:1
	s_nop 1
	v_add_f32_dpp v26, v26, v26 row_mirror row_mask:0xf bank_mask:0xf bound_ctrl:1
	s_nop 0
	v_readlane_b32 s8, v26, 16
	v_readlane_b32 s9, v26, 48
	v_readlane_b32 s6, v26, 0
	v_readlane_b32 s7, v26, 32
	v_mov_b32_e32 v26, s8
	v_mov_b32_e32 v27, s9
	v_pk_add_f32 v[26:27], s[6:7], v[26:27]
	s_nop 0
	v_add_f32_e32 v26, v26, v27
	v_fmamk_f32 v26, v26, 0x3a000000, v252
	v_cmp_gt_f32_e32 vcc, s55, v26
	v_mul_f32_e32 v27, 0x4f800000, v26
	s_nop 0
	v_cndmask_b32_e32 v26, v26, v27, vcc
	v_sqrt_f32_e32 v27, v26
	s_nop 0
	v_add_u32_e32 v50, -1, v27
	v_fma_f32 v51, -v50, v27, v26
	v_cmp_ge_f32_e64 s[8:9], 0, v51
	v_add_u32_e32 v51, 1, v27
	s_nop 0
	v_cndmask_b32_e64 v50, v27, v50, s[8:9]
	v_fma_f32 v27, -v51, v27, v26
	v_cmp_lt_f32_e64 s[8:9], 0, v27
	s_nop 1
	v_cndmask_b32_e64 v27, v50, v51, s[8:9]
	v_mul_f32_e32 v50, 0x37800000, v27
	v_cndmask_b32_e32 v27, v27, v50, vcc
	v_cmp_class_f32_e32 vcc, v26, v253
	s_nop 1
	v_cndmask_b32_e32 v26, v27, v26, vcc
	v_div_scale_f32 v27, s[6:7], v26, v26, 1.0
	v_rcp_f32_e32 v50, v27
	s_lshl_b32 s6, s18, 1
	s_and_b32 s6, s6, 0xffffe000
	s_add_i32 s6, s6, 0
	v_fma_f32 v51, -v27, v50, 1.0
	v_fmac_f32_e32 v50, v51, v50
	v_div_scale_f32 v51, vcc, 1.0, v26, 1.0
	v_mul_f32_e32 v60, v51, v50
	v_fma_f32 v61, -v27, v60, v51
	v_fmac_f32_e32 v60, v61, v50
	v_fma_f32 v27, -v27, v60, v51
	v_div_fmas_f32 v27, v27, v50, v60
	v_div_fixup_f32 v50, v27, v26, 1.0
	v_pk_mul_f32 v[64:65], v[56:57], v[50:51] op_sel_hi:[1,0]
	v_pk_mul_f32 v[66:67], v[58:59], v[50:51] op_sel_hi:[1,0]
	v_add_u32_e32 v51, s6, v0
	ds_read_b128 v[56:59], v51
	ds_read_b128 v[60:63], v51 offset:40960
	v_lshl_add_u64 v[26:27], s[20:21], 1, v[2:3]
	v_lshl_add_u64 v[26:27], v[26:27], 0, v[6:7]
	v_pk_mul_f32 v[4:5], v[4:5], v[50:51] op_sel_hi:[1,0]
	v_pk_mul_f32 v[30:31], v[30:31], v[50:51] op_sel_hi:[1,0]
	s_waitcnt lgkmcnt(0)
	v_pk_fma_f32 v[58:59], v[58:59], v[66:67], v[62:63]
	v_pk_fma_f32 v[56:57], v[56:57], v[64:65], v[60:61]
	v_pk_mul_f32 v[60:61], v[52:53], v[50:51] op_sel_hi:[1,0]
	v_cvt_pk_bf16_f32 v56, v56, v57
	v_cvt_pk_bf16_f32 v57, v58, v59
	global_store_dwordx2 v[26:27], v[56:57], off
	v_pk_mul_f32 v[62:63], v[54:55], v[50:51] op_sel_hi:[1,0]
	ds_read_b128 v[52:55], v51 offset:1024
	ds_read_b128 v[56:59], v51 offset:41984
	s_waitcnt lgkmcnt(0)
	v_pk_fma_f32 v[54:55], v[54:55], v[62:63], v[58:59]
	v_pk_fma_f32 v[52:53], v[52:53], v[60:61], v[56:57]
	v_pk_mul_f32 v[56:57], v[42:43], v[50:51] op_sel_hi:[1,0]
	v_cvt_pk_bf16_f32 v52, v52, v53
	v_cvt_pk_bf16_f32 v53, v54, v55
	global_store_dwordx2 v[26:27], v[52:53], off offset:512
	v_pk_mul_f32 v[58:59], v[44:45], v[50:51] op_sel_hi:[1,0]
	ds_read_b128 v[42:45], v51 offset:2048
	ds_read_b128 v[52:55], v51 offset:43008
	s_waitcnt lgkmcnt(0)
	v_pk_fma_f32 v[44:45], v[44:45], v[58:59], v[54:55]
	v_pk_fma_f32 v[42:43], v[42:43], v[56:57], v[52:53]
	v_pk_mul_f32 v[52:53], v[46:47], v[50:51] op_sel_hi:[1,0]
	v_cvt_pk_bf16_f32 v42, v42, v43
	v_cvt_pk_bf16_f32 v43, v44, v45
	global_store_dwordx2 v[26:27], v[42:43], off offset:1024
	v_pk_mul_f32 v[54:55], v[48:49], v[50:51] op_sel_hi:[1,0]
	ds_read_b128 v[42:45], v51 offset:3072
	ds_read_b128 v[46:49], v51 offset:44032
	s_waitcnt lgkmcnt(0)
	v_pk_fma_f32 v[44:45], v[54:55], v[44:45], v[48:49]
	v_pk_fma_f32 v[42:43], v[52:53], v[42:43], v[46:47]
	v_pk_mul_f32 v[46:47], v[34:35], v[50:51] op_sel_hi:[1,0]
	v_cvt_pk_bf16_f32 v42, v42, v43
	v_cvt_pk_bf16_f32 v43, v44, v45
	global_store_dwordx2 v[26:27], v[42:43], off offset:1536
	v_pk_mul_f32 v[48:49], v[36:37], v[50:51] op_sel_hi:[1,0]
	ds_read_b128 v[34:37], v51 offset:4096
	ds_read_b128 v[42:45], v51 offset:45056
	s_waitcnt lgkmcnt(0)
	v_pk_fma_f32 v[36:37], v[48:49], v[36:37], v[44:45]
	v_pk_fma_f32 v[34:35], v[46:47], v[34:35], v[42:43]
	v_pk_mul_f32 v[42:43], v[38:39], v[50:51] op_sel_hi:[1,0]
	v_cvt_pk_bf16_f32 v34, v34, v35
	v_cvt_pk_bf16_f32 v35, v36, v37
	global_store_dwordx2 v[26:27], v[34:35], off offset:2048
	v_pk_mul_f32 v[44:45], v[40:41], v[50:51] op_sel_hi:[1,0]
	ds_read_b128 v[34:37], v51 offset:5120
	ds_read_b128 v[38:41], v51 offset:46080
	s_waitcnt lgkmcnt(0)
	v_pk_fma_f32 v[36:37], v[44:45], v[36:37], v[40:41]
	v_pk_fma_f32 v[34:35], v[42:43], v[34:35], v[38:39]
	s_waitcnt vmcnt(60)
; __device__ __forceinline__ void norm_mod_phase2(const Args& a, Frame& F, const float* gain, const float* modl, int sh_off, int sc_off, int nrows, const float* slab_gate) {
;     ...
;     NR_FINISH(r7, nw + 7 * 2048, (nw + 7 * 2048) >> 12);
;     if (ML + nw < nrows) {
	v_cvt_f32_f16_sdwa v43, v25 dst_sel:DWORD dst_unused:UNUSED_PAD src0_sel:WORD_1
	v_cvt_pk_bf16_f32 v34, v34, v35
	v_cvt_pk_bf16_f32 v35, v36, v37
	global_store_dwordx2 v[26:27], v[34:35], off offset:2560
	ds_read_b128 v[34:37], v51 offset:6144
	ds_read_b128 v[38:41], v51 offset:47104
	v_cvt_f32_f16_e32 v42, v25
	s_waitcnt lgkmcnt(0)
	v_pk_fma_f32 v[30:31], v[30:31], v[36:37], v[40:41]
	v_pk_fma_f32 v[4:5], v[4:5], v[34:35], v[38:39]
	v_pk_mul_f32 v[36:37], v[32:33], v[50:51] op_sel_hi:[1,0]
	v_cvt_pk_bf16_f32 v4, v4, v5
	v_cvt_pk_bf16_f32 v5, v30, v31
	global_store_dwordx2 v[26:27], v[4:5], off offset:3072
	v_pk_mul_f32 v[4:5], v[28:29], v[50:51] op_sel_hi:[1,0]
	ds_read_b128 v[28:31], v51 offset:7168
	ds_read_b128 v[32:35], v51 offset:48128
	v_cvt_f32_f16_sdwa v41, v24 dst_sel:DWORD dst_unused:UNUSED_PAD src0_sel:WORD_1
	v_cvt_f32_f16_e32 v40, v24
	s_waitcnt vmcnt(61)
	v_cvt_f32_f16_sdwa v39, v23 dst_sel:DWORD dst_unused:UNUSED_PAD src0_sel:WORD_1
	v_cvt_f32_f16_e32 v38, v23
	s_waitcnt lgkmcnt(0)
	v_pk_fma_f32 v[30:31], v[36:37], v[30:31], v[34:35]
	v_cvt_f32_f16_sdwa v37, v22 dst_sel:DWORD dst_unused:UNUSED_PAD src0_sel:WORD_1
	v_cvt_f32_f16_e32 v36, v22
	v_pk_fma_f32 v[4:5], v[4:5], v[28:29], v[32:33]
	v_mov_b32_e32 v22, v41
	v_cvt_pk_bf16_f32 v4, v4, v5
	v_cvt_pk_bf16_f32 v5, v30, v31
	global_store_dwordx2 v[26:27], v[4:5], off offset:3584
	v_mov_b32_e32 v23, v37
	s_waitcnt vmcnt(61)
	v_cvt_f32_f16_sdwa v27, v20 dst_sel:DWORD dst_unused:UNUSED_PAD src0_sel:WORD_1
	v_cvt_f32_f16_sdwa v29, v21 dst_sel:DWORD dst_unused:UNUSED_PAD src0_sel:WORD_1
	v_mov_b32_e32 v4, v40
	v_mov_b32_e32 v5, v36
	v_pk_mul_f32 v[22:23], v[22:23], v[22:23]
	v_mov_b32_e32 v24, v43
	v_mov_b32_e32 v25, v39
	v_cvt_f32_f16_e32 v26, v20
	v_cvt_f32_f16_e32 v28, v21
	s_waitcnt vmcnt(60)
	v_cvt_f32_f16_sdwa v31, v18 dst_sel:DWORD dst_unused:UNUSED_PAD src0_sel:WORD_1
	v_pk_fma_f32 v[4:5], v[4:5], v[4:5], v[22:23]
	v_mov_b32_e32 v22, v42
	v_mov_b32_e32 v23, v38
	v_pk_mul_f32 v[24:25], v[24:25], v[24:25]
	v_cvt_f32_f16_e32 v30, v18
	v_cvt_f32_f16_sdwa v33, v19 dst_sel:DWORD dst_unused:UNUSED_PAD src0_sel:WORD_1
	v_pk_fma_f32 v[22:23], v[22:23], v[22:23], v[24:25]
	v_cvt_f32_f16_e32 v32, v19
	v_pk_add_f32 v[4:5], v[4:5], v[22:23]
	v_mov_b32_e32 v22, v27
	v_mov_b32_e32 v23, v29
	v_mov_b32_e32 v20, v26
	v_mov_b32_e32 v21, v28
	v_pk_mul_f32 v[22:23], v[22:23], v[22:23]
	v_mul_f32_e32 v18, v31, v31
	v_pk_fma_f32 v[20:21], v[20:21], v[20:21], v[22:23]
	v_pk_fma_f32 v[24:25], v[30:31], v[30:31], v[18:19] op_sel_hi:[1,1,0]
	v_mul_f32_e32 v18, v33, v33
	v_pk_add_f32 v[22:23], v[20:21], v[20:21] op_sel:[0,1] op_sel_hi:[1,0]
	v_pk_fma_f32 v[34:35], v[32:33], v[32:33], v[18:19] op_sel_hi:[1,1,0]
	s_waitcnt vmcnt(59)
	v_cvt_f32_f16_sdwa v19, v16 dst_sel:DWORD dst_unused:UNUSED_PAD src0_sel:WORD_1
	v_cvt_f32_f16_e32 v18, v16
	v_cvt_f32_f16_sdwa v21, v17 dst_sel:DWORD dst_unused:UNUSED_PAD src0_sel:WORD_1
	v_cvt_f32_f16_e32 v20, v17
	v_pk_add_f32 v[4:5], v[4:5], v[4:5] op_sel:[0,1] op_sel_hi:[1,0]
	v_pk_mul_f32 v[16:17], v[18:19], v[18:19]
	v_pk_mul_f32 v[44:45], v[20:21], v[20:21]
	v_mov_b32_e32 v5, v16
	v_mov_b32_e32 v23, v17
	v_mov_b32_e32 v25, v44
	v_mov_b32_e32 v35, v45
	v_pk_add_f32 v[4:5], v[4:5], v[22:23]
	v_pk_add_f32 v[16:17], v[24:25], v[34:35]
	s_waitcnt vmcnt(58)
	v_cvt_f32_f16_sdwa v23, v14 dst_sel:DWORD dst_unused:UNUSED_PAD src0_sel:WORD_1
	v_cvt_f32_f16_sdwa v25, v15 dst_sel:DWORD dst_unused:UNUSED_PAD src0_sel:WORD_1
	v_cvt_f32_f16_e32 v22, v14
	v_cvt_f32_f16_e32 v24, v15
	v_pk_add_f32 v[4:5], v[4:5], v[16:17]
	v_mov_b32_e32 v14, v23
	v_mov_b32_e32 v15, v25
	v_pk_add_f32 v[34:35], v[4:5], v[4:5] op_sel:[0,1] op_sel_hi:[1,0]
	v_mov_b32_e32 v4, v22
	v_mov_b32_e32 v5, v24
	v_pk_mul_f32 v[14:15], v[14:15], v[14:15]
	s_waitcnt vmcnt(56)
	v_cvt_f32_f16_sdwa v17, v11 dst_sel:DWORD dst_unused:UNUSED_PAD src0_sel:WORD_1
	v_pk_fma_f32 v[4:5], v[4:5], v[4:5], v[14:15]
	v_cvt_f32_f16_sdwa v15, v13 dst_sel:DWORD dst_unused:UNUSED_PAD src0_sel:WORD_1
	v_pk_add_f32 v[44:45], v[4:5], v[4:5] op_sel:[0,1] op_sel_hi:[1,0]
	v_cvt_f32_f16_sdwa v5, v12 dst_sel:DWORD dst_unused:UNUSED_PAD src0_sel:WORD_1
	v_cvt_f32_f16_e32 v4, v12
	v_cvt_f32_f16_e32 v14, v13
	v_cvt_f32_f16_e32 v16, v11
	v_mul_f32_e32 v12, v5, v5
	v_pk_fma_f32 v[46:47], v[4:5], v[4:5], v[12:13] op_sel_hi:[1,1,0]
	v_mul_f32_e32 v12, v15, v15
	v_pk_fma_f32 v[48:49], v[14:15], v[14:15], v[12:13] op_sel_hi:[1,1,0]
	v_cvt_f32_f16_sdwa v13, v10 dst_sel:DWORD dst_unused:UNUSED_PAD src0_sel:WORD_1
	v_cvt_f32_f16_e32 v12, v10
	v_pk_mul_f32 v[50:51], v[16:17], v[16:17]
	v_pk_mul_f32 v[10:11], v[12:13], v[12:13]
	s_nop 0
	v_mov_b32_e32 v35, v10
	v_mov_b32_e32 v45, v11
	v_mov_b32_e32 v47, v50
	v_mov_b32_e32 v49, v51
	v_pk_add_f32 v[10:11], v[34:35], v[44:45]
	v_pk_add_f32 v[34:35], v[46:47], v[48:49]
	s_nop 0
	v_pk_add_f32 v[10:11], v[10:11], v[34:35]
	s_nop 0
	v_add_f32_e32 v10, v10, v11
	s_nop 1
	v_add_f32_dpp v10, v10, v10 quad_perm:[1,0,3,2] row_mask:0xf bank_mask:0xf bound_ctrl:1
	s_nop 1
	v_add_f32_dpp v10, v10, v10 quad_perm:[2,3,0,1] row_mask:0xf bank_mask:0xf bound_ctrl:1
	s_nop 1
	v_add_f32_dpp v10, v10, v10 row_half_mirror row_mask:0xf bank_mask:0xf bound_ctrl:1
	s_nop 1
	v_add_f32_dpp v10, v10, v10 row_mirror row_mask:0xf bank_mask:0xf bound_ctrl:1
	s_nop 0
	v_readlane_b32 s8, v10, 16
	v_readlane_b32 s9, v10, 48
	v_readlane_b32 s6, v10, 0
	v_readlane_b32 s7, v10, 32
	v_mov_b32_e32 v10, s8
	v_mov_b32_e32 v11, s9
	v_pk_add_f32 v[10:11], s[6:7], v[10:11]
	s_nop 0
	v_add_f32_e32 v10, v10, v11
	v_fmamk_f32 v10, v10, 0x3a000000, v252
	v_cmp_gt_f32_e32 vcc, s55, v10
	v_mul_f32_e32 v11, 0x4f800000, v10
	s_nop 0
	v_cndmask_b32_e32 v10, v10, v11, vcc
	v_sqrt_f32_e32 v11, v10
	s_nop 0
	v_add_u32_e32 v34, -1, v11
	v_fma_f32 v35, -v34, v11, v10
	v_cmp_ge_f32_e64 s[8:9], 0, v35
	v_add_u32_e32 v35, 1, v11
	s_nop 0
	v_cndmask_b32_e64 v34, v11, v34, s[8:9]
	v_fma_f32 v11, -v35, v11, v10
	v_cmp_lt_f32_e64 s[8:9], 0, v11
	s_nop 1
	v_cndmask_b32_e64 v11, v34, v35, s[8:9]
	v_mul_f32_e32 v34, 0x37800000, v11
	v_cndmask_b32_e32 v11, v11, v34, vcc
	v_cmp_class_f32_e32 vcc, v10, v253
	s_add_i32 s8, s10, 0x4000
	s_nop 0
	v_cndmask_b32_e32 v10, v11, v10, vcc
	v_div_scale_f32 v11, s[6:7], v10, v10, 1.0
	v_rcp_f32_e32 v34, v11
	s_lshl_b32 s6, s14, 1
	s_and_b32 s6, s6, 0xffffe000
	s_add_i32 s6, s6, 0
	v_fma_f32 v35, -v11, v34, 1.0
	v_fmac_f32_e32 v34, v35, v34
	v_div_scale_f32 v35, vcc, 1.0, v10, 1.0
	v_mul_f32_e32 v44, v35, v34
	v_fma_f32 v45, -v11, v44, v35
	v_fmac_f32_e32 v44, v45, v34
	v_fma_f32 v11, -v11, v44, v35
	v_div_fmas_f32 v11, v11, v34, v44
	v_div_fixup_f32 v34, v11, v10, 1.0
	v_pk_mul_f32 v[48:49], v[40:41], v[34:35] op_sel_hi:[1,0]
	v_pk_mul_f32 v[50:51], v[42:43], v[34:35] op_sel_hi:[1,0]
	v_add_u32_e32 v35, s6, v0
	ds_read_b128 v[40:43], v35
	ds_read_b128 v[44:47], v35 offset:40960
	v_lshl_add_u64 v[10:11], s[16:17], 1, v[2:3]
	v_lshl_add_u64 v[10:11], v[10:11], 0, v[6:7]
	v_pk_mul_f32 v[4:5], v[4:5], v[34:35] op_sel_hi:[1,0]
	v_pk_mul_f32 v[14:15], v[14:15], v[34:35] op_sel_hi:[1,0]
	s_waitcnt lgkmcnt(0)
; #define GAS __attribute__((address_space(1)))
; __device__ __forceinline__ unsigned xpk2(float lo, float hi) { if (XRES_F16) { const f32x2_t v = {lo, hi}; const f16x2_t h = __builtin_convertvector(v, f16x2_t); return __builtin_bit_cast(unsigned, h); } return pk2(lo, hi); }
; __device__ __forceinline__ float xlo(unsigned w) { if (XRES_F16) { const f16x2_t h = __builtin_bit_cast(f16x2_t, w); return (float)h[0]; } return __builtin_bit_cast(float, w << 16); }
; __device__ __forceinline__ float xhi(unsigned w) { if (XRES_F16) { const f16x2_t h = __builtin_bit_cast(f16x2_t, w); return (float)h[1]; } return __builtin_bit_cast(float, w & 0xffff0000u); }
; __device__ __forceinline__ void norm_mod_phase2(const Args& a, Frame& F, const float* gain, const float* modl, int sh_off, int sc_off, int nrows, const float* slab_gate) {
;     ...
;     if (ML + nw < nrows) {
;         const int r = ML + nw, rc = nw;
;         const GAS v2u* xr = (const GAS v2u*)(X + (size_t)r * D) + F.lane;
; #pragma unroll
;         for (int j = 0; j < 8; ++j) r0[j] = xr[64 * j];
;         if (slab_gate != nullptr) { const GAS f32x4* sl = (const GAS f32x4*)((const float*)(a.ws + WS_SLAB) + (size_t)rc * D) + F.lane;
; #pragma unroll
;             for (int j = 0; j < 8; ++j) { const f32x4 p = (sl[64 * j] + sl[64 * j + (size_t)MC * D / 4]) + (sl[64 * j + 2 * ((size_t)MC * D / 4)] + sl[64 * j + 3 * ((size_t)MC * D / 4)]);
;                 const f32x4 x = (f32x4){xlo(r0[j].x), xhi(r0[j].x), xlo(r0[j].y), xhi(r0[j].y)} + *(const GAS f32x4*)(slab_gate + 256 * j + 4 * F.lane) * p;
;                 v2u w; w.x = xpk2(x[0], x[1]); w.y = xpk2(x[2], x[3]); ((GAS v2u*)(X + (size_t)r * D) + F.lane)[64 * j] = w; r0[j] = w; } }
	v_pk_fma_f32 v[42:43], v[42:43], v[50:51], v[46:47]
	v_pk_fma_f32 v[40:41], v[40:41], v[48:49], v[44:45]
	v_pk_mul_f32 v[44:45], v[36:37], v[34:35] op_sel_hi:[1,0]
	v_cvt_pk_bf16_f32 v40, v40, v41
	v_cvt_pk_bf16_f32 v41, v42, v43
	global_store_dwordx2 v[10:11], v[40:41], off
	v_pk_mul_f32 v[46:47], v[38:39], v[34:35] op_sel_hi:[1,0]
	ds_read_b128 v[36:39], v35 offset:1024
	ds_read_b128 v[40:43], v35 offset:41984
	s_cmp_lt_i32 s8, s47
	s_waitcnt lgkmcnt(0)
	v_pk_fma_f32 v[38:39], v[38:39], v[46:47], v[42:43]
	v_pk_fma_f32 v[36:37], v[36:37], v[44:45], v[40:41]
	v_pk_mul_f32 v[40:41], v[26:27], v[34:35] op_sel_hi:[1,0]
	v_cvt_pk_bf16_f32 v36, v36, v37
	v_cvt_pk_bf16_f32 v37, v38, v39
	global_store_dwordx2 v[10:11], v[36:37], off offset:512
	v_pk_mul_f32 v[42:43], v[28:29], v[34:35] op_sel_hi:[1,0]
	ds_read_b128 v[26:29], v35 offset:2048
	ds_read_b128 v[36:39], v35 offset:43008
	s_waitcnt lgkmcnt(0)
	v_pk_fma_f32 v[28:29], v[28:29], v[42:43], v[38:39]
	v_pk_fma_f32 v[26:27], v[26:27], v[40:41], v[36:37]
	v_pk_mul_f32 v[36:37], v[30:31], v[34:35] op_sel_hi:[1,0]
	v_cvt_pk_bf16_f32 v26, v26, v27
	v_cvt_pk_bf16_f32 v27, v28, v29
	global_store_dwordx2 v[10:11], v[26:27], off offset:1024
	v_pk_mul_f32 v[38:39], v[32:33], v[34:35] op_sel_hi:[1,0]
	ds_read_b128 v[26:29], v35 offset:3072
	ds_read_b128 v[30:33], v35 offset:44032
	s_waitcnt lgkmcnt(0)
	v_pk_fma_f32 v[28:29], v[38:39], v[28:29], v[32:33]
	v_pk_fma_f32 v[26:27], v[36:37], v[26:27], v[30:31]
	v_pk_mul_f32 v[30:31], v[18:19], v[34:35] op_sel_hi:[1,0]
	v_cvt_pk_bf16_f32 v26, v26, v27
	v_cvt_pk_bf16_f32 v27, v28, v29
	global_store_dwordx2 v[10:11], v[26:27], off offset:1536
	v_pk_mul_f32 v[32:33], v[20:21], v[34:35] op_sel_hi:[1,0]
	ds_read_b128 v[18:21], v35 offset:4096
	ds_read_b128 v[26:29], v35 offset:45056
	s_waitcnt lgkmcnt(0)
	v_pk_fma_f32 v[20:21], v[32:33], v[20:21], v[28:29]
	v_pk_fma_f32 v[18:19], v[30:31], v[18:19], v[26:27]
	v_pk_mul_f32 v[26:27], v[22:23], v[34:35] op_sel_hi:[1,0]
	v_cvt_pk_bf16_f32 v18, v18, v19
	v_cvt_pk_bf16_f32 v19, v20, v21
	global_store_dwordx2 v[10:11], v[18:19], off offset:2048
	v_pk_mul_f32 v[28:29], v[24:25], v[34:35] op_sel_hi:[1,0]
	ds_read_b128 v[18:21], v35 offset:5120
	ds_read_b128 v[22:25], v35 offset:46080
	s_waitcnt lgkmcnt(0)
	v_pk_fma_f32 v[20:21], v[28:29], v[20:21], v[24:25]
	v_pk_fma_f32 v[18:19], v[26:27], v[18:19], v[22:23]
	s_nop 0
	v_cvt_pk_bf16_f32 v18, v18, v19
	v_cvt_pk_bf16_f32 v19, v20, v21
	global_store_dwordx2 v[10:11], v[18:19], off offset:2560
	ds_read_b128 v[18:21], v35 offset:6144
	ds_read_b128 v[22:25], v35 offset:47104
	s_waitcnt lgkmcnt(0)
	v_pk_fma_f32 v[14:15], v[14:15], v[20:21], v[24:25]
	v_pk_fma_f32 v[4:5], v[4:5], v[18:19], v[22:23]
	v_pk_mul_f32 v[20:21], v[16:17], v[34:35] op_sel_hi:[1,0]
	v_cvt_pk_bf16_f32 v4, v4, v5
	v_cvt_pk_bf16_f32 v5, v14, v15
	global_store_dwordx2 v[10:11], v[4:5], off offset:3072
	v_pk_mul_f32 v[4:5], v[12:13], v[34:35] op_sel_hi:[1,0]
	ds_read_b128 v[12:15], v35 offset:7168
	ds_read_b128 v[16:19], v35 offset:48128
	s_waitcnt lgkmcnt(0)
	v_pk_fma_f32 v[14:15], v[20:21], v[14:15], v[18:19]
	v_pk_fma_f32 v[4:5], v[4:5], v[12:13], v[16:17]
	s_nop 0
	v_cvt_pk_bf16_f32 v4, v4, v5
	v_cvt_pk_bf16_f32 v5, v14, v15
	global_store_dwordx2 v[10:11], v[4:5], off offset:3584
	s_cbranch_scc0 .LBB0_1050
	s_ashr_i32 s9, s8, 31
	s_lshl_b64 s[6:7], s[8:9], 12
	v_lshl_add_u64 v[4:5], v[8:9], 0, s[6:7]
	v_lshl_add_u64 v[18:19], v[4:5], 0, v[6:7]
	global_load_dwordx2 v[22:23], v[18:19], off
	global_load_dwordx2 v[20:21], v[18:19], off offset:512
	global_load_dwordx2 v[16:17], v[18:19], off offset:1024
	global_load_dwordx2 v[12:13], v[18:19], off offset:1536
	global_load_dwordx2 v[14:15], v[18:19], off offset:2048
	global_load_dwordx2 v[10:11], v[18:19], off offset:2560
	global_load_dwordx2 v[8:9], v[18:19], off offset:3072
	global_load_dwordx2 v[4:5], v[18:19], off offset:3584
	s_andn2_b64 vcc, exec, s[4:5]
	v_lshlrev_b32_e32 v46, 2, v147
	s_cbranch_vccnz .LBB0_1049
	v_mov_b32_e32 v24, s72
	v_mov_b32_e32 v25, s73
	v_lshl_add_u64 v[24:25], s[12:13], 2, v[24:25]
	v_lshl_add_u64 v[24:25], v[24:25], 0, v[0:1]
	v_lshlrev_b32_e32 v0, 2, v46
	v_lshl_add_u64 v[26:27], s[86:87], 0, v[0:1]
	v_add_co_u32_e32 v28, vcc, 0x58400000, v24
	s_nop 1
	v_addc_co_u32_e32 v29, vcc, 0, v25, vcc
	v_add_co_u32_e32 v30, vcc, 0x58c00000, v24
	s_nop 1
	v_addc_co_u32_e32 v31, vcc, 0, v25, vcc
	v_add_co_u32_e32 v32, vcc, 0x59400000, v24
	s_nop 1
	v_addc_co_u32_e32 v33, vcc, 0, v25, vcc
	v_add_co_u32_e32 v34, vcc, 0x59c00000, v24
	s_nop 1
	v_addc_co_u32_e32 v35, vcc, 0, v25, vcc
	v_add_co_u32_e32 v36, vcc, 0x58401000, v24
	s_nop 1
	v_addc_co_u32_e32 v37, vcc, 0, v25, vcc
	v_add_co_u32_e32 v38, vcc, 0x58c01000, v24
	s_nop 1
	v_addc_co_u32_e32 v39, vcc, 0, v25, vcc
	v_add_co_u32_e32 v42, vcc, 0x59401000, v24
	s_nop 1
	v_addc_co_u32_e32 v43, vcc, 0, v25, vcc
	v_add_co_u32_e32 v44, vcc, 0x59c01000, v24
	s_nop 1
	v_addc_co_u32_e32 v45, vcc, 0, v25, vcc
	v_add_co_u32_e32 v48, vcc, 0x34000, v26
	s_nop 1
	v_addc_co_u32_e32 v49, vcc, 0, v27, vcc
	v_add_co_u32_e32 v50, vcc, 0x35000, v26
	s_nop 1
	v_addc_co_u32_e32 v51, vcc, 0, v27, vcc
	global_load_dwordx4 v[94:97], v[28:29], off
	global_load_dwordx4 v[98:101], v[30:31], off
	global_load_dwordx4 v[102:105], v[32:33], off
	global_load_dwordx4 v[106:109], v[34:35], off
	global_load_dwordx4 v[110:113], v[48:49], off
	global_load_dwordx4 v[114:117], v[28:29], off offset:1024
	global_load_dwordx4 v[118:121], v[30:31], off offset:1024
	global_load_dwordx4 v[122:125], v[32:33], off offset:1024
	global_load_dwordx4 v[126:129], v[34:35], off offset:1024
	global_load_dwordx4 v[130:133], v[48:49], off offset:1024
	global_load_dwordx4 v[134:137], v[28:29], off offset:2048
	global_load_dwordx4 v[138:141], v[30:31], off offset:2048
	global_load_dwordx4 v[142:145], v[32:33], off offset:2048
	global_load_dwordx4 v[146:149], v[34:35], off offset:2048
	global_load_dwordx4 v[150:153], v[48:49], off offset:2048
	global_load_dwordx4 v[154:157], v[28:29], off offset:3072
	global_load_dwordx4 v[158:161], v[30:31], off offset:3072
	global_load_dwordx4 v[162:165], v[32:33], off offset:3072
	global_load_dwordx4 v[170:173], v[34:35], off offset:3072
	global_load_dwordx4 v[174:177], v[48:49], off offset:3072
	s_waitcnt vmcnt(15)
; #define GAS __attribute__((address_space(1)))
; __device__ __forceinline__ unsigned xpk2(float lo, float hi) { if (XRES_F16) { const f32x2_t v = {lo, hi}; const f16x2_t h = __builtin_convertvector(v, f16x2_t); return __builtin_bit_cast(unsigned, h); } return pk2(lo, hi); }
; __device__ __forceinline__ float xlo(unsigned w) { if (XRES_F16) { const f16x2_t h = __builtin_bit_cast(f16x2_t, w); return (float)h[0]; } return __builtin_bit_cast(float, w << 16); }
; __device__ __forceinline__ float xhi(unsigned w) { if (XRES_F16) { const f16x2_t h = __builtin_bit_cast(f16x2_t, w); return (float)h[1]; } return __builtin_bit_cast(float, w & 0xffff0000u); }
; __device__ __forceinline__ void norm_mod_phase2(const Args& a, Frame& F, const float* gain, const float* modl, int sh_off, int sc_off, int nrows, const float* slab_gate) {
;     ...
;         if (slab_gate != nullptr) { const GAS f32x4* sl = (const GAS f32x4*)((const float*)(a.ws + WS_SLAB) + (size_t)rc * D) + F.lane;
; #pragma unroll
;             for (int j = 0; j < 8; ++j) { const f32x4 p = (sl[64 * j] + sl[64 * j + (size_t)MC * D / 4]) + (sl[64 * j + 2 * ((size_t)MC * D / 4)] + sl[64 * j + 3 * ((size_t)MC * D / 4)]);
;                 const f32x4 x = (f32x4){xlo(r0[j].x), xhi(r0[j].x), xlo(r0[j].y), xhi(r0[j].y)} + *(const GAS f32x4*)(slab_gate + 256 * j + 4 * F.lane) * p;
;                 v2u w; w.x = xpk2(x[0], x[1]); w.y = xpk2(x[2], x[3]); ((GAS v2u*)(X + (size_t)r * D) + F.lane)[64 * j] = w; r0[j] = w; } }
	v_pk_add_f32 v[220:221], v[94:95], v[98:99]
	v_pk_add_f32 v[222:223], v[96:97], v[100:101]
	v_pk_add_f32 v[224:225], v[102:103], v[106:107]
	v_pk_add_f32 v[226:227], v[104:105], v[108:109]
	v_cvt_f32_f16_e32 v232, v22
	v_cvt_f32_f16_sdwa v233, v22 dst_sel:DWORD dst_unused:UNUSED_PAD src0_sel:WORD_1
	v_cvt_f32_f16_e32 v234, v23
	v_cvt_f32_f16_sdwa v235, v23 dst_sel:DWORD dst_unused:UNUSED_PAD src0_sel:WORD_1
	v_pk_add_f32 v[228:229], v[220:221], v[224:225]
	v_pk_add_f32 v[230:231], v[222:223], v[226:227]
	s_nop 1
	v_pk_fma_f32 v[236:237], v[110:111], v[228:229], v[232:233]
	v_pk_fma_f32 v[238:239], v[112:113], v[230:231], v[234:235]
	s_nop 1
	v_cvt_pk_f16_f32 v22, v236, v237
	v_cvt_pk_f16_f32 v23, v238, v239
	global_store_dwordx2 v[18:19], v[22:23], off
	global_load_dwordx4 v[94:97], v[36:37], off
	global_load_dwordx4 v[98:101], v[38:39], off
	global_load_dwordx4 v[102:105], v[42:43], off
	global_load_dwordx4 v[106:109], v[44:45], off
	global_load_dwordx4 v[110:113], v[50:51], off
	s_waitcnt vmcnt(16)
	v_pk_add_f32 v[220:221], v[114:115], v[118:119]
	v_pk_add_f32 v[222:223], v[116:117], v[120:121]
	v_pk_add_f32 v[224:225], v[122:123], v[126:127]
	v_pk_add_f32 v[226:227], v[124:125], v[128:129]
	v_cvt_f32_f16_e32 v232, v20
	v_cvt_f32_f16_sdwa v233, v20 dst_sel:DWORD dst_unused:UNUSED_PAD src0_sel:WORD_1
	v_cvt_f32_f16_e32 v234, v21
	v_cvt_f32_f16_sdwa v235, v21 dst_sel:DWORD dst_unused:UNUSED_PAD src0_sel:WORD_1
	v_pk_add_f32 v[228:229], v[220:221], v[224:225]
	v_pk_add_f32 v[230:231], v[222:223], v[226:227]
	s_nop 1
	v_pk_fma_f32 v[236:237], v[130:131], v[228:229], v[232:233]
	v_pk_fma_f32 v[238:239], v[132:133], v[230:231], v[234:235]
	s_nop 1
	v_cvt_pk_f16_f32 v20, v236, v237
	v_cvt_pk_f16_f32 v21, v238, v239
	global_store_dwordx2 v[18:19], v[20:21], off offset:512
	global_load_dwordx4 v[114:117], v[36:37], off offset:1024
	global_load_dwordx4 v[118:121], v[38:39], off offset:1024
	global_load_dwordx4 v[122:125], v[42:43], off offset:1024
	global_load_dwordx4 v[126:129], v[44:45], off offset:1024
	global_load_dwordx4 v[130:133], v[50:51], off offset:1024
	s_waitcnt vmcnt(17)
	v_pk_add_f32 v[220:221], v[134:135], v[138:139]
	v_pk_add_f32 v[222:223], v[136:137], v[140:141]
	v_pk_add_f32 v[224:225], v[142:143], v[146:147]
	v_pk_add_f32 v[226:227], v[144:145], v[148:149]
	v_cvt_f32_f16_e32 v232, v16
	v_cvt_f32_f16_sdwa v233, v16 dst_sel:DWORD dst_unused:UNUSED_PAD src0_sel:WORD_1
	v_cvt_f32_f16_e32 v234, v17
	v_cvt_f32_f16_sdwa v235, v17 dst_sel:DWORD dst_unused:UNUSED_PAD src0_sel:WORD_1
	v_pk_add_f32 v[228:229], v[220:221], v[224:225]
	v_pk_add_f32 v[230:231], v[222:223], v[226:227]
	s_nop 1
	v_pk_fma_f32 v[236:237], v[150:151], v[228:229], v[232:233]
	v_pk_fma_f32 v[238:239], v[152:153], v[230:231], v[234:235]
	s_nop 1
	v_cvt_pk_f16_f32 v16, v236, v237
	v_cvt_pk_f16_f32 v17, v238, v239
	global_store_dwordx2 v[18:19], v[16:17], off offset:1024
	global_load_dwordx4 v[134:137], v[36:37], off offset:2048
	global_load_dwordx4 v[138:141], v[38:39], off offset:2048
	global_load_dwordx4 v[142:145], v[42:43], off offset:2048
	global_load_dwordx4 v[146:149], v[44:45], off offset:2048
	global_load_dwordx4 v[150:153], v[50:51], off offset:2048
	s_waitcnt vmcnt(18)
; #define GAS __attribute__((address_space(1)))
; __device__ __forceinline__ unsigned xpk2(float lo, float hi) { if (XRES_F16) { const f32x2_t v = {lo, hi}; const f16x2_t h = __builtin_convertvector(v, f16x2_t); return __builtin_bit_cast(unsigned, h); } return pk2(lo, hi); }
; __device__ __forceinline__ float xlo(unsigned w) { if (XRES_F16) { const f16x2_t h = __builtin_bit_cast(f16x2_t, w); return (float)h[0]; } return __builtin_bit_cast(float, w << 16); }
; __device__ __forceinline__ float xhi(unsigned w) { if (XRES_F16) { const f16x2_t h = __builtin_bit_cast(f16x2_t, w); return (float)h[1]; } return __builtin_bit_cast(float, w & 0xffff0000u); }
; __device__ __forceinline__ void norm_mod_phase2(const Args& a, Frame& F, const float* gain, const float* modl, int sh_off, int sc_off, int nrows, const float* slab_gate) {
;     ...
;         if (slab_gate != nullptr) { const GAS f32x4* sl = (const GAS f32x4*)((const float*)(a.ws + WS_SLAB) + (size_t)rc * D) + F.lane;
; #pragma unroll
;             for (int j = 0; j < 8; ++j) { const f32x4 p = (sl[64 * j] + sl[64 * j + (size_t)MC * D / 4]) + (sl[64 * j + 2 * ((size_t)MC * D / 4)] + sl[64 * j + 3 * ((size_t)MC * D / 4)]);
;                 const f32x4 x = (f32x4){xlo(r0[j].x), xhi(r0[j].x), xlo(r0[j].y), xhi(r0[j].y)} + *(const GAS f32x4*)(slab_gate + 256 * j + 4 * F.lane) * p;
;                 v2u w; w.x = xpk2(x[0], x[1]); w.y = xpk2(x[2], x[3]); ((GAS v2u*)(X + (size_t)r * D) + F.lane)[64 * j] = w; r0[j] = w; } }
;         NR_FINISH(r0, r, 4);
	v_pk_add_f32 v[220:221], v[154:155], v[158:159]
	v_pk_add_f32 v[222:223], v[156:157], v[160:161]
	v_pk_add_f32 v[224:225], v[162:163], v[170:171]
	v_pk_add_f32 v[226:227], v[164:165], v[172:173]
	v_cvt_f32_f16_e32 v232, v12
	v_cvt_f32_f16_sdwa v233, v12 dst_sel:DWORD dst_unused:UNUSED_PAD src0_sel:WORD_1
	v_cvt_f32_f16_e32 v234, v13
	v_cvt_f32_f16_sdwa v235, v13 dst_sel:DWORD dst_unused:UNUSED_PAD src0_sel:WORD_1
	v_pk_add_f32 v[228:229], v[220:221], v[224:225]
	v_pk_add_f32 v[230:231], v[222:223], v[226:227]
	s_nop 1
	v_pk_fma_f32 v[236:237], v[174:175], v[228:229], v[232:233]
	v_pk_fma_f32 v[238:239], v[176:177], v[230:231], v[234:235]
	s_nop 1
	v_cvt_pk_f16_f32 v12, v236, v237
	v_cvt_pk_f16_f32 v13, v238, v239
	global_store_dwordx2 v[18:19], v[12:13], off offset:1536
	global_load_dwordx4 v[154:157], v[36:37], off offset:3072
	global_load_dwordx4 v[158:161], v[38:39], off offset:3072
	global_load_dwordx4 v[162:165], v[42:43], off offset:3072
	global_load_dwordx4 v[170:173], v[44:45], off offset:3072
	global_load_dwordx4 v[174:177], v[50:51], off offset:3072
	s_waitcnt vmcnt(18)
	v_pk_add_f32 v[220:221], v[94:95], v[98:99]
	v_pk_add_f32 v[222:223], v[96:97], v[100:101]
	v_pk_add_f32 v[224:225], v[102:103], v[106:107]
	v_pk_add_f32 v[226:227], v[104:105], v[108:109]
	v_cvt_f32_f16_e32 v232, v14
	v_cvt_f32_f16_sdwa v233, v14 dst_sel:DWORD dst_unused:UNUSED_PAD src0_sel:WORD_1
	v_cvt_f32_f16_e32 v234, v15
	v_cvt_f32_f16_sdwa v235, v15 dst_sel:DWORD dst_unused:UNUSED_PAD src0_sel:WORD_1
	v_pk_add_f32 v[228:229], v[220:221], v[224:225]
	v_pk_add_f32 v[230:231], v[222:223], v[226:227]
	s_nop 1
	v_pk_fma_f32 v[236:237], v[110:111], v[228:229], v[232:233]
	v_pk_fma_f32 v[238:239], v[112:113], v[230:231], v[234:235]
	s_nop 1
	v_cvt_pk_f16_f32 v14, v236, v237
	v_cvt_pk_f16_f32 v15, v238, v239
	global_store_dwordx2 v[18:19], v[14:15], off offset:2048
	s_waitcnt vmcnt(13)
	v_pk_add_f32 v[220:221], v[114:115], v[118:119]
	v_pk_add_f32 v[222:223], v[116:117], v[120:121]
	v_pk_add_f32 v[224:225], v[122:123], v[126:127]
	v_pk_add_f32 v[226:227], v[124:125], v[128:129]
	v_cvt_f32_f16_e32 v232, v10
	v_cvt_f32_f16_sdwa v233, v10 dst_sel:DWORD dst_unused:UNUSED_PAD src0_sel:WORD_1
	v_cvt_f32_f16_e32 v234, v11
	v_cvt_f32_f16_sdwa v235, v11 dst_sel:DWORD dst_unused:UNUSED_PAD src0_sel:WORD_1
	v_pk_add_f32 v[228:229], v[220:221], v[224:225]
	v_pk_add_f32 v[230:231], v[222:223], v[226:227]
	s_nop 1
	v_pk_fma_f32 v[236:237], v[130:131], v[228:229], v[232:233]
	v_pk_fma_f32 v[238:239], v[132:133], v[230:231], v[234:235]
	s_nop 1
	v_cvt_pk_f16_f32 v10, v236, v237
	v_cvt_pk_f16_f32 v11, v238, v239
	global_store_dwordx2 v[18:19], v[10:11], off offset:2560
	s_waitcnt vmcnt(8)
	v_pk_add_f32 v[220:221], v[134:135], v[138:139]
	v_pk_add_f32 v[222:223], v[136:137], v[140:141]
	v_pk_add_f32 v[224:225], v[142:143], v[146:147]
	v_pk_add_f32 v[226:227], v[144:145], v[148:149]
	v_cvt_f32_f16_e32 v232, v8
	v_cvt_f32_f16_sdwa v233, v8 dst_sel:DWORD dst_unused:UNUSED_PAD src0_sel:WORD_1
	v_cvt_f32_f16_e32 v234, v9
	v_cvt_f32_f16_sdwa v235, v9 dst_sel:DWORD dst_unused:UNUSED_PAD src0_sel:WORD_1
	v_pk_add_f32 v[228:229], v[220:221], v[224:225]
	v_pk_add_f32 v[230:231], v[222:223], v[226:227]
	s_nop 1
	v_pk_fma_f32 v[236:237], v[150:151], v[228:229], v[232:233]
	v_pk_fma_f32 v[238:239], v[152:153], v[230:231], v[234:235]
	s_nop 1
	v_cvt_pk_f16_f32 v8, v236, v237
	v_cvt_pk_f16_f32 v9, v238, v239
	global_store_dwordx2 v[18:19], v[8:9], off offset:3072
	s_waitcnt vmcnt(3)
	v_pk_add_f32 v[220:221], v[154:155], v[158:159]
	v_pk_add_f32 v[222:223], v[156:157], v[160:161]
	v_pk_add_f32 v[224:225], v[162:163], v[170:171]
	v_pk_add_f32 v[226:227], v[164:165], v[172:173]
	v_cvt_f32_f16_e32 v232, v4
	v_cvt_f32_f16_sdwa v233, v4 dst_sel:DWORD dst_unused:UNUSED_PAD src0_sel:WORD_1
	v_cvt_f32_f16_e32 v234, v5
	v_cvt_f32_f16_sdwa v235, v5 dst_sel:DWORD dst_unused:UNUSED_PAD src0_sel:WORD_1
	v_pk_add_f32 v[228:229], v[220:221], v[224:225]
	v_pk_add_f32 v[230:231], v[222:223], v[226:227]
	s_nop 1
	v_pk_fma_f32 v[236:237], v[174:175], v[228:229], v[232:233]
	v_pk_fma_f32 v[238:239], v[176:177], v[230:231], v[234:235]
	s_nop 1
	v_cvt_pk_f16_f32 v4, v236, v237
	v_cvt_pk_f16_f32 v5, v238, v239
	global_store_dwordx2 v[18:19], v[4:5], off offset:3584
